# prepare(): 8 serialised stats loads per unit issued together, one wait (all 12 sites)
# speedup vs baseline: 1.0237x; 1.0237x over previous
; #define LAS __attribute__((address_space(3)))
; __device__ __forceinline__ float shflx(float v, int k, int lane) { return __int_as_float(__builtin_amdgcn_ds_bpermute((lane ^ k) << 2, __float_as_int(v))); }
;     __device__ __forceinline__ void prepare(const pg8::Unit& u, LAS unsigned char* lds, int par, int tid) const { F.prepare(u, lds, par, tid); }
;     __device__ __forceinline__ void prepare(const pg8::Unit& u, LAS unsigned char* lds, int par, int tid) const { F.prepare(u, lds, par, tid); }
;     __device__ __forceinline__ void prepare(const pg8::Unit& u, LAS unsigned char* lds, int par, int tid) const { F.prepare(u, lds, par, tid); }
;     __device__ __forceinline__ void prepare(const pg8::Unit& u, LAS unsigned char* lds, int par, int tid) const {
;         if (stats == nullptr) return;
;         const int h = tid >> 8, tt = tid & 255, rl = tt >> 1, part = tt & 1, lrow = (rl >> 6) * 128 + h * 64 + (rl & 63);
;         const float* sp = stats + ((size_t)(u.pm * 256 + lrow) * 32 + part * 16) * 2;
;         float s1 = 0.f, s2 = 0.f;
; #pragma unroll
;         for (int i = 0; i < 8; ++i) { const f32x4 v = *(const f32x4*)(sp + 4 * i); s1 += v[0] + v[2]; s2 += v[1] + v[3]; }
;         s1 += shflx(s1, 1, tid & 63); s2 += shflx(s2, 1, tid & 63);
;         const float mu = s1 * (1.f / D), var = s2 * (1.f / D) - mu * mu, rstd = __builtin_amdgcn_rsqf(var + LN_EPS);
;         if (part == 0) { LAS float* rs = (LAS float*)(lds + RS_OFF) + (par * 256 + lrow) * 2; rs[0] = mu; rs[1] = rstd; }
.LBB0_111:
	s_waitcnt vmcnt(0)
	v_ashrrev_i32_e32 v3, 2, v210
	v_and_b32_e32 v2, 0x80, v210
	v_and_b32_e32 v3, 0xffffffc0, v3
	v_lshrrev_b32_e32 v0, 1, v210
	v_add_u32_e32 v2, v3, v2
	v_and_or_b32 v190, v0, 63, v2
	v_lshl_add_u32 v2, s26, 8, v190
	v_ashrrev_i32_e32 v3, 31, v2
	v_readlane_b32 s4, v251, 35
	v_and_b32_e32 v10, 1, v210
	v_lshlrev_b64 v[2:3], 8, v[2:3]
	v_readlane_b32 s5, v251, 36
	v_lshlrev_b32_e32 v0, 7, v10
	v_lshlrev_b32_e32 v11, 2, v210
	v_lshl_add_u64 v[2:3], s[4:5], 0, v[2:3]
	v_lshl_add_u64 v[6:7], v[2:3], 0, v[0:1]
	global_load_dwordx4 v[2:5], v[6:7], off
	global_load_dwordx4 v[222:225], v[6:7], off offset:16
	global_load_dwordx4 v[226:229], v[6:7], off offset:32
	global_load_dwordx4 v[230:233], v[6:7], off offset:48
	global_load_dwordx4 v[234:237], v[6:7], off offset:64
	global_load_dwordx4 v[238:241], v[6:7], off offset:80
	global_load_dwordx4 v[242:245], v[6:7], off offset:96
	global_load_dwordx4 v[246:249], v[6:7], off offset:112
	v_bitop3_b32 v191, v11, 4, v205 bitop3:0x6c
	v_cmp_eq_u32_e64 s[40:41], 0, v10
	s_waitcnt vmcnt(0) lgkmcnt(0)
	v_add_f32_e32 v0, v2, v4
	v_add_f32_e32 v2, v3, v5
	v_add_f32_e32 v8, 0, v2
	v_add_f32_e32 v0, 0, v0
	v_add_f32_e32 v2, v222, v224
	v_add_f32_e32 v0, v0, v2
	v_add_f32_e32 v2, v223, v225
	v_add_f32_e32 v8, v8, v2
	v_add_f32_e32 v2, v226, v228
	v_add_f32_e32 v0, v0, v2
	v_add_f32_e32 v2, v227, v229
	v_add_f32_e32 v8, v8, v2
	v_add_f32_e32 v2, v230, v232
	v_add_f32_e32 v0, v0, v2
	v_add_f32_e32 v2, v231, v233
	v_add_f32_e32 v8, v8, v2
	v_add_f32_e32 v2, v234, v236
	v_add_f32_e32 v0, v0, v2
	v_add_f32_e32 v2, v235, v237
	v_add_f32_e32 v8, v8, v2
	v_add_f32_e32 v2, v238, v240
	v_add_f32_e32 v0, v0, v2
	v_add_f32_e32 v2, v239, v241
	v_add_f32_e32 v8, v8, v2
	v_add_f32_e32 v2, v242, v244
	v_add_f32_e32 v0, v0, v2
	v_add_f32_e32 v2, v243, v245
	v_add_f32_e32 v8, v8, v2
	v_add_f32_e32 v2, v246, v248
	v_add_f32_e32 v0, v0, v2
	v_add_f32_e32 v2, v247, v249
	v_add_f32_e32 v2, v8, v2
	ds_bpermute_b32 v3, v191, v0
	ds_bpermute_b32 v4, v191, v2
	s_and_saveexec_b64 s[4:5], s[40:41]
	s_cbranch_execz .LBB0_113
	s_waitcnt lgkmcnt(1)
	v_add_f32_e32 v0, v0, v3
	s_waitcnt lgkmcnt(0)
	v_add_f32_e32 v4, v2, v4
	v_mul_f32_e32 v2, 0x3a000000, v0
	v_mul_f32_e32 v0, v2, v2
	v_fma_f32 v0, v4, s61, -v0
	v_add_f32_e32 v0, 0x3727c5ac, v0
	v_rsq_f32_e32 v3, v0
	v_lshl_add_u32 v0, v190, 3, 0
	v_add_u32_e32 v0, 0x20000, v0
	ds_write_b64 v0, v[2:3]

; #define LAS __attribute__((address_space(3)))
; __device__ __forceinline__ float shflx(float v, int k, int lane) { return __int_as_float(__builtin_amdgcn_ds_bpermute((lane ^ k) << 2, __float_as_int(v))); }
;     __device__ __forceinline__ void prepare(const pg8::Unit& u, LAS unsigned char* lds, int par, int tid) const { F.prepare(u, lds, par, tid); }
;     __device__ __forceinline__ void prepare(const pg8::Unit& u, LAS unsigned char* lds, int par, int tid) const { F.prepare(u, lds, par, tid); }
;     __device__ __forceinline__ void prepare(const pg8::Unit& u, LAS unsigned char* lds, int par, int tid) const { F.prepare(u, lds, par, tid); }
;     __device__ __forceinline__ void prepare(const pg8::Unit& u, LAS unsigned char* lds, int par, int tid) const {
;         if (stats == nullptr) return;
;         const int h = tid >> 8, tt = tid & 255, rl = tt >> 1, part = tt & 1, lrow = (rl >> 6) * 128 + h * 64 + (rl & 63);
;         const float* sp = stats + ((size_t)(u.pm * 256 + lrow) * 32 + part * 16) * 2;
;         float s1 = 0.f, s2 = 0.f;
; #pragma unroll
;         for (int i = 0; i < 8; ++i) { const f32x4 v = *(const f32x4*)(sp + 4 * i); s1 += v[0] + v[2]; s2 += v[1] + v[3]; }
;         s1 += shflx(s1, 1, tid & 63); s2 += shflx(s2, 1, tid & 63);
;         const float mu = s1 * (1.f / D), var = s2 * (1.f / D) - mu * mu, rstd = __builtin_amdgcn_rsqf(var + LN_EPS);
;         if (part == 0) { LAS float* rs = (LAS float*)(lds + RS_OFF) + (par * 256 + lrow) * 2; rs[0] = mu; rs[1] = rstd; }
.LBB0_145:
	s_or_b64 exec, exec, s[26:27]
	s_andn2_b64 vcc, exec, s[22:23]
	s_mov_b64 s[22:23], -1
	s_cbranch_vccnz .LBB0_117
	v_lshl_add_u32 v2, s16, 8, v190
	v_ashrrev_i32_e32 v3, 31, v2
	v_lshlrev_b64 v[2:3], 8, v[2:3]
	v_lshl_add_u64 v[6:7], v[168:169], 0, v[2:3]
	s_waitcnt lgkmcnt(0)
	global_load_dwordx4 v[2:5], v[6:7], off
	global_load_dwordx4 v[222:225], v[6:7], off offset:16
	global_load_dwordx4 v[226:229], v[6:7], off offset:32
	global_load_dwordx4 v[230:233], v[6:7], off offset:48
	global_load_dwordx4 v[234:237], v[6:7], off offset:64
	global_load_dwordx4 v[238:241], v[6:7], off offset:80
	global_load_dwordx4 v[242:245], v[6:7], off offset:96
	global_load_dwordx4 v[246:249], v[6:7], off offset:112
	s_waitcnt vmcnt(0) lgkmcnt(0)
	v_add_f32_e32 v2, v2, v4
	v_add_f32_e32 v8, 0, v2
	v_add_f32_e32 v2, v3, v5
	v_add_f32_e32 v9, 0, v2
	v_add_f32_e32 v2, v222, v224
	v_add_f32_e32 v8, v8, v2
	v_add_f32_e32 v2, v223, v225
	v_add_f32_e32 v9, v9, v2
	v_add_f32_e32 v2, v226, v228
	v_add_f32_e32 v8, v8, v2
	v_add_f32_e32 v2, v227, v229
	v_add_f32_e32 v9, v9, v2
	v_add_f32_e32 v2, v230, v232
	v_add_f32_e32 v8, v8, v2
	v_add_f32_e32 v2, v231, v233
	v_add_f32_e32 v9, v9, v2
	v_add_f32_e32 v2, v234, v236
	v_add_f32_e32 v8, v8, v2
	v_add_f32_e32 v2, v235, v237
	v_add_f32_e32 v9, v9, v2
	v_add_f32_e32 v2, v238, v240
	v_add_f32_e32 v8, v8, v2
	v_add_f32_e32 v2, v239, v241
	v_add_f32_e32 v9, v9, v2
	v_add_f32_e32 v2, v242, v244
	v_add_f32_e32 v8, v8, v2
	v_add_f32_e32 v2, v243, v245
	v_add_f32_e32 v9, v9, v2
	v_add_f32_e32 v2, v246, v248
	v_add_f32_e32 v3, v247, v249
	v_add_f32_e32 v2, v8, v2
	v_add_f32_e32 v3, v9, v3
	ds_bpermute_b32 v4, v191, v2
	ds_bpermute_b32 v5, v191, v3
	s_and_saveexec_b64 s[22:23], s[40:41]
	s_cbranch_execz .LBB0_148
	s_waitcnt lgkmcnt(1)
	v_add_f32_e32 v2, v2, v4
	v_mul_f32_e32 v2, 0x3a000000, v2
	s_waitcnt lgkmcnt(0)
	v_add_f32_e32 v3, v3, v5
	v_mul_f32_e32 v4, v2, v2
	v_fma_f32 v3, v3, s61, -v4
	v_add_f32_e32 v3, 0x3727c5ac, v3
	v_rsq_f32_e32 v3, v3
	s_lshl_b32 s15, s48, 11
	s_and_b32 s15, s15, 0x800
	v_add_u32_e32 v4, s15, v196
	ds_write_b64 v4, v[2:3]

; #define LAS __attribute__((address_space(3)))
; __device__ __forceinline__ float shflx(float v, int k, int lane) { return __int_as_float(__builtin_amdgcn_ds_bpermute((lane ^ k) << 2, __float_as_int(v))); }
;     __device__ __forceinline__ void prepare(const pg8::Unit& u, LAS unsigned char* lds, int par, int tid) const { F.prepare(u, lds, par, tid); }
;     __device__ __forceinline__ void prepare(const pg8::Unit& u, LAS unsigned char* lds, int par, int tid) const { F.prepare(u, lds, par, tid); }
;     __device__ __forceinline__ void prepare(const pg8::Unit& u, LAS unsigned char* lds, int par, int tid) const { F.prepare(u, lds, par, tid); }
;     __device__ bool next(int i, Unit& u) const {
;         const int nr = (nwg + G - 1) / G; if (i >= nr) return false;
;         const long L = (long)(rev ? nr - 1 - i : i) * G + c; if (L >= nwg) return false;
;         int wgid = (int)L; { const int q = nwg / NXCD, r = nwg % NXCD, xcd = wgid % NXCD, off = wgid / NXCD; wgid = (xcd < r ? xcd * (q + 1) : r * (q + 1) + (xcd - r) * q) + off; }
;         const int nig = WGM * nN, gid = wgid / nig, fm = gid * WGM, gsz = (nM - fm) < WGM ? (nM - fm) : WGM;
;         u.pm = fm + ((wgid % nig) % gsz); u.pn = (wgid % nig) / gsz; return true;
;     __device__ __forceinline__ void prepare(const pg8::Unit& u, LAS unsigned char* lds, int par, int tid) const {
;         if (stats == nullptr) return;
;         const int h = tid >> 8, tt = tid & 255, rl = tt >> 1, part = tt & 1, lrow = (rl >> 6) * 128 + h * 64 + (rl & 63);
;         const float* sp = stats + ((size_t)(u.pm * 256 + lrow) * 32 + part * 16) * 2;
;         float s1 = 0.f, s2 = 0.f;
; #pragma unroll
;         for (int i = 0; i < 8; ++i) { const f32x4 v = *(const f32x4*)(sp + 4 * i); s1 += v[0] + v[2]; s2 += v[1] + v[3]; }
;         s1 += shflx(s1, 1, tid & 63); s2 += shflx(s2, 1, tid & 63);
;         const float mu = s1 * (1.f / D), var = s2 * (1.f / D) - mu * mu, rstd = __builtin_amdgcn_rsqf(var + LN_EPS);
;         if (part == 0) { LAS float* rs = (LAS float*)(lds + RS_OFF) + (par * 256 + lrow) * 2; rs[0] = mu; rs[1] = rstd; }
.LBB0_158:
	s_ashr_i32 s0, s2, 3
	s_add_i32 s0, s5, s0
	s_ashr_i32 s1, s0, 31
	s_lshr_b32 s1, s1, 25
	s_add_i32 s1, s0, s1
	s_ashr_i32 s2, s1, 7
	s_and_b32 s1, s1, 0xff80
	s_sub_i32 s0, s0, s1
	s_bfe_i32 s1, s0, 0x80000
	s_bfe_u32 s1, s1, 0x2000d
	s_lshl_b32 s4, s2, 2
	s_add_i32 s2, s0, s1
	s_and_b32 s1, s2, 0xfc
	s_waitcnt vmcnt(0)
	v_ashrrev_i32_e32 v3, 2, v210
	s_sub_i32 s0, s0, s1
	v_and_b32_e32 v2, 0x80, v210
	v_and_b32_e32 v3, 0xffffffc0, v3
	s_sext_i32_i8 s0, s0
	v_lshrrev_b32_e32 v0, 1, v210
	v_add_u32_e32 v2, v3, v2
	s_add_i32 s24, s4, s0
	v_and_or_b32 v144, v0, 63, v2
	v_lshl_add_u32 v2, s24, 8, v144
	v_ashrrev_i32_e32 v3, 31, v2
	v_readlane_b32 s0, v251, 35
	v_and_b32_e32 v10, 1, v210
	v_lshlrev_b64 v[2:3], 8, v[2:3]
	v_readlane_b32 s1, v251, 36
	v_lshlrev_b32_e32 v0, 7, v10
	v_lshlrev_b32_e32 v11, 2, v210
	v_lshl_add_u64 v[2:3], s[0:1], 0, v[2:3]
	v_lshl_add_u64 v[6:7], v[2:3], 0, v[0:1]
	s_waitcnt lgkmcnt(0)
	global_load_dwordx4 v[2:5], v[6:7], off
	global_load_dwordx4 v[222:225], v[6:7], off offset:16
	global_load_dwordx4 v[226:229], v[6:7], off offset:32
	global_load_dwordx4 v[230:233], v[6:7], off offset:48
	global_load_dwordx4 v[234:237], v[6:7], off offset:64
	global_load_dwordx4 v[238:241], v[6:7], off offset:80
	global_load_dwordx4 v[242:245], v[6:7], off offset:96
	global_load_dwordx4 v[246:249], v[6:7], off offset:112
	v_bitop3_b32 v145, v11, 4, v205 bitop3:0x6c
	v_cmp_eq_u32_e64 s[0:1], 0, v10
	s_waitcnt vmcnt(0) lgkmcnt(0)
	v_add_f32_e32 v0, v2, v4
	v_add_f32_e32 v2, v3, v5
	v_add_f32_e32 v8, 0, v2
	v_add_f32_e32 v0, 0, v0
	v_add_f32_e32 v2, v222, v224
	v_add_f32_e32 v0, v0, v2
	v_add_f32_e32 v2, v223, v225
	v_add_f32_e32 v8, v8, v2
	v_add_f32_e32 v2, v226, v228
	v_add_f32_e32 v0, v0, v2
	v_add_f32_e32 v2, v227, v229
	v_add_f32_e32 v8, v8, v2
	v_add_f32_e32 v2, v230, v232
	v_add_f32_e32 v0, v0, v2
	v_add_f32_e32 v2, v231, v233
	v_add_f32_e32 v8, v8, v2
	v_add_f32_e32 v2, v234, v236
	v_add_f32_e32 v0, v0, v2
	v_add_f32_e32 v2, v235, v237
	v_add_f32_e32 v8, v8, v2
	v_add_f32_e32 v2, v238, v240
	v_add_f32_e32 v0, v0, v2
	v_add_f32_e32 v2, v239, v241
	v_add_f32_e32 v8, v8, v2
	v_add_f32_e32 v2, v242, v244
	v_add_f32_e32 v0, v0, v2
	v_add_f32_e32 v2, v243, v245
	v_add_f32_e32 v8, v8, v2
	v_add_f32_e32 v2, v246, v248
	v_add_f32_e32 v0, v0, v2
	v_add_f32_e32 v2, v247, v249
	v_add_f32_e32 v2, v8, v2
	ds_bpermute_b32 v3, v145, v0
	ds_bpermute_b32 v4, v145, v2
	s_and_saveexec_b64 s[4:5], s[0:1]
	s_cbranch_execz .LBB0_160
	s_waitcnt lgkmcnt(1)
	v_add_f32_e32 v0, v0, v3
	s_waitcnt lgkmcnt(0)
	v_add_f32_e32 v4, v2, v4
	v_mul_f32_e32 v2, 0x3a000000, v0
	v_mul_f32_e32 v0, v2, v2
	v_fma_f32 v0, v4, s61, -v0
	v_add_f32_e32 v0, 0x3727c5ac, v0
	v_rsq_f32_e32 v3, v0
	v_lshl_add_u32 v0, v144, 3, 0
	v_add_u32_e32 v0, 0x20000, v0
	ds_write_b64 v0, v[2:3]

; #define LAS __attribute__((address_space(3)))
; __device__ __forceinline__ float bf_lo(unsigned w) { return __uint_as_float(w << 16); }
;     __device__ __forceinline__ void operator()(const f32x4 (&acc)[2][2][4][2], const pg8::Unit& u, int wr, int wc, int fr, int fq, LAS unsigned char* lds, int par) const {
;         const bool fold = F.stats != nullptr;
;         const LAS float* rsb = (const LAS float*)(lds + RS_OFF) + par * 512; const LAS float* cvb = (const LAS float*)(lds + CV_OFF) + (par * 2 + wr) * 512;
;         const int row0 = u.pm * 256 + wr * 64 + fr, c0 = u.pn * 256 + wc * 64 + 16 * fq;
; #pragma unroll
;         for (int ai = 0; ai < 2; ++ai)
; #pragma unroll
;             for (int m = 0; m < 4; ++m) {
;                 const int row = row0 + ai * 128 + m * 16, lrow = ai * 128 + wr * 64 + m * 16 + fr;
;                 float mu = 0.f, rstd = 1.f; if (fold) { mu = rsb[2 * lrow]; rstd = rsb[2 * lrow + 1]; }
; #pragma unroll
;                 for (int bj = 0; bj < 2; ++bj) {
;                     const size_t off = (size_t)row * ld + c0 + bj * 8;
;                     f32x4 v0 = acc[ai][bj][m][0], v1 = acc[ai][bj][m][1];
;                     if (fold) fold_apply(v0, v1, mu, rstd, cvb, wc * 64 + 16 * fq + bj * 8);
;                     if (MODE == 0) { v0 *= scale; v1 *= scale; }
;                     if (MODE == 1) {
; #pragma unroll
;                         for (int j = 0; j < 4; ++j) { const float a = fmaxf(v0[j], 0.f), b = fmaxf(v1[j], 0.f); v0[j] = a * a; v1[j] = b * b; }
;                     }
;                     if (MODE == 2 || MODE == 3) {
;                         const u32x4 gw = *(const u32x4*)(gate + off);
;                         v0[0] *= bf_lo(gw.x); v0[1] *= bf_hi(gw.x); v0[2] *= bf_lo(gw.y); v0[3] *= bf_hi(gw.y);
;                         v1[0] *= bf_lo(gw.z); v1[1] *= bf_hi(gw.z); v1[2] *= bf_lo(gw.w); v1[3] *= bf_hi(gw.w);
;                     }
;                     if (MODE == 3) {
;                         const u32x4 pw = *(const u32x4*)(o + off);
;                         v0[0] += bf_lo(pw.x); v0[1] += bf_hi(pw.x); v0[2] += bf_lo(pw.y); v0[3] += bf_hi(pw.y);
;                         v1[0] += bf_lo(pw.z); v1[1] += bf_hi(pw.z); v1[2] += bf_lo(pw.w); v1[3] += bf_hi(pw.w);
;                     }
;                     *(u32x4*)(o + off) = pack8(v0, v1);
;                 }
.LBB0_176:
	s_and_b32 s15, s41, 1
	v_lshl_add_u32 v155, s15, 12, v153
	v_lshl_add_u32 v156, s15, 11, v152
	ds_read_b128 v[158:161], v155
	ds_read_b64 v[174:175], v156
	v_mov_b32_e32 v177, v124
	v_mov_b32_e32 v182, v126
	ds_read_b128 v[162:165], v155 offset:16
	ds_read_b128 v[166:169], v155 offset:32
	ds_read_b128 v[178:181], v155 offset:48
	v_lshl_add_u32 v142, s24, 8, v148
	s_waitcnt lgkmcnt(0)
	v_mov_b32_e32 v176, v175
	v_pk_mul_f32 v[176:177], v[176:177], v[174:175]
	v_pk_mov_b32 v[184:185], v[174:175], v[158:159] op_sel:[1,0]
	v_mov_b32_e32 v183, v176
	v_pk_mul_f32 v[182:183], v[182:183], v[184:185]
	v_pk_mov_b32 v[126:127], v[126:127], v[176:177] op_sel:[1,0]
	v_sub_f32_e32 v157, v182, v183
	v_add_f32_e32 v157, v159, v157
	v_pk_mov_b32 v[158:159], v[174:175], v[160:161] op_sel:[1,0]
	v_lshl_or_b32 v172, s40, 8, v150
	v_pk_mul_f32 v[126:127], v[126:127], v[158:159]
	v_pk_mov_b32 v[158:159], v[174:175], v[162:163] op_sel:[1,0]
	v_sub_f32_e32 v126, v126, v127
	v_add_f32_e32 v160, v161, v126
	v_mov_b32_e32 v126, v128
	v_mov_b32_e32 v127, v176
	v_pk_mul_f32 v[126:127], v[126:127], v[158:159]
	v_ashrrev_i32_e32 v143, 31, v142
	v_sub_f32_e32 v126, v126, v127
	v_add_f32_e32 v158, v163, v126
	v_pk_mov_b32 v[126:127], v[128:129], v[176:177] op_sel:[1,0]
	v_pk_mov_b32 v[128:129], v[174:175], v[164:165] op_sel:[1,0]
	v_readlane_b32 s26, v251, 43
	v_pk_mul_f32 v[126:127], v[126:127], v[128:129]
	v_pk_mov_b32 v[128:129], v[174:175], v[166:167] op_sel:[1,0]
	v_sub_f32_e32 v126, v126, v127
	v_add_f32_e32 v159, v165, v126
	v_mov_b32_e32 v126, v122
	v_mov_b32_e32 v127, v176
	v_pk_mul_f32 v[126:127], v[126:127], v[128:129]
	v_pk_mov_b32 v[122:123], v[122:123], v[176:177] op_sel:[1,0]
	v_sub_f32_e32 v126, v126, v127
	v_add_f32_e32 v128, v167, v126
	v_pk_mov_b32 v[126:127], v[174:175], v[168:169] op_sel:[1,0]
	v_ashrrev_i32_e32 v173, 31, v172
	v_pk_mul_f32 v[122:123], v[122:123], v[126:127]
	v_readlane_b32 s27, v251, 44
	v_sub_f32_e32 v122, v122, v123
	v_add_f32_e32 v126, v169, v122
	v_fma_f32 v122, -v176, v178, v177
	v_add_f32_e32 v127, v179, v122
	v_pk_mov_b32 v[122:123], v[124:125], v[176:177] op_sel:[1,0]
	v_pk_mov_b32 v[124:125], v[174:175], v[180:181] op_sel:[1,0]
	v_max_f32_e32 v126, 0, v126
	v_pk_mul_f32 v[122:123], v[122:123], v[124:125]
	v_max_f32_e32 v124, 0, v128
	v_sub_f32_e32 v122, v122, v123
	v_add_f32_e32 v122, v181, v122
	v_mul_f32_e32 v128, v126, v126
	v_max_f32_e32 v126, 0, v158
	v_max_f32_e32 v123, 0, v157
	v_max_f32_e32 v127, 0, v127
	v_mul_f32_e32 v129, v126, v126
	v_max_f32_e32 v126, 0, v159
	v_max_f32_e32 v122, 0, v122
	v_mul_f32_e32 v123, v123, v123
	v_max_f32_e32 v125, 0, v160
	v_mul_f32_e32 v157, v127, v127
	v_mul_f32_e32 v127, v126, v126
	v_mul_f32_e32 v122, v122, v122
	v_mul_f32_e32 v124, v124, v124
	v_mul_f32_e32 v125, v125, v125
	v_cvt_pk_bf16_f32 v126, v123, v125
	v_cvt_pk_bf16_f32 v127, v129, v127
	v_cvt_pk_bf16_f32 v128, v124, v128
	v_cvt_pk_bf16_f32 v129, v157, v122
	v_lshlrev_b64 v[122:123], 14, v[142:143]
	v_lshl_add_u64 v[122:123], s[26:27], 0, v[122:123]
	v_lshlrev_b64 v[124:125], 1, v[172:173]
	v_lshl_add_u64 v[122:123], v[122:123], 0, v[124:125]
	flat_store_dwordx4 v[122:123], v[126:129]
	ds_read_b128 v[126:129], v155 offset:64
	ds_read_b128 v[158:161], v155 offset:80
	ds_read_b128 v[162:165], v155 offset:96
	ds_read_b128 v[166:169], v155 offset:112
	v_mov_b32_e32 v172, v118
	v_mov_b32_e32 v173, v176
	s_waitcnt lgkmcnt(0)
	v_pk_mov_b32 v[178:179], v[174:175], v[126:127] op_sel:[1,0]
	v_pk_mov_b32 v[118:119], v[118:119], v[176:177] op_sel:[1,0]
	v_pk_mul_f32 v[172:173], v[172:173], v[178:179]
	s_mov_b32 s15, 0x200000
	v_sub_f32_e32 v126, v172, v173
	v_add_f32_e32 v143, v127, v126
	v_pk_mov_b32 v[126:127], v[174:175], v[128:129] op_sel:[1,0]
	s_nop 0
	v_pk_mul_f32 v[118:119], v[118:119], v[126:127]
	v_pk_mov_b32 v[126:127], v[174:175], v[158:159] op_sel:[1,0]
	v_sub_f32_e32 v118, v118, v119
	v_add_f32_e32 v128, v129, v118
	v_mov_b32_e32 v118, v120
	v_mov_b32_e32 v119, v176
	v_pk_mul_f32 v[118:119], v[118:119], v[126:127]
	s_nop 0
	v_sub_f32_e32 v118, v118, v119
	v_add_f32_e32 v126, v159, v118
	v_pk_mov_b32 v[118:119], v[120:121], v[176:177] op_sel:[1,0]
	v_pk_mov_b32 v[120:121], v[174:175], v[160:161] op_sel:[1,0]
	s_nop 0
	v_pk_mul_f32 v[118:119], v[118:119], v[120:121]
	v_pk_mov_b32 v[120:121], v[174:175], v[162:163] op_sel:[1,0]
	v_sub_f32_e32 v118, v118, v119
	v_add_f32_e32 v127, v161, v118
	v_mov_b32_e32 v118, v114
	v_mov_b32_e32 v119, v176
	v_pk_mul_f32 v[118:119], v[118:119], v[120:121]
	v_pk_mov_b32 v[114:115], v[114:115], v[176:177] op_sel:[1,0]
	v_sub_f32_e32 v118, v118, v119
	v_add_f32_e32 v120, v163, v118
	v_pk_mov_b32 v[118:119], v[174:175], v[164:165] op_sel:[1,0]
	v_or_b32_e32 v162, 16, v142
	v_pk_mul_f32 v[114:115], v[114:115], v[118:119]
	v_pk_mov_b32 v[118:119], v[174:175], v[166:167] op_sel:[1,0]
	v_sub_f32_e32 v114, v114, v115
	v_add_f32_e32 v121, v165, v114
	v_mov_b32_e32 v114, v116
	v_mov_b32_e32 v115, v176
	v_pk_mul_f32 v[114:115], v[114:115], v[118:119]
	v_max_f32_e32 v119, 0, v121
	v_sub_f32_e32 v114, v114, v115
	v_add_f32_e32 v118, v167, v114
	v_pk_mov_b32 v[114:115], v[116:117], v[176:177] op_sel:[1,0]
	v_pk_mov_b32 v[116:117], v[174:175], v[168:169] op_sel:[1,0]
	v_max_f32_e32 v118, 0, v118
	v_pk_mul_f32 v[114:115], v[114:115], v[116:117]
	v_max_f32_e32 v116, 0, v120
	v_sub_f32_e32 v114, v114, v115
	v_add_f32_e32 v114, v169, v114
	v_max_f32_e32 v115, 0, v143
	v_max_f32_e32 v117, 0, v128
	v_mul_f32_e32 v115, v115, v115
	v_mul_f32_e32 v116, v116, v116
	v_mul_f32_e32 v117, v117, v117
	v_max_f32_e32 v120, 0, v126
	v_max_f32_e32 v121, 0, v127
	v_max_f32_e32 v114, 0, v114
	v_mul_f32_e32 v119, v119, v119
	v_mul_f32_e32 v120, v120, v120
	v_mul_f32_e32 v118, v118, v118
	v_mul_f32_e32 v121, v121, v121
	v_mul_f32_e32 v126, v114, v114
	v_cvt_pk_bf16_f32 v114, v115, v117
	v_cvt_pk_bf16_f32 v115, v120, v121
	v_cvt_pk_bf16_f32 v116, v116, v119
	v_cvt_pk_bf16_f32 v117, v118, v126
	flat_store_dwordx4 v[122:123], v[114:117] offset:16
	ds_read_b128 v[114:117], v155
	ds_read_b64 v[164:165], v156 offset:128
	v_mov_b32_e32 v167, v108
	v_mov_b32_e32 v168, v110
	ds_read_b128 v[118:121], v155 offset:16
	ds_read_b128 v[126:129], v155 offset:32
	ds_read_b128 v[158:161], v155 offset:48
	v_ashrrev_i32_e32 v163, 31, v162
	s_waitcnt lgkmcnt(0)
; #define LAS __attribute__((address_space(3)))
; __device__ __forceinline__ float bf_lo(unsigned w) { return __uint_as_float(w << 16); }
;     __device__ __forceinline__ void operator()(const f32x4 (&acc)[2][2][4][2], const pg8::Unit& u, int wr, int wc, int fr, int fq, LAS unsigned char* lds, int par) const {
;         const bool fold = F.stats != nullptr;
;         const LAS float* rsb = (const LAS float*)(lds + RS_OFF) + par * 512; const LAS float* cvb = (const LAS float*)(lds + CV_OFF) + (par * 2 + wr) * 512;
;         const int row0 = u.pm * 256 + wr * 64 + fr, c0 = u.pn * 256 + wc * 64 + 16 * fq;
; #pragma unroll
;         for (int ai = 0; ai < 2; ++ai)
; #pragma unroll
;             for (int m = 0; m < 4; ++m) {
;                 const int row = row0 + ai * 128 + m * 16, lrow = ai * 128 + wr * 64 + m * 16 + fr;
;                 float mu = 0.f, rstd = 1.f; if (fold) { mu = rsb[2 * lrow]; rstd = rsb[2 * lrow + 1]; }
; #pragma unroll
;                 for (int bj = 0; bj < 2; ++bj) {
;                     const size_t off = (size_t)row * ld + c0 + bj * 8;
;                     f32x4 v0 = acc[ai][bj][m][0], v1 = acc[ai][bj][m][1];
;                     if (fold) fold_apply(v0, v1, mu, rstd, cvb, wc * 64 + 16 * fq + bj * 8);
;                     if (MODE == 0) { v0 *= scale; v1 *= scale; }
;                     if (MODE == 1) {
; #pragma unroll
;                         for (int j = 0; j < 4; ++j) { const float a = fmaxf(v0[j], 0.f), b = fmaxf(v1[j], 0.f); v0[j] = a * a; v1[j] = b * b; }
;                     }
;                     if (MODE == 2 || MODE == 3) {
;                         const u32x4 gw = *(const u32x4*)(gate + off);
;                         v0[0] *= bf_lo(gw.x); v0[1] *= bf_hi(gw.x); v0[2] *= bf_lo(gw.y); v0[3] *= bf_hi(gw.y);
;                         v1[0] *= bf_lo(gw.z); v1[1] *= bf_hi(gw.z); v1[2] *= bf_lo(gw.w); v1[3] *= bf_hi(gw.w);
;                     }
;                     if (MODE == 3) {
;                         const u32x4 pw = *(const u32x4*)(o + off);
;                         v0[0] += bf_lo(pw.x); v0[1] += bf_hi(pw.x); v0[2] += bf_lo(pw.y); v0[3] += bf_hi(pw.y);
;                         v1[0] += bf_lo(pw.z); v1[1] += bf_hi(pw.z); v1[2] += bf_lo(pw.w); v1[3] += bf_hi(pw.w);
;                     }
;                     *(u32x4*)(o + off) = pack8(v0, v1);
;                 }
	v_mov_b32_e32 v166, v165
	v_pk_mul_f32 v[166:167], v[166:167], v[164:165]
	v_pk_mov_b32 v[172:173], v[164:165], v[114:115] op_sel:[1,0]
	v_mov_b32_e32 v169, v166
	v_pk_mul_f32 v[168:169], v[168:169], v[172:173]
	v_pk_mov_b32 v[110:111], v[110:111], v[166:167] op_sel:[1,0]
	v_sub_f32_e32 v114, v168, v169
	v_add_f32_e32 v143, v115, v114
	v_pk_mov_b32 v[114:115], v[164:165], v[116:117] op_sel:[1,0]
	s_nop 0
	v_pk_mul_f32 v[110:111], v[110:111], v[114:115]
	v_pk_mov_b32 v[114:115], v[164:165], v[118:119] op_sel:[1,0]
	v_sub_f32_e32 v110, v110, v111
	v_add_f32_e32 v116, v117, v110
	v_mov_b32_e32 v110, v112
	v_mov_b32_e32 v111, v166
	v_pk_mul_f32 v[110:111], v[110:111], v[114:115]
	s_nop 0
	v_sub_f32_e32 v110, v110, v111
	v_add_f32_e32 v114, v119, v110
	v_pk_mov_b32 v[110:111], v[112:113], v[166:167] op_sel:[1,0]
	v_pk_mov_b32 v[112:113], v[164:165], v[120:121] op_sel:[1,0]
	s_nop 0
	v_pk_mul_f32 v[110:111], v[110:111], v[112:113]
	v_pk_mov_b32 v[112:113], v[164:165], v[126:127] op_sel:[1,0]
	v_sub_f32_e32 v110, v110, v111
	v_add_f32_e32 v115, v121, v110
	v_mov_b32_e32 v110, v106
	v_mov_b32_e32 v111, v166
	v_pk_mul_f32 v[110:111], v[110:111], v[112:113]
	v_pk_mov_b32 v[106:107], v[106:107], v[166:167] op_sel:[1,0]
	v_sub_f32_e32 v110, v110, v111
	v_add_f32_e32 v112, v127, v110
	v_pk_mov_b32 v[110:111], v[164:165], v[128:129] op_sel:[1,0]
	v_max_f32_e32 v113, 0, v115
	v_pk_mul_f32 v[106:107], v[106:107], v[110:111]
	v_mul_f32_e32 v113, v113, v113
	v_sub_f32_e32 v106, v106, v107
	v_add_f32_e32 v110, v129, v106
	v_fma_f32 v106, -v166, v158, v167
	v_add_f32_e32 v111, v159, v106
	v_pk_mov_b32 v[106:107], v[108:109], v[166:167] op_sel:[1,0]
	v_pk_mov_b32 v[108:109], v[164:165], v[160:161] op_sel:[1,0]
	v_max_f32_e32 v110, 0, v110
	v_pk_mul_f32 v[106:107], v[106:107], v[108:109]
	v_max_f32_e32 v108, 0, v112
	v_sub_f32_e32 v106, v106, v107
	v_add_f32_e32 v106, v161, v106
	v_max_f32_e32 v107, 0, v143
	v_max_f32_e32 v109, 0, v116
	v_max_f32_e32 v111, 0, v111
	v_mul_f32_e32 v107, v107, v107
	v_mul_f32_e32 v108, v108, v108
	v_mul_f32_e32 v109, v109, v109
	v_mul_f32_e32 v110, v110, v110
	v_max_f32_e32 v112, 0, v114
	v_mul_f32_e32 v111, v111, v111
	v_max_f32_e32 v106, 0, v106
	v_mul_f32_e32 v112, v112, v112
	v_mul_f32_e32 v114, v106, v106
	v_cvt_pk_bf16_f32 v106, v107, v109
	v_cvt_pk_bf16_f32 v107, v112, v113
	v_cvt_pk_bf16_f32 v108, v108, v110
	v_cvt_pk_bf16_f32 v109, v111, v114
	v_lshlrev_b64 v[110:111], 14, v[162:163]
	v_lshl_add_u64 v[110:111], s[26:27], 0, v[110:111]
	v_lshl_add_u64 v[126:127], v[110:111], 0, v[124:125]
	flat_store_dwordx4 v[126:127], v[106:109]
	ds_read_b128 v[106:109], v155 offset:64
	ds_read_b128 v[110:113], v155 offset:80
	ds_read_b128 v[114:117], v155 offset:96
	ds_read_b128 v[118:121], v155 offset:112
	v_mov_b32_e32 v128, v102
	v_mov_b32_e32 v129, v166
	s_waitcnt lgkmcnt(0)
	v_pk_mov_b32 v[158:159], v[164:165], v[106:107] op_sel:[1,0]
	v_pk_mov_b32 v[102:103], v[102:103], v[166:167] op_sel:[1,0]
	v_pk_mul_f32 v[128:129], v[128:129], v[158:159]
	s_nop 0
	v_sub_f32_e32 v106, v128, v129
	v_add_f32_e32 v128, v107, v106
	v_pk_mov_b32 v[106:107], v[164:165], v[108:109] op_sel:[1,0]
	s_nop 0
	v_pk_mul_f32 v[102:103], v[102:103], v[106:107]
	v_pk_mov_b32 v[106:107], v[164:165], v[110:111] op_sel:[1,0]
	v_sub_f32_e32 v102, v102, v103
	v_add_f32_e32 v108, v109, v102
	v_mov_b32_e32 v102, v104
	v_mov_b32_e32 v103, v166
	v_pk_mul_f32 v[102:103], v[102:103], v[106:107]
	s_nop 0
	v_sub_f32_e32 v102, v102, v103
	v_add_f32_e32 v106, v111, v102
	v_pk_mov_b32 v[102:103], v[104:105], v[166:167] op_sel:[1,0]
	v_pk_mov_b32 v[104:105], v[164:165], v[112:113] op_sel:[1,0]
	s_nop 0
	v_pk_mul_f32 v[102:103], v[102:103], v[104:105]
	v_pk_mov_b32 v[104:105], v[164:165], v[114:115] op_sel:[1,0]
	v_sub_f32_e32 v102, v102, v103
	v_add_f32_e32 v107, v113, v102
	v_mov_b32_e32 v102, v98
	v_mov_b32_e32 v103, v166
	v_pk_mul_f32 v[102:103], v[102:103], v[104:105]
	v_pk_mov_b32 v[98:99], v[98:99], v[166:167] op_sel:[1,0]
	v_sub_f32_e32 v102, v102, v103
	v_add_f32_e32 v104, v115, v102
	v_pk_mov_b32 v[102:103], v[164:165], v[116:117] op_sel:[1,0]
	v_or_b32_e32 v114, 32, v142
	v_pk_mul_f32 v[98:99], v[98:99], v[102:103]
	v_pk_mov_b32 v[102:103], v[164:165], v[118:119] op_sel:[1,0]
	v_sub_f32_e32 v98, v98, v99
	v_add_f32_e32 v105, v117, v98
	v_mov_b32_e32 v98, v100
	v_mov_b32_e32 v99, v166
	v_pk_mul_f32 v[98:99], v[98:99], v[102:103]
	v_max_f32_e32 v103, 0, v105
	v_sub_f32_e32 v98, v98, v99
	v_add_f32_e32 v102, v119, v98
	v_pk_mov_b32 v[98:99], v[100:101], v[166:167] op_sel:[1,0]
	v_pk_mov_b32 v[100:101], v[164:165], v[120:121] op_sel:[1,0]
	v_max_f32_e32 v102, 0, v102
	v_pk_mul_f32 v[98:99], v[98:99], v[100:101]
	v_max_f32_e32 v100, 0, v104
	v_sub_f32_e32 v98, v98, v99
	v_add_f32_e32 v98, v121, v98
	v_max_f32_e32 v99, 0, v128
	v_max_f32_e32 v101, 0, v108
	v_mul_f32_e32 v99, v99, v99
	v_mul_f32_e32 v100, v100, v100
	v_mul_f32_e32 v101, v101, v101
	v_max_f32_e32 v104, 0, v106
	v_max_f32_e32 v105, 0, v107
	v_max_f32_e32 v98, 0, v98
	v_mul_f32_e32 v103, v103, v103
	v_mul_f32_e32 v104, v104, v104
	v_mul_f32_e32 v102, v102, v102
	v_mul_f32_e32 v105, v105, v105
	v_mul_f32_e32 v106, v98, v98
	v_cvt_pk_bf16_f32 v98, v99, v101
	v_cvt_pk_bf16_f32 v99, v104, v105
	v_cvt_pk_bf16_f32 v100, v100, v103
	v_cvt_pk_bf16_f32 v101, v102, v106
	flat_store_dwordx4 v[126:127], v[98:101] offset:16
	ds_read_b128 v[98:101], v155
	ds_read_b64 v[116:117], v156 offset:256
	v_mov_b32_e32 v119, v92
	v_mov_b32_e32 v120, v94
	ds_read_b128 v[102:105], v155 offset:16
	ds_read_b128 v[106:109], v155 offset:32
	ds_read_b128 v[110:113], v155 offset:48
	v_ashrrev_i32_e32 v115, 31, v114
	s_waitcnt lgkmcnt(0)
; #define LAS __attribute__((address_space(3)))
; __device__ __forceinline__ float bf_lo(unsigned w) { return __uint_as_float(w << 16); }
;     __device__ __forceinline__ void operator()(const f32x4 (&acc)[2][2][4][2], const pg8::Unit& u, int wr, int wc, int fr, int fq, LAS unsigned char* lds, int par) const {
;         const bool fold = F.stats != nullptr;
;         const LAS float* rsb = (const LAS float*)(lds + RS_OFF) + par * 512; const LAS float* cvb = (const LAS float*)(lds + CV_OFF) + (par * 2 + wr) * 512;
;         const int row0 = u.pm * 256 + wr * 64 + fr, c0 = u.pn * 256 + wc * 64 + 16 * fq;
; #pragma unroll
;         for (int ai = 0; ai < 2; ++ai)
; #pragma unroll
;             for (int m = 0; m < 4; ++m) {
;                 const int row = row0 + ai * 128 + m * 16, lrow = ai * 128 + wr * 64 + m * 16 + fr;
;                 float mu = 0.f, rstd = 1.f; if (fold) { mu = rsb[2 * lrow]; rstd = rsb[2 * lrow + 1]; }
; #pragma unroll
;                 for (int bj = 0; bj < 2; ++bj) {
;                     const size_t off = (size_t)row * ld + c0 + bj * 8;
;                     f32x4 v0 = acc[ai][bj][m][0], v1 = acc[ai][bj][m][1];
;                     if (fold) fold_apply(v0, v1, mu, rstd, cvb, wc * 64 + 16 * fq + bj * 8);
;                     if (MODE == 0) { v0 *= scale; v1 *= scale; }
;                     if (MODE == 1) {
; #pragma unroll
;                         for (int j = 0; j < 4; ++j) { const float a = fmaxf(v0[j], 0.f), b = fmaxf(v1[j], 0.f); v0[j] = a * a; v1[j] = b * b; }
;                     }
;                     if (MODE == 2 || MODE == 3) {
;                         const u32x4 gw = *(const u32x4*)(gate + off);
;                         v0[0] *= bf_lo(gw.x); v0[1] *= bf_hi(gw.x); v0[2] *= bf_lo(gw.y); v0[3] *= bf_hi(gw.y);
;                         v1[0] *= bf_lo(gw.z); v1[1] *= bf_hi(gw.z); v1[2] *= bf_lo(gw.w); v1[3] *= bf_hi(gw.w);
;                     }
;                     if (MODE == 3) {
;                         const u32x4 pw = *(const u32x4*)(o + off);
;                         v0[0] += bf_lo(pw.x); v0[1] += bf_hi(pw.x); v0[2] += bf_lo(pw.y); v0[3] += bf_hi(pw.y);
;                         v1[0] += bf_lo(pw.z); v1[1] += bf_hi(pw.z); v1[2] += bf_lo(pw.w); v1[3] += bf_hi(pw.w);
;                     }
;                     *(u32x4*)(o + off) = pack8(v0, v1);
;                 }
	v_mov_b32_e32 v118, v117
	v_pk_mul_f32 v[118:119], v[118:119], v[116:117]
	v_pk_mov_b32 v[126:127], v[116:117], v[98:99] op_sel:[1,0]
	v_mov_b32_e32 v121, v118
	v_pk_mul_f32 v[120:121], v[120:121], v[126:127]
	v_pk_mov_b32 v[94:95], v[94:95], v[118:119] op_sel:[1,0]
	v_sub_f32_e32 v98, v120, v121
	v_add_f32_e32 v120, v99, v98
	v_pk_mov_b32 v[98:99], v[116:117], v[100:101] op_sel:[1,0]
	s_nop 0
	v_pk_mul_f32 v[94:95], v[94:95], v[98:99]
	v_pk_mov_b32 v[98:99], v[116:117], v[102:103] op_sel:[1,0]
	v_sub_f32_e32 v94, v94, v95
	v_add_f32_e32 v100, v101, v94
	v_mov_b32_e32 v94, v96
	v_mov_b32_e32 v95, v118
	v_pk_mul_f32 v[94:95], v[94:95], v[98:99]
	s_nop 0
	v_sub_f32_e32 v94, v94, v95
	v_add_f32_e32 v98, v103, v94
	v_pk_mov_b32 v[94:95], v[96:97], v[118:119] op_sel:[1,0]
	v_pk_mov_b32 v[96:97], v[116:117], v[104:105] op_sel:[1,0]
	s_nop 0
	v_pk_mul_f32 v[94:95], v[94:95], v[96:97]
	v_pk_mov_b32 v[96:97], v[116:117], v[106:107] op_sel:[1,0]
	v_sub_f32_e32 v94, v94, v95
	v_add_f32_e32 v99, v105, v94
	v_mov_b32_e32 v94, v90
	v_mov_b32_e32 v95, v118
	v_pk_mul_f32 v[94:95], v[94:95], v[96:97]
	v_pk_mov_b32 v[90:91], v[90:91], v[118:119] op_sel:[1,0]
	v_sub_f32_e32 v94, v94, v95
	v_add_f32_e32 v96, v107, v94
	v_pk_mov_b32 v[94:95], v[116:117], v[108:109] op_sel:[1,0]
	v_max_f32_e32 v97, 0, v99
	v_pk_mul_f32 v[90:91], v[90:91], v[94:95]
	v_mul_f32_e32 v97, v97, v97
	v_sub_f32_e32 v90, v90, v91
	v_add_f32_e32 v94, v109, v90
	v_fma_f32 v90, -v118, v110, v119
	v_add_f32_e32 v95, v111, v90
	v_pk_mov_b32 v[90:91], v[92:93], v[118:119] op_sel:[1,0]
	v_pk_mov_b32 v[92:93], v[116:117], v[112:113] op_sel:[1,0]
	v_max_f32_e32 v94, 0, v94
	v_pk_mul_f32 v[90:91], v[90:91], v[92:93]
	v_max_f32_e32 v92, 0, v96
	v_sub_f32_e32 v90, v90, v91
	v_add_f32_e32 v90, v113, v90
	v_max_f32_e32 v91, 0, v120
	v_max_f32_e32 v93, 0, v100
	v_max_f32_e32 v95, 0, v95
	v_mul_f32_e32 v91, v91, v91
	v_mul_f32_e32 v92, v92, v92
	v_mul_f32_e32 v93, v93, v93
	v_mul_f32_e32 v94, v94, v94
	v_max_f32_e32 v96, 0, v98
	v_mul_f32_e32 v95, v95, v95
	v_max_f32_e32 v90, 0, v90
	v_mul_f32_e32 v96, v96, v96
	v_mul_f32_e32 v98, v90, v90
	v_cvt_pk_bf16_f32 v90, v91, v93
	v_cvt_pk_bf16_f32 v91, v96, v97
	v_cvt_pk_bf16_f32 v92, v92, v94
	v_cvt_pk_bf16_f32 v93, v95, v98
	v_lshlrev_b64 v[94:95], 14, v[114:115]
	v_lshl_add_u64 v[94:95], s[26:27], 0, v[94:95]
	v_lshl_add_u64 v[106:107], v[94:95], 0, v[124:125]
	flat_store_dwordx4 v[106:107], v[90:93]
	ds_read_b128 v[90:93], v155 offset:64
	ds_read_b128 v[94:97], v155 offset:80
	ds_read_b128 v[98:101], v155 offset:96
	ds_read_b128 v[102:105], v155 offset:112
	v_mov_b32_e32 v108, v86
	v_mov_b32_e32 v109, v118
	s_waitcnt lgkmcnt(0)
	v_pk_mov_b32 v[110:111], v[116:117], v[90:91] op_sel:[1,0]
	v_pk_mov_b32 v[86:87], v[86:87], v[118:119] op_sel:[1,0]
	v_pk_mul_f32 v[108:109], v[108:109], v[110:111]
	s_nop 0
	v_sub_f32_e32 v90, v108, v109
	v_add_f32_e32 v108, v91, v90
	v_pk_mov_b32 v[90:91], v[116:117], v[92:93] op_sel:[1,0]
	s_nop 0
	v_pk_mul_f32 v[86:87], v[86:87], v[90:91]
	v_pk_mov_b32 v[90:91], v[116:117], v[94:95] op_sel:[1,0]
	v_sub_f32_e32 v86, v86, v87
	v_add_f32_e32 v92, v93, v86
	v_mov_b32_e32 v86, v88
	v_mov_b32_e32 v87, v118
	v_pk_mul_f32 v[86:87], v[86:87], v[90:91]
	s_nop 0
	v_sub_f32_e32 v86, v86, v87
	v_add_f32_e32 v90, v95, v86
	v_pk_mov_b32 v[86:87], v[88:89], v[118:119] op_sel:[1,0]
	v_pk_mov_b32 v[88:89], v[116:117], v[96:97] op_sel:[1,0]
	s_nop 0
	v_pk_mul_f32 v[86:87], v[86:87], v[88:89]
	v_pk_mov_b32 v[88:89], v[116:117], v[98:99] op_sel:[1,0]
	v_sub_f32_e32 v86, v86, v87
	v_add_f32_e32 v91, v97, v86
	v_mov_b32_e32 v86, v82
	v_mov_b32_e32 v87, v118
	v_pk_mul_f32 v[86:87], v[86:87], v[88:89]
	v_pk_mov_b32 v[82:83], v[82:83], v[118:119] op_sel:[1,0]
	v_sub_f32_e32 v86, v86, v87
	v_add_f32_e32 v88, v99, v86
	v_pk_mov_b32 v[86:87], v[116:117], v[100:101] op_sel:[1,0]
	v_or_b32_e32 v98, 48, v142
	v_pk_mul_f32 v[82:83], v[82:83], v[86:87]
	v_pk_mov_b32 v[86:87], v[116:117], v[102:103] op_sel:[1,0]
	v_sub_f32_e32 v82, v82, v83
	v_add_f32_e32 v89, v101, v82
	v_mov_b32_e32 v82, v84
	v_mov_b32_e32 v83, v118
	v_pk_mul_f32 v[82:83], v[82:83], v[86:87]
	v_max_f32_e32 v87, 0, v89
	v_sub_f32_e32 v82, v82, v83
	v_add_f32_e32 v86, v103, v82
	v_pk_mov_b32 v[82:83], v[84:85], v[118:119] op_sel:[1,0]
	v_pk_mov_b32 v[84:85], v[116:117], v[104:105] op_sel:[1,0]
	v_max_f32_e32 v86, 0, v86
	v_pk_mul_f32 v[82:83], v[82:83], v[84:85]
	v_max_f32_e32 v84, 0, v88
	v_sub_f32_e32 v82, v82, v83
	v_add_f32_e32 v82, v105, v82
	v_max_f32_e32 v83, 0, v108
	v_max_f32_e32 v85, 0, v92
	v_mul_f32_e32 v83, v83, v83
	v_mul_f32_e32 v84, v84, v84
	v_mul_f32_e32 v85, v85, v85
	v_max_f32_e32 v88, 0, v90
	v_max_f32_e32 v89, 0, v91
	v_max_f32_e32 v82, 0, v82
	v_mul_f32_e32 v87, v87, v87
	v_mul_f32_e32 v88, v88, v88
	v_mul_f32_e32 v86, v86, v86
	v_mul_f32_e32 v89, v89, v89
	v_mul_f32_e32 v90, v82, v82
	v_cvt_pk_bf16_f32 v82, v83, v85
	v_cvt_pk_bf16_f32 v83, v88, v89
	v_cvt_pk_bf16_f32 v84, v84, v87
	v_cvt_pk_bf16_f32 v85, v86, v90
	flat_store_dwordx4 v[106:107], v[82:85] offset:16
	ds_read_b128 v[82:85], v155
	ds_read_b64 v[100:101], v156 offset:384
	v_mov_b32_e32 v103, v76
	v_mov_b32_e32 v104, v78
	ds_read_b128 v[86:89], v155 offset:16
	ds_read_b128 v[90:93], v155 offset:32
	ds_read_b128 v[94:97], v155 offset:48
	v_ashrrev_i32_e32 v99, 31, v98
	s_waitcnt lgkmcnt(0)
; #define LAS __attribute__((address_space(3)))
; __device__ __forceinline__ float bf_lo(unsigned w) { return __uint_as_float(w << 16); }
;     __device__ __forceinline__ void operator()(const f32x4 (&acc)[2][2][4][2], const pg8::Unit& u, int wr, int wc, int fr, int fq, LAS unsigned char* lds, int par) const {
;         const bool fold = F.stats != nullptr;
;         const LAS float* rsb = (const LAS float*)(lds + RS_OFF) + par * 512; const LAS float* cvb = (const LAS float*)(lds + CV_OFF) + (par * 2 + wr) * 512;
;         const int row0 = u.pm * 256 + wr * 64 + fr, c0 = u.pn * 256 + wc * 64 + 16 * fq;
; #pragma unroll
;         for (int ai = 0; ai < 2; ++ai)
; #pragma unroll
;             for (int m = 0; m < 4; ++m) {
;                 const int row = row0 + ai * 128 + m * 16, lrow = ai * 128 + wr * 64 + m * 16 + fr;
;                 float mu = 0.f, rstd = 1.f; if (fold) { mu = rsb[2 * lrow]; rstd = rsb[2 * lrow + 1]; }
; #pragma unroll
;                 for (int bj = 0; bj < 2; ++bj) {
;                     const size_t off = (size_t)row * ld + c0 + bj * 8;
;                     f32x4 v0 = acc[ai][bj][m][0], v1 = acc[ai][bj][m][1];
;                     if (fold) fold_apply(v0, v1, mu, rstd, cvb, wc * 64 + 16 * fq + bj * 8);
;                     if (MODE == 0) { v0 *= scale; v1 *= scale; }
;                     if (MODE == 1) {
; #pragma unroll
;                         for (int j = 0; j < 4; ++j) { const float a = fmaxf(v0[j], 0.f), b = fmaxf(v1[j], 0.f); v0[j] = a * a; v1[j] = b * b; }
;                     }
;                     if (MODE == 2 || MODE == 3) {
;                         const u32x4 gw = *(const u32x4*)(gate + off);
;                         v0[0] *= bf_lo(gw.x); v0[1] *= bf_hi(gw.x); v0[2] *= bf_lo(gw.y); v0[3] *= bf_hi(gw.y);
;                         v1[0] *= bf_lo(gw.z); v1[1] *= bf_hi(gw.z); v1[2] *= bf_lo(gw.w); v1[3] *= bf_hi(gw.w);
;                     }
;                     if (MODE == 3) {
;                         const u32x4 pw = *(const u32x4*)(o + off);
;                         v0[0] += bf_lo(pw.x); v0[1] += bf_hi(pw.x); v0[2] += bf_lo(pw.y); v0[3] += bf_hi(pw.y);
;                         v1[0] += bf_lo(pw.z); v1[1] += bf_hi(pw.z); v1[2] += bf_lo(pw.w); v1[3] += bf_hi(pw.w);
;                     }
;                     *(u32x4*)(o + off) = pack8(v0, v1);
;                 }
	v_mov_b32_e32 v102, v101
	v_pk_mul_f32 v[102:103], v[102:103], v[100:101]
	v_pk_mov_b32 v[106:107], v[100:101], v[82:83] op_sel:[1,0]
	v_mov_b32_e32 v105, v102
	v_pk_mul_f32 v[104:105], v[104:105], v[106:107]
	v_pk_mov_b32 v[78:79], v[78:79], v[102:103] op_sel:[1,0]
	v_sub_f32_e32 v82, v104, v105
	v_add_f32_e32 v104, v83, v82
	v_pk_mov_b32 v[82:83], v[100:101], v[84:85] op_sel:[1,0]
	s_nop 0
	v_pk_mul_f32 v[78:79], v[78:79], v[82:83]
	v_pk_mov_b32 v[82:83], v[100:101], v[86:87] op_sel:[1,0]
	v_sub_f32_e32 v78, v78, v79
	v_add_f32_e32 v84, v85, v78
	v_mov_b32_e32 v78, v80
	v_mov_b32_e32 v79, v102
	v_pk_mul_f32 v[78:79], v[78:79], v[82:83]
	s_nop 0
	v_sub_f32_e32 v78, v78, v79
	v_add_f32_e32 v82, v87, v78
	v_pk_mov_b32 v[78:79], v[80:81], v[102:103] op_sel:[1,0]
	v_pk_mov_b32 v[80:81], v[100:101], v[88:89] op_sel:[1,0]
	s_nop 0
	v_pk_mul_f32 v[78:79], v[78:79], v[80:81]
	v_pk_mov_b32 v[80:81], v[100:101], v[90:91] op_sel:[1,0]
	v_sub_f32_e32 v78, v78, v79
	v_add_f32_e32 v83, v89, v78
	v_mov_b32_e32 v78, v74
	v_mov_b32_e32 v79, v102
	v_pk_mul_f32 v[78:79], v[78:79], v[80:81]
	v_pk_mov_b32 v[74:75], v[74:75], v[102:103] op_sel:[1,0]
	v_sub_f32_e32 v78, v78, v79
	v_add_f32_e32 v80, v91, v78
	v_pk_mov_b32 v[78:79], v[100:101], v[92:93] op_sel:[1,0]
	v_max_f32_e32 v81, 0, v83
	v_pk_mul_f32 v[74:75], v[74:75], v[78:79]
	v_mul_f32_e32 v81, v81, v81
	v_sub_f32_e32 v74, v74, v75
	v_add_f32_e32 v78, v93, v74
	v_fma_f32 v74, -v102, v94, v103
	v_add_f32_e32 v79, v95, v74
	v_pk_mov_b32 v[74:75], v[76:77], v[102:103] op_sel:[1,0]
	v_pk_mov_b32 v[76:77], v[100:101], v[96:97] op_sel:[1,0]
	v_max_f32_e32 v78, 0, v78
	v_pk_mul_f32 v[74:75], v[74:75], v[76:77]
	v_max_f32_e32 v76, 0, v80
	v_sub_f32_e32 v74, v74, v75
	v_add_f32_e32 v74, v97, v74
	v_max_f32_e32 v75, 0, v104
	v_max_f32_e32 v77, 0, v84
	v_max_f32_e32 v79, 0, v79
	v_mul_f32_e32 v75, v75, v75
	v_mul_f32_e32 v76, v76, v76
	v_mul_f32_e32 v77, v77, v77
	v_mul_f32_e32 v78, v78, v78
	v_max_f32_e32 v80, 0, v82
	v_mul_f32_e32 v79, v79, v79
	v_max_f32_e32 v74, 0, v74
	v_mul_f32_e32 v80, v80, v80
	v_mul_f32_e32 v82, v74, v74
	v_cvt_pk_bf16_f32 v74, v75, v77
	v_cvt_pk_bf16_f32 v75, v80, v81
	v_cvt_pk_bf16_f32 v76, v76, v78
	v_cvt_pk_bf16_f32 v77, v79, v82
	v_lshlrev_b64 v[78:79], 14, v[98:99]
	v_lshl_add_u64 v[78:79], s[26:27], 0, v[78:79]
	v_lshl_add_u64 v[90:91], v[78:79], 0, v[124:125]
	flat_store_dwordx4 v[90:91], v[74:77]
	ds_read_b128 v[74:77], v155 offset:64
	ds_read_b128 v[78:81], v155 offset:80
	ds_read_b128 v[82:85], v155 offset:96
	ds_read_b128 v[86:89], v155 offset:112
	v_mov_b32_e32 v92, v70
	v_mov_b32_e32 v93, v102
	s_waitcnt lgkmcnt(0)
	v_pk_mov_b32 v[94:95], v[100:101], v[74:75] op_sel:[1,0]
	v_pk_mov_b32 v[70:71], v[70:71], v[102:103] op_sel:[1,0]
	v_pk_mul_f32 v[92:93], v[92:93], v[94:95]
	s_mov_b64 s[26:27], 0x200000
	v_sub_f32_e32 v74, v92, v93
	v_add_f32_e32 v92, v75, v74
	v_pk_mov_b32 v[74:75], v[100:101], v[76:77] op_sel:[1,0]
	s_nop 0
	v_pk_mul_f32 v[70:71], v[70:71], v[74:75]
	v_pk_mov_b32 v[74:75], v[100:101], v[78:79] op_sel:[1,0]
	v_sub_f32_e32 v70, v70, v71
	v_add_f32_e32 v76, v77, v70
	v_mov_b32_e32 v70, v72
	v_mov_b32_e32 v71, v102
	v_pk_mul_f32 v[70:71], v[70:71], v[74:75]
	s_nop 0
	v_sub_f32_e32 v70, v70, v71
	v_add_f32_e32 v74, v79, v70
	v_pk_mov_b32 v[70:71], v[72:73], v[102:103] op_sel:[1,0]
	v_pk_mov_b32 v[72:73], v[100:101], v[80:81] op_sel:[1,0]
	s_nop 0
	v_pk_mul_f32 v[70:71], v[70:71], v[72:73]
	v_pk_mov_b32 v[72:73], v[100:101], v[82:83] op_sel:[1,0]
	v_sub_f32_e32 v70, v70, v71
	v_add_f32_e32 v75, v81, v70
	v_mov_b32_e32 v70, v66
	v_mov_b32_e32 v71, v102
	v_pk_mul_f32 v[70:71], v[70:71], v[72:73]
	v_pk_mov_b32 v[66:67], v[66:67], v[102:103] op_sel:[1,0]
	v_sub_f32_e32 v70, v70, v71
	v_add_f32_e32 v72, v83, v70
	v_pk_mov_b32 v[70:71], v[100:101], v[84:85] op_sel:[1,0]
	s_nop 0
	v_pk_mul_f32 v[66:67], v[66:67], v[70:71]
	v_pk_mov_b32 v[70:71], v[100:101], v[86:87] op_sel:[1,0]
	v_sub_f32_e32 v66, v66, v67
	v_add_f32_e32 v73, v85, v66
	v_mov_b32_e32 v66, v68
	v_mov_b32_e32 v67, v102
	v_pk_mul_f32 v[66:67], v[66:67], v[70:71]
	v_max_f32_e32 v71, 0, v73
	v_sub_f32_e32 v66, v66, v67
	v_add_f32_e32 v70, v87, v66
	v_pk_mov_b32 v[66:67], v[68:69], v[102:103] op_sel:[1,0]
	v_pk_mov_b32 v[68:69], v[100:101], v[88:89] op_sel:[1,0]
	v_max_f32_e32 v70, 0, v70
	v_pk_mul_f32 v[66:67], v[66:67], v[68:69]
	v_max_f32_e32 v68, 0, v72
	v_sub_f32_e32 v66, v66, v67
	v_add_f32_e32 v66, v89, v66
	v_max_f32_e32 v67, 0, v92
	v_max_f32_e32 v69, 0, v76
	v_mul_f32_e32 v67, v67, v67
	v_mul_f32_e32 v68, v68, v68
	v_mul_f32_e32 v69, v69, v69
	v_max_f32_e32 v72, 0, v74
	v_max_f32_e32 v73, 0, v75
	v_max_f32_e32 v66, 0, v66
	v_mul_f32_e32 v71, v71, v71
	v_mul_f32_e32 v72, v72, v72
	v_mul_f32_e32 v70, v70, v70
	v_mul_f32_e32 v73, v73, v73
	v_mul_f32_e32 v74, v66, v66
	v_cvt_pk_bf16_f32 v66, v67, v69
	v_cvt_pk_bf16_f32 v67, v72, v73
	v_cvt_pk_bf16_f32 v68, v68, v71
	v_cvt_pk_bf16_f32 v69, v70, v74
	flat_store_dwordx4 v[90:91], v[66:69] offset:16
	ds_read_b64 v[82:83], v156 offset:1024
	ds_read_b128 v[66:69], v155
	ds_read_b128 v[70:73], v155 offset:16
	ds_read_b128 v[74:77], v155 offset:32
	ds_read_b128 v[78:81], v155 offset:48
	s_waitcnt lgkmcnt(0)
; #define LAS __attribute__((address_space(3)))
; __device__ __forceinline__ float bf_lo(unsigned w) { return __uint_as_float(w << 16); }
;     __device__ __forceinline__ void operator()(const f32x4 (&acc)[2][2][4][2], const pg8::Unit& u, int wr, int wc, int fr, int fq, LAS unsigned char* lds, int par) const {
;         const bool fold = F.stats != nullptr;
;         const LAS float* rsb = (const LAS float*)(lds + RS_OFF) + par * 512; const LAS float* cvb = (const LAS float*)(lds + CV_OFF) + (par * 2 + wr) * 512;
;         const int row0 = u.pm * 256 + wr * 64 + fr, c0 = u.pn * 256 + wc * 64 + 16 * fq;
; #pragma unroll
;         for (int ai = 0; ai < 2; ++ai)
; #pragma unroll
;             for (int m = 0; m < 4; ++m) {
;                 const int row = row0 + ai * 128 + m * 16, lrow = ai * 128 + wr * 64 + m * 16 + fr;
;                 float mu = 0.f, rstd = 1.f; if (fold) { mu = rsb[2 * lrow]; rstd = rsb[2 * lrow + 1]; }
; #pragma unroll
;                 for (int bj = 0; bj < 2; ++bj) {
;                     const size_t off = (size_t)row * ld + c0 + bj * 8;
;                     f32x4 v0 = acc[ai][bj][m][0], v1 = acc[ai][bj][m][1];
;                     if (fold) fold_apply(v0, v1, mu, rstd, cvb, wc * 64 + 16 * fq + bj * 8);
;                     if (MODE == 0) { v0 *= scale; v1 *= scale; }
;                     if (MODE == 1) {
; #pragma unroll
;                         for (int j = 0; j < 4; ++j) { const float a = fmaxf(v0[j], 0.f), b = fmaxf(v1[j], 0.f); v0[j] = a * a; v1[j] = b * b; }
;                     }
;                     if (MODE == 2 || MODE == 3) {
;                         const u32x4 gw = *(const u32x4*)(gate + off);
;                         v0[0] *= bf_lo(gw.x); v0[1] *= bf_hi(gw.x); v0[2] *= bf_lo(gw.y); v0[3] *= bf_hi(gw.y);
;                         v1[0] *= bf_lo(gw.z); v1[1] *= bf_hi(gw.z); v1[2] *= bf_lo(gw.w); v1[3] *= bf_hi(gw.w);
;                     }
;                     if (MODE == 3) {
;                         const u32x4 pw = *(const u32x4*)(o + off);
;                         v0[0] += bf_lo(pw.x); v0[1] += bf_hi(pw.x); v0[2] += bf_lo(pw.y); v0[3] += bf_hi(pw.y);
;                         v1[0] += bf_lo(pw.z); v1[1] += bf_hi(pw.z); v1[2] += bf_lo(pw.w); v1[3] += bf_hi(pw.w);
;                     }
;                     *(u32x4*)(o + off) = pack8(v0, v1);
;                 }
	v_mov_b32_e32 v84, v83
	v_mov_b32_e32 v85, v60
	v_pk_mul_f32 v[84:85], v[84:85], v[82:83]
	v_mov_b32_e32 v86, v62
	v_mov_b32_e32 v87, v84
	v_pk_mov_b32 v[88:89], v[82:83], v[66:67] op_sel:[1,0]
	v_pk_mov_b32 v[62:63], v[62:63], v[84:85] op_sel:[1,0]
	v_pk_mul_f32 v[86:87], v[86:87], v[88:89]
	s_nop 0
	v_sub_f32_e32 v66, v86, v87
	v_add_f32_e32 v86, v67, v66
	v_pk_mov_b32 v[66:67], v[82:83], v[68:69] op_sel:[1,0]
	s_nop 0
	v_pk_mul_f32 v[62:63], v[62:63], v[66:67]
	v_pk_mov_b32 v[66:67], v[82:83], v[70:71] op_sel:[1,0]
	v_sub_f32_e32 v62, v62, v63
	v_add_f32_e32 v68, v69, v62
	v_mov_b32_e32 v62, v64
	v_mov_b32_e32 v63, v84
	v_pk_mul_f32 v[62:63], v[62:63], v[66:67]
	s_nop 0
	v_sub_f32_e32 v62, v62, v63
	v_add_f32_e32 v66, v71, v62
	v_pk_mov_b32 v[62:63], v[64:65], v[84:85] op_sel:[1,0]
	v_pk_mov_b32 v[64:65], v[82:83], v[72:73] op_sel:[1,0]
	s_nop 0
	v_pk_mul_f32 v[62:63], v[62:63], v[64:65]
	v_pk_mov_b32 v[64:65], v[82:83], v[74:75] op_sel:[1,0]
	v_sub_f32_e32 v62, v62, v63
	v_add_f32_e32 v67, v73, v62
	v_mov_b32_e32 v62, v58
	v_mov_b32_e32 v63, v84
	v_pk_mul_f32 v[62:63], v[62:63], v[64:65]
	v_pk_mov_b32 v[58:59], v[58:59], v[84:85] op_sel:[1,0]
	v_sub_f32_e32 v62, v62, v63
	v_add_f32_e32 v64, v75, v62
	v_pk_mov_b32 v[62:63], v[82:83], v[76:77] op_sel:[1,0]
	v_max_f32_e32 v65, 0, v67
	v_pk_mul_f32 v[58:59], v[58:59], v[62:63]
	v_mul_f32_e32 v65, v65, v65
	v_sub_f32_e32 v58, v58, v59
	v_add_f32_e32 v62, v77, v58
	v_fma_f32 v58, -v84, v78, v85
	v_add_f32_e32 v63, v79, v58
	v_pk_mov_b32 v[58:59], v[60:61], v[84:85] op_sel:[1,0]
	v_pk_mov_b32 v[60:61], v[82:83], v[80:81] op_sel:[1,0]
	v_max_f32_e32 v62, 0, v62
	v_pk_mul_f32 v[58:59], v[58:59], v[60:61]
	v_max_f32_e32 v60, 0, v64
	v_sub_f32_e32 v58, v58, v59
	v_add_f32_e32 v58, v81, v58
	v_max_f32_e32 v59, 0, v86
	v_mul_f32_e32 v59, v59, v59
	v_mul_f32_e32 v60, v60, v60
	v_max_f32_e32 v61, 0, v68
	v_mul_f32_e32 v62, v62, v62
	v_max_f32_e32 v64, 0, v66
	v_max_f32_e32 v63, 0, v63
	v_max_f32_e32 v58, 0, v58
	v_mul_f32_e32 v61, v61, v61
	v_mul_f32_e32 v64, v64, v64
	v_mul_f32_e32 v63, v63, v63
	v_mul_f32_e32 v66, v58, v58
	v_cvt_pk_bf16_f32 v58, v59, v61
	v_cvt_pk_bf16_f32 v59, v64, v65
	v_cvt_pk_bf16_f32 v60, v60, v62
	v_add_co_u32_e32 v62, vcc, s15, v122
	v_cvt_pk_bf16_f32 v61, v63, v66
	v_mov_b32_e32 v76, v54
	s_nop 0
	v_addc_co_u32_e32 v63, vcc, 0, v123, vcc
	flat_store_dwordx4 v[62:63], v[58:61]
	ds_read_b128 v[58:61], v155 offset:64
	ds_read_b128 v[62:65], v155 offset:80
	ds_read_b128 v[66:69], v155 offset:96
	ds_read_b128 v[70:73], v155 offset:112
	v_mov_b32_e32 v77, v84
	s_waitcnt lgkmcnt(0)
	v_pk_mov_b32 v[78:79], v[82:83], v[58:59] op_sel:[1,0]
	v_pk_mov_b32 v[54:55], v[54:55], v[84:85] op_sel:[1,0]
	v_pk_mul_f32 v[76:77], v[76:77], v[78:79]
	v_lshl_add_u64 v[74:75], v[122:123], 0, s[26:27]
	v_sub_f32_e32 v58, v76, v77
	v_add_f32_e32 v76, v59, v58
	v_pk_mov_b32 v[58:59], v[82:83], v[60:61] op_sel:[1,0]
	s_mov_b32 s15, 0x240000
	v_pk_mul_f32 v[54:55], v[54:55], v[58:59]
	v_pk_mov_b32 v[58:59], v[82:83], v[62:63] op_sel:[1,0]
	v_sub_f32_e32 v54, v54, v55
	v_add_f32_e32 v60, v61, v54
	v_mov_b32_e32 v54, v56
	v_mov_b32_e32 v55, v84
	v_pk_mul_f32 v[54:55], v[54:55], v[58:59]
	s_mov_b64 s[26:27], 0x240000
	v_sub_f32_e32 v54, v54, v55
	v_add_f32_e32 v58, v63, v54
	v_pk_mov_b32 v[54:55], v[56:57], v[84:85] op_sel:[1,0]
	v_pk_mov_b32 v[56:57], v[82:83], v[64:65] op_sel:[1,0]
	s_nop 0
	v_pk_mul_f32 v[54:55], v[54:55], v[56:57]
	v_pk_mov_b32 v[56:57], v[82:83], v[66:67] op_sel:[1,0]
	v_sub_f32_e32 v54, v54, v55
	v_add_f32_e32 v59, v65, v54
	v_mov_b32_e32 v54, v50
	v_mov_b32_e32 v55, v84
	v_pk_mul_f32 v[54:55], v[54:55], v[56:57]
	v_pk_mov_b32 v[50:51], v[50:51], v[84:85] op_sel:[1,0]
	v_sub_f32_e32 v54, v54, v55
	v_add_f32_e32 v56, v67, v54
	v_pk_mov_b32 v[54:55], v[82:83], v[68:69] op_sel:[1,0]
	s_nop 0
	v_pk_mul_f32 v[50:51], v[50:51], v[54:55]
	v_pk_mov_b32 v[54:55], v[82:83], v[70:71] op_sel:[1,0]
	v_sub_f32_e32 v50, v50, v51
	v_add_f32_e32 v57, v69, v50
	v_mov_b32_e32 v50, v52
	v_mov_b32_e32 v51, v84
	v_pk_mul_f32 v[50:51], v[50:51], v[54:55]
	v_max_f32_e32 v55, 0, v57
	v_sub_f32_e32 v50, v50, v51
	v_add_f32_e32 v54, v71, v50
	v_pk_mov_b32 v[50:51], v[52:53], v[84:85] op_sel:[1,0]
	v_pk_mov_b32 v[52:53], v[82:83], v[72:73] op_sel:[1,0]
	v_max_f32_e32 v54, 0, v54
	v_pk_mul_f32 v[50:51], v[50:51], v[52:53]
	v_max_f32_e32 v52, 0, v56
	v_sub_f32_e32 v50, v50, v51
	v_add_f32_e32 v50, v73, v50
	v_max_f32_e32 v51, 0, v76
	v_max_f32_e32 v53, 0, v60
	v_mul_f32_e32 v51, v51, v51
	v_mul_f32_e32 v52, v52, v52
	v_mul_f32_e32 v53, v53, v53
	v_max_f32_e32 v56, 0, v58
	v_max_f32_e32 v57, 0, v59
	v_max_f32_e32 v50, 0, v50
	v_mul_f32_e32 v55, v55, v55
	v_mul_f32_e32 v56, v56, v56
	v_mul_f32_e32 v54, v54, v54
	v_mul_f32_e32 v57, v57, v57
	v_mul_f32_e32 v58, v50, v50
	v_cvt_pk_bf16_f32 v50, v51, v53
	v_cvt_pk_bf16_f32 v51, v56, v57
	v_cvt_pk_bf16_f32 v52, v52, v55
	v_cvt_pk_bf16_f32 v53, v54, v58
	flat_store_dwordx4 v[74:75], v[50:53] offset:16
	ds_read_b64 v[66:67], v156 offset:1152
	ds_read_b128 v[50:53], v155
	ds_read_b128 v[54:57], v155 offset:16
	ds_read_b128 v[58:61], v155 offset:32
	ds_read_b128 v[62:65], v155 offset:48
	s_waitcnt lgkmcnt(0)
; #define LAS __attribute__((address_space(3)))
; __device__ __forceinline__ float bf_lo(unsigned w) { return __uint_as_float(w << 16); }
;     __device__ __forceinline__ void operator()(const f32x4 (&acc)[2][2][4][2], const pg8::Unit& u, int wr, int wc, int fr, int fq, LAS unsigned char* lds, int par) const {
;         const bool fold = F.stats != nullptr;
;         const LAS float* rsb = (const LAS float*)(lds + RS_OFF) + par * 512; const LAS float* cvb = (const LAS float*)(lds + CV_OFF) + (par * 2 + wr) * 512;
;         const int row0 = u.pm * 256 + wr * 64 + fr, c0 = u.pn * 256 + wc * 64 + 16 * fq;
; #pragma unroll
;         for (int ai = 0; ai < 2; ++ai)
; #pragma unroll
;             for (int m = 0; m < 4; ++m) {
;                 const int row = row0 + ai * 128 + m * 16, lrow = ai * 128 + wr * 64 + m * 16 + fr;
;                 float mu = 0.f, rstd = 1.f; if (fold) { mu = rsb[2 * lrow]; rstd = rsb[2 * lrow + 1]; }
; #pragma unroll
;                 for (int bj = 0; bj < 2; ++bj) {
;                     const size_t off = (size_t)row * ld + c0 + bj * 8;
;                     f32x4 v0 = acc[ai][bj][m][0], v1 = acc[ai][bj][m][1];
;                     if (fold) fold_apply(v0, v1, mu, rstd, cvb, wc * 64 + 16 * fq + bj * 8);
;                     if (MODE == 0) { v0 *= scale; v1 *= scale; }
;                     if (MODE == 1) {
; #pragma unroll
;                         for (int j = 0; j < 4; ++j) { const float a = fmaxf(v0[j], 0.f), b = fmaxf(v1[j], 0.f); v0[j] = a * a; v1[j] = b * b; }
;                     }
;                     if (MODE == 2 || MODE == 3) {
;                         const u32x4 gw = *(const u32x4*)(gate + off);
;                         v0[0] *= bf_lo(gw.x); v0[1] *= bf_hi(gw.x); v0[2] *= bf_lo(gw.y); v0[3] *= bf_hi(gw.y);
;                         v1[0] *= bf_lo(gw.z); v1[1] *= bf_hi(gw.z); v1[2] *= bf_lo(gw.w); v1[3] *= bf_hi(gw.w);
;                     }
;                     if (MODE == 3) {
;                         const u32x4 pw = *(const u32x4*)(o + off);
;                         v0[0] += bf_lo(pw.x); v0[1] += bf_hi(pw.x); v0[2] += bf_lo(pw.y); v0[3] += bf_hi(pw.y);
;                         v1[0] += bf_lo(pw.z); v1[1] += bf_hi(pw.z); v1[2] += bf_lo(pw.w); v1[3] += bf_hi(pw.w);
;                     }
;                     *(u32x4*)(o + off) = pack8(v0, v1);
;                 }
	v_mov_b32_e32 v68, v67
	v_mov_b32_e32 v69, v44
	v_pk_mul_f32 v[68:69], v[68:69], v[66:67]
	v_mov_b32_e32 v70, v46
	v_mov_b32_e32 v71, v68
	v_pk_mov_b32 v[72:73], v[66:67], v[50:51] op_sel:[1,0]
	v_pk_mov_b32 v[46:47], v[46:47], v[68:69] op_sel:[1,0]
	v_pk_mul_f32 v[70:71], v[70:71], v[72:73]
	s_nop 0
	v_sub_f32_e32 v50, v70, v71
	v_add_f32_e32 v70, v51, v50
	v_pk_mov_b32 v[50:51], v[66:67], v[52:53] op_sel:[1,0]
	s_nop 0
	v_pk_mul_f32 v[46:47], v[46:47], v[50:51]
	v_pk_mov_b32 v[50:51], v[66:67], v[54:55] op_sel:[1,0]
	v_sub_f32_e32 v46, v46, v47
	v_add_f32_e32 v52, v53, v46
	v_mov_b32_e32 v46, v48
	v_mov_b32_e32 v47, v68
	v_pk_mul_f32 v[46:47], v[46:47], v[50:51]
	s_nop 0
	v_sub_f32_e32 v46, v46, v47
	v_add_f32_e32 v50, v55, v46
	v_pk_mov_b32 v[46:47], v[48:49], v[68:69] op_sel:[1,0]
	v_pk_mov_b32 v[48:49], v[66:67], v[56:57] op_sel:[1,0]
	s_nop 0
	v_pk_mul_f32 v[46:47], v[46:47], v[48:49]
	v_pk_mov_b32 v[48:49], v[66:67], v[58:59] op_sel:[1,0]
	v_sub_f32_e32 v46, v46, v47
	v_add_f32_e32 v51, v57, v46
	v_mov_b32_e32 v46, v42
	v_mov_b32_e32 v47, v68
	v_pk_mul_f32 v[46:47], v[46:47], v[48:49]
	v_pk_mov_b32 v[42:43], v[42:43], v[68:69] op_sel:[1,0]
	v_sub_f32_e32 v46, v46, v47
	v_add_f32_e32 v48, v59, v46
	v_pk_mov_b32 v[46:47], v[66:67], v[60:61] op_sel:[1,0]
	v_max_f32_e32 v49, 0, v51
	v_pk_mul_f32 v[42:43], v[42:43], v[46:47]
	v_mul_f32_e32 v49, v49, v49
	v_sub_f32_e32 v42, v42, v43
	v_add_f32_e32 v46, v61, v42
	v_fma_f32 v42, -v68, v62, v69
	v_add_f32_e32 v47, v63, v42
	v_pk_mov_b32 v[42:43], v[44:45], v[68:69] op_sel:[1,0]
	v_pk_mov_b32 v[44:45], v[66:67], v[64:65] op_sel:[1,0]
	v_max_f32_e32 v46, 0, v46
	v_pk_mul_f32 v[42:43], v[42:43], v[44:45]
	v_max_f32_e32 v44, 0, v48
	v_sub_f32_e32 v42, v42, v43
	v_add_f32_e32 v42, v65, v42
	v_max_f32_e32 v43, 0, v70
	v_mul_f32_e32 v43, v43, v43
	v_mul_f32_e32 v44, v44, v44
	v_max_f32_e32 v45, 0, v52
	v_mul_f32_e32 v46, v46, v46
	v_max_f32_e32 v48, 0, v50
	v_max_f32_e32 v47, 0, v47
	v_max_f32_e32 v42, 0, v42
	v_mul_f32_e32 v45, v45, v45
	v_mul_f32_e32 v48, v48, v48
	v_mul_f32_e32 v47, v47, v47
	v_mul_f32_e32 v50, v42, v42
	v_cvt_pk_bf16_f32 v42, v43, v45
	v_cvt_pk_bf16_f32 v43, v48, v49
	v_cvt_pk_bf16_f32 v44, v44, v46
	v_add_co_u32_e32 v46, vcc, s15, v122
	v_cvt_pk_bf16_f32 v45, v47, v50
	v_mov_b32_e32 v60, v38
	s_nop 0
	v_addc_co_u32_e32 v47, vcc, 0, v123, vcc
	flat_store_dwordx4 v[46:47], v[42:45]
	ds_read_b128 v[42:45], v155 offset:64
	ds_read_b128 v[46:49], v155 offset:80
	ds_read_b128 v[50:53], v155 offset:96
	ds_read_b128 v[54:57], v155 offset:112
	v_mov_b32_e32 v61, v68
	s_waitcnt lgkmcnt(0)
	v_pk_mov_b32 v[62:63], v[66:67], v[42:43] op_sel:[1,0]
	v_pk_mov_b32 v[38:39], v[38:39], v[68:69] op_sel:[1,0]
	v_pk_mul_f32 v[60:61], v[60:61], v[62:63]
	v_lshl_add_u64 v[58:59], v[122:123], 0, s[26:27]
	v_sub_f32_e32 v42, v60, v61
	v_add_f32_e32 v60, v43, v42
	v_pk_mov_b32 v[42:43], v[66:67], v[44:45] op_sel:[1,0]
	s_mov_b32 s15, 0x280000
	v_pk_mul_f32 v[38:39], v[38:39], v[42:43]
	v_pk_mov_b32 v[42:43], v[66:67], v[46:47] op_sel:[1,0]
	v_sub_f32_e32 v38, v38, v39
	v_add_f32_e32 v44, v45, v38
	v_mov_b32_e32 v38, v40
	v_mov_b32_e32 v39, v68
	v_pk_mul_f32 v[38:39], v[38:39], v[42:43]
	s_mov_b64 s[26:27], 0x280000
	v_sub_f32_e32 v38, v38, v39
	v_add_f32_e32 v42, v47, v38
	v_pk_mov_b32 v[38:39], v[40:41], v[68:69] op_sel:[1,0]
	v_pk_mov_b32 v[40:41], v[66:67], v[48:49] op_sel:[1,0]
	s_nop 0
	v_pk_mul_f32 v[38:39], v[38:39], v[40:41]
	v_pk_mov_b32 v[40:41], v[66:67], v[50:51] op_sel:[1,0]
	v_sub_f32_e32 v38, v38, v39
	v_add_f32_e32 v43, v49, v38
	v_mov_b32_e32 v38, v34
	v_mov_b32_e32 v39, v68
	v_pk_mul_f32 v[38:39], v[38:39], v[40:41]
	v_pk_mov_b32 v[34:35], v[34:35], v[68:69] op_sel:[1,0]
	v_sub_f32_e32 v38, v38, v39
	v_add_f32_e32 v40, v51, v38
	v_pk_mov_b32 v[38:39], v[66:67], v[52:53] op_sel:[1,0]
	s_nop 0
	v_pk_mul_f32 v[34:35], v[34:35], v[38:39]
	v_pk_mov_b32 v[38:39], v[66:67], v[54:55] op_sel:[1,0]
	v_sub_f32_e32 v34, v34, v35
	v_add_f32_e32 v41, v53, v34
	v_mov_b32_e32 v34, v36
	v_mov_b32_e32 v35, v68
	v_pk_mul_f32 v[34:35], v[34:35], v[38:39]
	v_max_f32_e32 v39, 0, v41
	v_sub_f32_e32 v34, v34, v35
	v_add_f32_e32 v38, v55, v34
	v_pk_mov_b32 v[34:35], v[36:37], v[68:69] op_sel:[1,0]
	v_pk_mov_b32 v[36:37], v[66:67], v[56:57] op_sel:[1,0]
	v_max_f32_e32 v38, 0, v38
	v_pk_mul_f32 v[34:35], v[34:35], v[36:37]
	v_max_f32_e32 v36, 0, v40
	v_sub_f32_e32 v34, v34, v35
	v_add_f32_e32 v34, v57, v34
	v_max_f32_e32 v35, 0, v60
	v_max_f32_e32 v37, 0, v44
	v_mul_f32_e32 v35, v35, v35
	v_mul_f32_e32 v36, v36, v36
	v_mul_f32_e32 v37, v37, v37
	v_max_f32_e32 v40, 0, v42
	v_max_f32_e32 v41, 0, v43
	v_max_f32_e32 v34, 0, v34
	v_mul_f32_e32 v39, v39, v39
	v_mul_f32_e32 v40, v40, v40
	v_mul_f32_e32 v38, v38, v38
	v_mul_f32_e32 v41, v41, v41
	v_mul_f32_e32 v42, v34, v34
	v_cvt_pk_bf16_f32 v34, v35, v37
	v_cvt_pk_bf16_f32 v35, v40, v41
	v_cvt_pk_bf16_f32 v36, v36, v39
	v_cvt_pk_bf16_f32 v37, v38, v42
	flat_store_dwordx4 v[58:59], v[34:37] offset:16
	ds_read_b64 v[50:51], v156 offset:1280
	ds_read_b128 v[34:37], v155
	ds_read_b128 v[38:41], v155 offset:16
	ds_read_b128 v[42:45], v155 offset:32
	ds_read_b128 v[46:49], v155 offset:48
	s_waitcnt lgkmcnt(0)
; #define LAS __attribute__((address_space(3)))
; __device__ __forceinline__ float bf_lo(unsigned w) { return __uint_as_float(w << 16); }
;     __device__ __forceinline__ void operator()(const f32x4 (&acc)[2][2][4][2], const pg8::Unit& u, int wr, int wc, int fr, int fq, LAS unsigned char* lds, int par) const {
;         const bool fold = F.stats != nullptr;
;         const LAS float* rsb = (const LAS float*)(lds + RS_OFF) + par * 512; const LAS float* cvb = (const LAS float*)(lds + CV_OFF) + (par * 2 + wr) * 512;
;         const int row0 = u.pm * 256 + wr * 64 + fr, c0 = u.pn * 256 + wc * 64 + 16 * fq;
; #pragma unroll
;         for (int ai = 0; ai < 2; ++ai)
; #pragma unroll
;             for (int m = 0; m < 4; ++m) {
;                 const int row = row0 + ai * 128 + m * 16, lrow = ai * 128 + wr * 64 + m * 16 + fr;
;                 float mu = 0.f, rstd = 1.f; if (fold) { mu = rsb[2 * lrow]; rstd = rsb[2 * lrow + 1]; }
; #pragma unroll
;                 for (int bj = 0; bj < 2; ++bj) {
;                     const size_t off = (size_t)row * ld + c0 + bj * 8;
;                     f32x4 v0 = acc[ai][bj][m][0], v1 = acc[ai][bj][m][1];
;                     if (fold) fold_apply(v0, v1, mu, rstd, cvb, wc * 64 + 16 * fq + bj * 8);
;                     if (MODE == 0) { v0 *= scale; v1 *= scale; }
;                     if (MODE == 1) {
; #pragma unroll
;                         for (int j = 0; j < 4; ++j) { const float a = fmaxf(v0[j], 0.f), b = fmaxf(v1[j], 0.f); v0[j] = a * a; v1[j] = b * b; }
;                     }
;                     if (MODE == 2 || MODE == 3) {
;                         const u32x4 gw = *(const u32x4*)(gate + off);
;                         v0[0] *= bf_lo(gw.x); v0[1] *= bf_hi(gw.x); v0[2] *= bf_lo(gw.y); v0[3] *= bf_hi(gw.y);
;                         v1[0] *= bf_lo(gw.z); v1[1] *= bf_hi(gw.z); v1[2] *= bf_lo(gw.w); v1[3] *= bf_hi(gw.w);
;                     }
;                     if (MODE == 3) {
;                         const u32x4 pw = *(const u32x4*)(o + off);
;                         v0[0] += bf_lo(pw.x); v0[1] += bf_hi(pw.x); v0[2] += bf_lo(pw.y); v0[3] += bf_hi(pw.y);
;                         v1[0] += bf_lo(pw.z); v1[1] += bf_hi(pw.z); v1[2] += bf_lo(pw.w); v1[3] += bf_hi(pw.w);
;                     }
;                     *(u32x4*)(o + off) = pack8(v0, v1);
;                 }
	v_mov_b32_e32 v52, v51
	v_mov_b32_e32 v53, v28
	v_pk_mul_f32 v[52:53], v[52:53], v[50:51]
	v_mov_b32_e32 v54, v30
	v_mov_b32_e32 v55, v52
	v_pk_mov_b32 v[56:57], v[50:51], v[34:35] op_sel:[1,0]
	v_pk_mov_b32 v[30:31], v[30:31], v[52:53] op_sel:[1,0]
	v_pk_mul_f32 v[54:55], v[54:55], v[56:57]
	s_nop 0
	v_sub_f32_e32 v34, v54, v55
	v_add_f32_e32 v54, v35, v34
	v_pk_mov_b32 v[34:35], v[50:51], v[36:37] op_sel:[1,0]
	s_nop 0
	v_pk_mul_f32 v[30:31], v[30:31], v[34:35]
	v_pk_mov_b32 v[34:35], v[50:51], v[38:39] op_sel:[1,0]
	v_sub_f32_e32 v30, v30, v31
	v_add_f32_e32 v36, v37, v30
	v_mov_b32_e32 v30, v32
	v_mov_b32_e32 v31, v52
	v_pk_mul_f32 v[30:31], v[30:31], v[34:35]
	s_nop 0
	v_sub_f32_e32 v30, v30, v31
	v_add_f32_e32 v34, v39, v30
	v_pk_mov_b32 v[30:31], v[32:33], v[52:53] op_sel:[1,0]
	v_pk_mov_b32 v[32:33], v[50:51], v[40:41] op_sel:[1,0]
	s_nop 0
	v_pk_mul_f32 v[30:31], v[30:31], v[32:33]
	v_pk_mov_b32 v[32:33], v[50:51], v[42:43] op_sel:[1,0]
	v_sub_f32_e32 v30, v30, v31
	v_add_f32_e32 v35, v41, v30
	v_mov_b32_e32 v30, v26
	v_mov_b32_e32 v31, v52
	v_pk_mul_f32 v[30:31], v[30:31], v[32:33]
	v_pk_mov_b32 v[26:27], v[26:27], v[52:53] op_sel:[1,0]
	v_sub_f32_e32 v30, v30, v31
	v_add_f32_e32 v32, v43, v30
	v_pk_mov_b32 v[30:31], v[50:51], v[44:45] op_sel:[1,0]
	v_max_f32_e32 v33, 0, v35
	v_pk_mul_f32 v[26:27], v[26:27], v[30:31]
	v_mul_f32_e32 v33, v33, v33
	v_sub_f32_e32 v26, v26, v27
	v_add_f32_e32 v30, v45, v26
	v_fma_f32 v26, -v52, v46, v53
	v_add_f32_e32 v31, v47, v26
	v_pk_mov_b32 v[26:27], v[28:29], v[52:53] op_sel:[1,0]
	v_pk_mov_b32 v[28:29], v[50:51], v[48:49] op_sel:[1,0]
	v_max_f32_e32 v30, 0, v30
	v_pk_mul_f32 v[26:27], v[26:27], v[28:29]
	v_max_f32_e32 v28, 0, v32
	v_sub_f32_e32 v26, v26, v27
	v_add_f32_e32 v26, v49, v26
	v_max_f32_e32 v27, 0, v54
	v_mul_f32_e32 v27, v27, v27
	v_mul_f32_e32 v28, v28, v28
	v_max_f32_e32 v29, 0, v36
	v_mul_f32_e32 v30, v30, v30
	v_max_f32_e32 v32, 0, v34
	v_max_f32_e32 v31, 0, v31
	v_max_f32_e32 v26, 0, v26
	v_mul_f32_e32 v29, v29, v29
	v_mul_f32_e32 v32, v32, v32
	v_mul_f32_e32 v31, v31, v31
	v_mul_f32_e32 v34, v26, v26
	v_cvt_pk_bf16_f32 v26, v27, v29
	v_cvt_pk_bf16_f32 v27, v32, v33
	v_cvt_pk_bf16_f32 v28, v28, v30
	v_add_co_u32_e32 v30, vcc, s15, v122
	v_cvt_pk_bf16_f32 v29, v31, v34
	v_mov_b32_e32 v44, v22
	s_nop 0
	v_addc_co_u32_e32 v31, vcc, 0, v123, vcc
	flat_store_dwordx4 v[30:31], v[26:29]
	ds_read_b128 v[26:29], v155 offset:64
	ds_read_b128 v[30:33], v155 offset:80
	ds_read_b128 v[34:37], v155 offset:96
	ds_read_b128 v[38:41], v155 offset:112
	v_mov_b32_e32 v45, v52
	s_waitcnt lgkmcnt(0)
	v_pk_mov_b32 v[46:47], v[50:51], v[26:27] op_sel:[1,0]
	v_pk_mov_b32 v[22:23], v[22:23], v[52:53] op_sel:[1,0]
	v_pk_mul_f32 v[44:45], v[44:45], v[46:47]
	v_lshl_add_u64 v[42:43], v[122:123], 0, s[26:27]
	v_sub_f32_e32 v26, v44, v45
	v_add_f32_e32 v44, v27, v26
	v_pk_mov_b32 v[26:27], v[50:51], v[28:29] op_sel:[1,0]
	s_mov_b32 s15, 0x2c0000
	v_pk_mul_f32 v[22:23], v[22:23], v[26:27]
	v_pk_mov_b32 v[26:27], v[50:51], v[30:31] op_sel:[1,0]
	v_sub_f32_e32 v22, v22, v23
	v_add_f32_e32 v28, v29, v22
	v_mov_b32_e32 v22, v24
	v_mov_b32_e32 v23, v52
	v_pk_mul_f32 v[22:23], v[22:23], v[26:27]
	s_mov_b64 s[26:27], 0x2c0000
	v_sub_f32_e32 v22, v22, v23
	v_add_f32_e32 v26, v31, v22
	v_pk_mov_b32 v[22:23], v[24:25], v[52:53] op_sel:[1,0]
	v_pk_mov_b32 v[24:25], v[50:51], v[32:33] op_sel:[1,0]
	s_nop 0
	v_pk_mul_f32 v[22:23], v[22:23], v[24:25]
	v_pk_mov_b32 v[24:25], v[50:51], v[34:35] op_sel:[1,0]
	v_sub_f32_e32 v22, v22, v23
	v_add_f32_e32 v27, v33, v22
	v_mov_b32_e32 v22, v18
	v_mov_b32_e32 v23, v52
	v_pk_mul_f32 v[22:23], v[22:23], v[24:25]
	v_pk_mov_b32 v[18:19], v[18:19], v[52:53] op_sel:[1,0]
	v_sub_f32_e32 v22, v22, v23
	v_add_f32_e32 v24, v35, v22
	v_pk_mov_b32 v[22:23], v[50:51], v[36:37] op_sel:[1,0]
	s_nop 0
	v_pk_mul_f32 v[18:19], v[18:19], v[22:23]
	v_pk_mov_b32 v[22:23], v[50:51], v[38:39] op_sel:[1,0]
	v_sub_f32_e32 v18, v18, v19
	v_add_f32_e32 v25, v37, v18
	v_mov_b32_e32 v18, v20
	v_mov_b32_e32 v19, v52
	v_pk_mul_f32 v[18:19], v[18:19], v[22:23]
	v_max_f32_e32 v23, 0, v25
	v_sub_f32_e32 v18, v18, v19
	v_add_f32_e32 v22, v39, v18
	v_pk_mov_b32 v[18:19], v[20:21], v[52:53] op_sel:[1,0]
	v_pk_mov_b32 v[20:21], v[50:51], v[40:41] op_sel:[1,0]
	v_max_f32_e32 v22, 0, v22
	v_pk_mul_f32 v[18:19], v[18:19], v[20:21]
	v_max_f32_e32 v20, 0, v24
	v_sub_f32_e32 v18, v18, v19
	v_add_f32_e32 v18, v41, v18
	v_max_f32_e32 v19, 0, v44
	v_max_f32_e32 v21, 0, v28
	v_mul_f32_e32 v19, v19, v19
	v_mul_f32_e32 v20, v20, v20
	v_mul_f32_e32 v21, v21, v21
	v_max_f32_e32 v24, 0, v26
	v_max_f32_e32 v25, 0, v27
	v_max_f32_e32 v18, 0, v18
	v_mul_f32_e32 v23, v23, v23
	v_mul_f32_e32 v24, v24, v24
	v_mul_f32_e32 v22, v22, v22
	v_mul_f32_e32 v25, v25, v25
	v_mul_f32_e32 v26, v18, v18
	v_cvt_pk_bf16_f32 v18, v19, v21
	v_cvt_pk_bf16_f32 v19, v24, v25
	v_cvt_pk_bf16_f32 v20, v20, v23
	v_cvt_pk_bf16_f32 v21, v22, v26
	flat_store_dwordx4 v[42:43], v[18:21] offset:16
	ds_read_b64 v[34:35], v156 offset:1408
	ds_read_b128 v[18:21], v155
	ds_read_b128 v[22:25], v155 offset:16
	ds_read_b128 v[26:29], v155 offset:32
	ds_read_b128 v[30:33], v155 offset:48
	s_waitcnt lgkmcnt(0)
;     __device__ __forceinline__ void prepare(const pg8::Unit& u, LAS unsigned char* lds, int par, int tid) const {
;         if (stats == nullptr) return;
;     __device__ __forceinline__ void operator()(const f32x4 (&acc)[2][2][4][2], const pg8::Unit& u, int wr, int wc, int fr, int fq, LAS unsigned char* lds, int par) const {
;         const bool fold = F.stats != nullptr;
;         const LAS float* rsb = (const LAS float*)(lds + RS_OFF) + par * 512; const LAS float* cvb = (const LAS float*)(lds + CV_OFF) + (par * 2 + wr) * 512;
;         const int row0 = u.pm * 256 + wr * 64 + fr, c0 = u.pn * 256 + wc * 64 + 16 * fq;
; #pragma unroll
;         for (int ai = 0; ai < 2; ++ai)
; #pragma unroll
;             for (int m = 0; m < 4; ++m) {
;                 const int row = row0 + ai * 128 + m * 16, lrow = ai * 128 + wr * 64 + m * 16 + fr;
;                 float mu = 0.f, rstd = 1.f; if (fold) { mu = rsb[2 * lrow]; rstd = rsb[2 * lrow + 1]; }
; #pragma unroll
;                 for (int bj = 0; bj < 2; ++bj) {
;                     const size_t off = (size_t)row * ld + c0 + bj * 8;
;                     f32x4 v0 = acc[ai][bj][m][0], v1 = acc[ai][bj][m][1];
;                     if (fold) fold_apply(v0, v1, mu, rstd, cvb, wc * 64 + 16 * fq + bj * 8);
;                     if (MODE == 0) { v0 *= scale; v1 *= scale; }
;                     if (MODE == 1) {
; #pragma unroll
;                         for (int j = 0; j < 4; ++j) { const float a = fmaxf(v0[j], 0.f), b = fmaxf(v1[j], 0.f); v0[j] = a * a; v1[j] = b * b; }
;                     }
;                     if (MODE == 2 || MODE == 3) {
;                         const u32x4 gw = *(const u32x4*)(gate + off);
;                         v0[0] *= bf_lo(gw.x); v0[1] *= bf_hi(gw.x); v0[2] *= bf_lo(gw.y); v0[3] *= bf_hi(gw.y);
;                         v1[0] *= bf_lo(gw.z); v1[1] *= bf_hi(gw.z); v1[2] *= bf_lo(gw.w); v1[3] *= bf_hi(gw.w);
;                     }
;                     if (MODE == 3) {
;                         const u32x4 pw = *(const u32x4*)(o + off);
;                         v0[0] += bf_lo(pw.x); v0[1] += bf_hi(pw.x); v0[2] += bf_lo(pw.y); v0[3] += bf_hi(pw.y);
;                         v1[0] += bf_lo(pw.z); v1[1] += bf_hi(pw.z); v1[2] += bf_lo(pw.w); v1[3] += bf_hi(pw.w);
;                     }
;                     *(u32x4*)(o + off) = pack8(v0, v1);
;                 }
	v_mov_b32_e32 v36, v35
	v_mov_b32_e32 v37, v12
	v_pk_mul_f32 v[36:37], v[36:37], v[34:35]
	v_mov_b32_e32 v38, v14
	v_mov_b32_e32 v39, v36
	v_pk_mov_b32 v[40:41], v[34:35], v[18:19] op_sel:[1,0]
	v_pk_mov_b32 v[14:15], v[14:15], v[36:37] op_sel:[1,0]
	v_pk_mul_f32 v[38:39], v[38:39], v[40:41]
	s_nop 0
	v_sub_f32_e32 v18, v38, v39
	v_add_f32_e32 v38, v19, v18
	v_pk_mov_b32 v[18:19], v[34:35], v[20:21] op_sel:[1,0]
	s_nop 0
	v_pk_mul_f32 v[14:15], v[14:15], v[18:19]
	v_pk_mov_b32 v[18:19], v[34:35], v[22:23] op_sel:[1,0]
	v_sub_f32_e32 v14, v14, v15
	v_add_f32_e32 v20, v21, v14
	v_mov_b32_e32 v14, v16
	v_mov_b32_e32 v15, v36
	v_pk_mul_f32 v[14:15], v[14:15], v[18:19]
	s_nop 0
	v_sub_f32_e32 v14, v14, v15
	v_add_f32_e32 v18, v23, v14
	v_pk_mov_b32 v[14:15], v[16:17], v[36:37] op_sel:[1,0]
	v_pk_mov_b32 v[16:17], v[34:35], v[24:25] op_sel:[1,0]
	s_nop 0
	v_pk_mul_f32 v[14:15], v[14:15], v[16:17]
	v_pk_mov_b32 v[16:17], v[34:35], v[26:27] op_sel:[1,0]
	v_sub_f32_e32 v14, v14, v15
	v_add_f32_e32 v19, v25, v14
	v_mov_b32_e32 v14, v10
	v_mov_b32_e32 v15, v36
	v_pk_mul_f32 v[14:15], v[14:15], v[16:17]
	v_pk_mov_b32 v[10:11], v[10:11], v[36:37] op_sel:[1,0]
	v_sub_f32_e32 v14, v14, v15
	v_add_f32_e32 v16, v27, v14
	v_pk_mov_b32 v[14:15], v[34:35], v[28:29] op_sel:[1,0]
	v_max_f32_e32 v17, 0, v19
	v_pk_mul_f32 v[10:11], v[10:11], v[14:15]
	v_mul_f32_e32 v17, v17, v17
	v_sub_f32_e32 v10, v10, v11
	v_add_f32_e32 v14, v29, v10
	v_fma_f32 v10, -v36, v30, v37
	v_add_f32_e32 v15, v31, v10
	v_pk_mov_b32 v[10:11], v[12:13], v[36:37] op_sel:[1,0]
	v_pk_mov_b32 v[12:13], v[34:35], v[32:33] op_sel:[1,0]
	v_max_f32_e32 v14, 0, v14
	v_pk_mul_f32 v[10:11], v[10:11], v[12:13]
	v_max_f32_e32 v12, 0, v16
	v_sub_f32_e32 v10, v10, v11
	v_add_f32_e32 v10, v33, v10
	v_max_f32_e32 v11, 0, v38
	v_mul_f32_e32 v11, v11, v11
	v_mul_f32_e32 v12, v12, v12
	v_max_f32_e32 v13, 0, v20
	v_mul_f32_e32 v14, v14, v14
	v_max_f32_e32 v16, 0, v18
	v_max_f32_e32 v15, 0, v15
	v_max_f32_e32 v10, 0, v10
	v_mul_f32_e32 v13, v13, v13
	v_mul_f32_e32 v16, v16, v16
	v_mul_f32_e32 v15, v15, v15
	v_mul_f32_e32 v18, v10, v10
	v_cvt_pk_bf16_f32 v10, v11, v13
	v_cvt_pk_bf16_f32 v11, v16, v17
	v_cvt_pk_bf16_f32 v12, v12, v14
	v_add_co_u32_e32 v14, vcc, s15, v122
	v_cvt_pk_bf16_f32 v13, v15, v18
	v_mov_b32_e32 v28, v6
	s_nop 0
	v_addc_co_u32_e32 v15, vcc, 0, v123, vcc
	flat_store_dwordx4 v[14:15], v[10:13]
	ds_read_b128 v[10:13], v155 offset:64
	ds_read_b128 v[14:17], v155 offset:80
	ds_read_b128 v[18:21], v155 offset:96
	ds_read_b128 v[22:25], v155 offset:112
	v_mov_b32_e32 v29, v36
	s_waitcnt lgkmcnt(0)
	v_pk_mov_b32 v[30:31], v[34:35], v[10:11] op_sel:[1,0]
	v_pk_mov_b32 v[6:7], v[6:7], v[36:37] op_sel:[1,0]
	v_pk_mul_f32 v[28:29], v[28:29], v[30:31]
	v_lshl_add_u64 v[26:27], v[122:123], 0, s[26:27]
	v_sub_f32_e32 v10, v28, v29
	v_add_f32_e32 v28, v11, v10
	v_pk_mov_b32 v[10:11], v[34:35], v[12:13] op_sel:[1,0]
	s_andn2_b64 vcc, exec, s[22:23]
	v_pk_mul_f32 v[6:7], v[6:7], v[10:11]
	v_pk_mov_b32 v[10:11], v[34:35], v[14:15] op_sel:[1,0]
	v_sub_f32_e32 v6, v6, v7
	v_add_f32_e32 v12, v13, v6
	v_mov_b32_e32 v6, v8
	v_mov_b32_e32 v7, v36
	v_pk_mul_f32 v[6:7], v[6:7], v[10:11]
	s_mov_b64 s[22:23], -1
	v_sub_f32_e32 v6, v6, v7
	v_add_f32_e32 v10, v15, v6
	v_pk_mov_b32 v[6:7], v[8:9], v[36:37] op_sel:[1,0]
	v_pk_mov_b32 v[8:9], v[34:35], v[16:17] op_sel:[1,0]
	s_nop 0
	v_pk_mul_f32 v[6:7], v[6:7], v[8:9]
	v_pk_mov_b32 v[8:9], v[34:35], v[18:19] op_sel:[1,0]
	v_sub_f32_e32 v6, v6, v7
	v_add_f32_e32 v11, v17, v6
	v_mov_b32_e32 v6, v2
	v_mov_b32_e32 v7, v36
	v_pk_mul_f32 v[6:7], v[6:7], v[8:9]
	v_pk_mov_b32 v[2:3], v[2:3], v[36:37] op_sel:[1,0]
	v_sub_f32_e32 v6, v6, v7
	v_add_f32_e32 v8, v19, v6
	v_pk_mov_b32 v[6:7], v[34:35], v[20:21] op_sel:[1,0]
	s_nop 0
	v_pk_mul_f32 v[2:3], v[2:3], v[6:7]
	v_pk_mov_b32 v[6:7], v[34:35], v[22:23] op_sel:[1,0]
	v_sub_f32_e32 v2, v2, v3
	v_add_f32_e32 v9, v21, v2
	v_mov_b32_e32 v2, v4
	v_mov_b32_e32 v3, v36
	v_pk_mul_f32 v[2:3], v[2:3], v[6:7]
	v_max_f32_e32 v7, 0, v9
	v_sub_f32_e32 v2, v2, v3
	v_add_f32_e32 v6, v23, v2
	v_pk_mov_b32 v[2:3], v[4:5], v[36:37] op_sel:[1,0]
	v_pk_mov_b32 v[4:5], v[34:35], v[24:25] op_sel:[1,0]
	v_max_f32_e32 v6, 0, v6
	v_pk_mul_f32 v[2:3], v[2:3], v[4:5]
	v_max_f32_e32 v4, 0, v8
	v_sub_f32_e32 v2, v2, v3
	v_add_f32_e32 v2, v25, v2
	v_max_f32_e32 v3, 0, v28
	v_max_f32_e32 v5, 0, v12
	v_mul_f32_e32 v3, v3, v3
	v_mul_f32_e32 v4, v4, v4
	v_mul_f32_e32 v5, v5, v5
	v_max_f32_e32 v8, 0, v10
	v_max_f32_e32 v9, 0, v11
	v_max_f32_e32 v2, 0, v2
	v_mul_f32_e32 v7, v7, v7
	v_mul_f32_e32 v8, v8, v8
	v_mul_f32_e32 v6, v6, v6
	v_mul_f32_e32 v9, v9, v9
	v_mul_f32_e32 v10, v2, v2
	v_cvt_pk_bf16_f32 v2, v3, v5
	v_cvt_pk_bf16_f32 v3, v8, v9
	v_cvt_pk_bf16_f32 v4, v4, v7
	v_cvt_pk_bf16_f32 v5, v6, v10
	flat_store_dwordx4 v[26:27], v[2:5] offset:16
	s_cbranch_vccnz .LBB0_164
	s_nop 0
	v_lshl_add_u32 v2, s16, 8, v144
	v_ashrrev_i32_e32 v3, 31, v2
	v_lshlrev_b64 v[2:3], 8, v[2:3]
	v_lshl_add_u64 v[6:7], v[136:137], 0, v[2:3]
	global_load_dwordx4 v[2:5], v[6:7], off
	global_load_dwordx4 v[222:225], v[6:7], off offset:16
	global_load_dwordx4 v[226:229], v[6:7], off offset:32
	global_load_dwordx4 v[230:233], v[6:7], off offset:48
	global_load_dwordx4 v[234:237], v[6:7], off offset:64
	global_load_dwordx4 v[238:241], v[6:7], off offset:80
	global_load_dwordx4 v[242:245], v[6:7], off offset:96
	global_load_dwordx4 v[246:249], v[6:7], off offset:112
	s_and_b32 s15, s39, 1
	s_waitcnt vmcnt(0) lgkmcnt(0)
	v_add_f32_e32 v2, v2, v4
	v_add_f32_e32 v8, 0, v2
	v_add_f32_e32 v2, v3, v5
	v_add_f32_e32 v9, 0, v2
	v_add_f32_e32 v2, v222, v224
	v_add_f32_e32 v8, v8, v2
	v_add_f32_e32 v2, v223, v225
	v_add_f32_e32 v9, v9, v2
	v_add_f32_e32 v2, v226, v228
	v_add_f32_e32 v8, v8, v2
	v_add_f32_e32 v2, v227, v229
	v_add_f32_e32 v9, v9, v2
	v_add_f32_e32 v2, v230, v232
	v_add_f32_e32 v8, v8, v2
	v_add_f32_e32 v2, v231, v233
	v_add_f32_e32 v9, v9, v2
	v_add_f32_e32 v2, v234, v236
	v_add_f32_e32 v8, v8, v2
	v_add_f32_e32 v2, v235, v237
	v_add_f32_e32 v9, v9, v2
	v_add_f32_e32 v2, v238, v240
	v_add_f32_e32 v8, v8, v2
	v_add_f32_e32 v2, v239, v241
	v_add_f32_e32 v9, v9, v2
	v_add_f32_e32 v2, v242, v244
	v_add_f32_e32 v8, v8, v2
	v_add_f32_e32 v2, v243, v245
	v_add_f32_e32 v9, v9, v2
	v_add_f32_e32 v2, v246, v248
	v_add_f32_e32 v3, v247, v249
	v_add_f32_e32 v2, v8, v2
	v_add_f32_e32 v3, v9, v3
	ds_bpermute_b32 v4, v145, v2
	ds_bpermute_b32 v5, v145, v3
	s_and_saveexec_b64 s[22:23], s[0:1]
	s_cbranch_execz .LBB0_179
	s_waitcnt lgkmcnt(1)
	v_add_f32_e32 v2, v2, v4
	v_mul_f32_e32 v2, 0x3a000000, v2
	s_waitcnt lgkmcnt(0)
	v_add_f32_e32 v3, v3, v5
	v_mul_f32_e32 v4, v2, v2
	v_fma_f32 v3, v3, s61, -v4
	v_add_f32_e32 v3, 0x3727c5ac, v3
	v_rsq_f32_e32 v3, v3
	v_lshl_add_u32 v4, s15, 11, v151
	ds_write_b64 v4, v[2:3]

; #define LAS __attribute__((address_space(3)))
; __device__ __forceinline__ float shflx(float v, int k, int lane) { return __int_as_float(__builtin_amdgcn_ds_bpermute((lane ^ k) << 2, __float_as_int(v))); }
;     __device__ __forceinline__ void prepare(const pg8::Unit& u, LAS unsigned char* lds, int par, int tid) const { F.prepare(u, lds, par, tid); }
;     __device__ __forceinline__ void prepare(const pg8::Unit& u, LAS unsigned char* lds, int par, int tid) const { F.prepare(u, lds, par, tid); }
;     __device__ __forceinline__ void prepare(const pg8::Unit& u, LAS unsigned char* lds, int par, int tid) const { F.prepare(u, lds, par, tid); }
;     __device__ __forceinline__ void prepare(const pg8::Unit& u, LAS unsigned char* lds, int par, int tid) const {
;         if (stats == nullptr) return;
;         const int h = tid >> 8, tt = tid & 255, rl = tt >> 1, part = tt & 1, lrow = (rl >> 6) * 128 + h * 64 + (rl & 63);
;         const float* sp = stats + ((size_t)(u.pm * 256 + lrow) * 32 + part * 16) * 2;
;         float s1 = 0.f, s2 = 0.f;
; #pragma unroll
;         for (int i = 0; i < 8; ++i) { const f32x4 v = *(const f32x4*)(sp + 4 * i); s1 += v[0] + v[2]; s2 += v[1] + v[3]; }
;         s1 += shflx(s1, 1, tid & 63); s2 += shflx(s2, 1, tid & 63);
;         const float mu = s1 * (1.f / D), var = s2 * (1.f / D) - mu * mu, rstd = __builtin_amdgcn_rsqf(var + LN_EPS);
;         if (part == 0) { LAS float* rs = (LAS float*)(lds + RS_OFF) + (par * 256 + lrow) * 2; rs[0] = mu; rs[1] = rstd; }
.LBB0_190:
	s_load_dwordx4 s[4:7], s[12:13], 0x60
	s_and_b64 vcc, exec, s[0:1]
	s_cbranch_vccnz .LBB0_231
	s_waitcnt vmcnt(0)
	v_ashrrev_i32_e32 v3, 2, v210
	v_and_b32_e32 v2, 0x80, v210
	v_and_b32_e32 v3, 0xffffffc0, v3
	v_lshrrev_b32_e32 v0, 1, v210
	v_add_u32_e32 v2, v3, v2
	v_and_or_b32 v190, v0, 63, v2
	v_lshl_add_u32 v2, s26, 8, v190
	v_ashrrev_i32_e32 v3, 31, v2
	v_and_b32_e32 v10, 1, v210
	v_lshlrev_b64 v[2:3], 8, v[2:3]
	v_lshl_add_u64 v[2:3], s[10:11], 0, v[2:3]
	v_lshlrev_b32_e32 v0, 7, v10
	v_lshl_add_u64 v[6:7], v[2:3], 0, v[0:1]
	s_waitcnt lgkmcnt(0)
	global_load_dwordx4 v[2:5], v[6:7], off
	global_load_dwordx4 v[222:225], v[6:7], off offset:16
	global_load_dwordx4 v[226:229], v[6:7], off offset:32
	global_load_dwordx4 v[230:233], v[6:7], off offset:48
	global_load_dwordx4 v[234:237], v[6:7], off offset:64
	global_load_dwordx4 v[238:241], v[6:7], off offset:80
	global_load_dwordx4 v[242:245], v[6:7], off offset:96
	global_load_dwordx4 v[246:249], v[6:7], off offset:112
	v_lshlrev_b32_e32 v11, 2, v210
	v_bitop3_b32 v191, v11, 4, v205 bitop3:0x6c
	v_cmp_eq_u32_e64 s[40:41], 0, v10
	s_waitcnt vmcnt(0) lgkmcnt(0)
	v_add_f32_e32 v0, v2, v4
	v_add_f32_e32 v2, v3, v5
	v_add_f32_e32 v8, 0, v2
	v_add_f32_e32 v0, 0, v0
	v_add_f32_e32 v2, v222, v224
	v_add_f32_e32 v0, v0, v2
	v_add_f32_e32 v2, v223, v225
	v_add_f32_e32 v8, v8, v2
	v_add_f32_e32 v2, v226, v228
	v_add_f32_e32 v0, v0, v2
	v_add_f32_e32 v2, v227, v229
	v_add_f32_e32 v8, v8, v2
	v_add_f32_e32 v2, v230, v232
	v_add_f32_e32 v0, v0, v2
	v_add_f32_e32 v2, v231, v233
	v_add_f32_e32 v8, v8, v2
	v_add_f32_e32 v2, v234, v236
	v_add_f32_e32 v0, v0, v2
	v_add_f32_e32 v2, v235, v237
	v_add_f32_e32 v8, v8, v2
	v_add_f32_e32 v2, v238, v240
	v_add_f32_e32 v0, v0, v2
	v_add_f32_e32 v2, v239, v241
	v_add_f32_e32 v8, v8, v2
	v_add_f32_e32 v2, v242, v244
	v_add_f32_e32 v0, v0, v2
	v_add_f32_e32 v2, v243, v245
	v_add_f32_e32 v8, v8, v2
	v_add_f32_e32 v2, v246, v248
	v_add_f32_e32 v0, v0, v2
	v_add_f32_e32 v2, v247, v249
	v_add_f32_e32 v2, v8, v2
	ds_bpermute_b32 v3, v191, v0
	ds_bpermute_b32 v4, v191, v2
	s_and_saveexec_b64 s[0:1], s[40:41]
	s_cbranch_execz .LBB0_193
	s_waitcnt lgkmcnt(1)
	v_add_f32_e32 v0, v0, v3
	s_waitcnt lgkmcnt(0)
	v_add_f32_e32 v4, v2, v4
	v_mul_f32_e32 v2, 0x3a000000, v0
	v_mul_f32_e32 v0, v2, v2
	v_fma_f32 v0, v4, s61, -v0
	v_add_f32_e32 v0, 0x3727c5ac, v0
	v_rsq_f32_e32 v3, v0
	v_lshl_add_u32 v0, v190, 3, 0
	v_add_u32_e32 v0, 0x20000, v0
	ds_write_b64 v0, v[2:3]

; #define LAS __attribute__((address_space(3)))
; __device__ __forceinline__ float shflx(float v, int k, int lane) { return __int_as_float(__builtin_amdgcn_ds_bpermute((lane ^ k) << 2, __float_as_int(v))); }
;     __device__ __forceinline__ void prepare(const pg8::Unit& u, LAS unsigned char* lds, int par, int tid) const { F.prepare(u, lds, par, tid); }
;     __device__ __forceinline__ void prepare(const pg8::Unit& u, LAS unsigned char* lds, int par, int tid) const { F.prepare(u, lds, par, tid); }
;     __device__ __forceinline__ void prepare(const pg8::Unit& u, LAS unsigned char* lds, int par, int tid) const { F.prepare(u, lds, par, tid); }
;     __device__ bool next(int i, Unit& u) const {
;         const int nr = (nwg + G - 1) / G; if (i >= nr) return false;
;         const long L = (long)(rev ? nr - 1 - i : i) * G + c; if (L >= nwg) return false;
;         int wgid = (int)L; { const int q = nwg / NXCD, r = nwg % NXCD, xcd = wgid % NXCD, off = wgid / NXCD; wgid = (xcd < r ? xcd * (q + 1) : r * (q + 1) + (xcd - r) * q) + off; }
;         const int nig = WGM * nN, gid = wgid / nig, fm = gid * WGM, gsz = (nM - fm) < WGM ? (nM - fm) : WGM;
;         u.pm = fm + ((wgid % nig) % gsz); u.pn = (wgid % nig) / gsz; return true;
;     __device__ __forceinline__ void prepare(const pg8::Unit& u, LAS unsigned char* lds, int par, int tid) const {
;         if (stats == nullptr) return;
;         const int h = tid >> 8, tt = tid & 255, rl = tt >> 1, part = tt & 1, lrow = (rl >> 6) * 128 + h * 64 + (rl & 63);
;         const float* sp = stats + ((size_t)(u.pm * 256 + lrow) * 32 + part * 16) * 2;
;         float s1 = 0.f, s2 = 0.f;
; #pragma unroll
;         for (int i = 0; i < 8; ++i) { const f32x4 v = *(const f32x4*)(sp + 4 * i); s1 += v[0] + v[2]; s2 += v[1] + v[3]; }
;         s1 += shflx(s1, 1, tid & 63); s2 += shflx(s2, 1, tid & 63);
;         const float mu = s1 * (1.f / D), var = s2 * (1.f / D) - mu * mu, rstd = __builtin_amdgcn_rsqf(var + LN_EPS);
;         if (part == 0) { LAS float* rs = (LAS float*)(lds + RS_OFF) + (par * 256 + lrow) * 2; rs[0] = mu; rs[1] = rstd; }
.LBB0_246:
	s_ashr_i32 s0, s2, 3
	s_add_i32 s0, s7, s0
	s_ashr_i32 s1, s0, 31
	s_lshr_b32 s1, s1, 29
	s_add_i32 s1, s0, s1
	s_ashr_i32 s2, s1, 3
	s_and_b32 s1, s1, 0xfff8
	s_sub_i32 s0, s0, s1
	s_bfe_i32 s1, s0, 0x80000
	s_bfe_u32 s1, s1, 0x2000d
	s_lshl_b32 s6, s2, 2
	s_add_i32 s2, s0, s1
	s_and_b32 s1, s2, 0xfc
	s_waitcnt vmcnt(0)
	v_ashrrev_i32_e32 v3, 2, v210
	s_sub_i32 s0, s0, s1
	v_and_b32_e32 v2, 0x80, v210
	v_and_b32_e32 v3, 0xffffffc0, v3
	s_sext_i32_i8 s0, s0
	v_lshrrev_b32_e32 v0, 1, v210
	v_add_u32_e32 v2, v3, v2
	s_add_i32 s26, s6, s0
	v_and_or_b32 v144, v0, 63, v2
	v_lshl_add_u32 v2, s26, 8, v144
	v_ashrrev_i32_e32 v3, 31, v2
	v_and_b32_e32 v10, 1, v210
	v_lshlrev_b64 v[2:3], 8, v[2:3]
	v_lshl_add_u64 v[2:3], s[10:11], 0, v[2:3]
	v_lshlrev_b32_e32 v0, 7, v10
	v_lshl_add_u64 v[6:7], v[2:3], 0, v[0:1]
	global_load_dwordx4 v[2:5], v[6:7], off
	global_load_dwordx4 v[222:225], v[6:7], off offset:16
	global_load_dwordx4 v[226:229], v[6:7], off offset:32
	global_load_dwordx4 v[230:233], v[6:7], off offset:48
	global_load_dwordx4 v[234:237], v[6:7], off offset:64
	global_load_dwordx4 v[238:241], v[6:7], off offset:80
	global_load_dwordx4 v[242:245], v[6:7], off offset:96
	global_load_dwordx4 v[246:249], v[6:7], off offset:112
	v_lshlrev_b32_e32 v11, 2, v210
	v_bitop3_b32 v145, v11, 4, v205 bitop3:0x6c
	v_cmp_eq_u32_e64 s[0:1], 0, v10
	s_waitcnt vmcnt(0) lgkmcnt(0)
	v_add_f32_e32 v0, v2, v4
	v_add_f32_e32 v2, v3, v5
	v_add_f32_e32 v8, 0, v2
	v_add_f32_e32 v0, 0, v0
	v_add_f32_e32 v2, v222, v224
	v_add_f32_e32 v0, v0, v2
	v_add_f32_e32 v2, v223, v225
	v_add_f32_e32 v8, v8, v2
	v_add_f32_e32 v2, v226, v228
	v_add_f32_e32 v0, v0, v2
	v_add_f32_e32 v2, v227, v229
	v_add_f32_e32 v8, v8, v2
	v_add_f32_e32 v2, v230, v232
	v_add_f32_e32 v0, v0, v2
	v_add_f32_e32 v2, v231, v233
	v_add_f32_e32 v8, v8, v2
	v_add_f32_e32 v2, v234, v236
	v_add_f32_e32 v0, v0, v2
	v_add_f32_e32 v2, v235, v237
	v_add_f32_e32 v8, v8, v2
	v_add_f32_e32 v2, v238, v240
	v_add_f32_e32 v0, v0, v2
	v_add_f32_e32 v2, v239, v241
	v_add_f32_e32 v8, v8, v2
	v_add_f32_e32 v2, v242, v244
	v_add_f32_e32 v0, v0, v2
	v_add_f32_e32 v2, v243, v245
	v_add_f32_e32 v8, v8, v2
	v_add_f32_e32 v2, v246, v248
	v_add_f32_e32 v0, v0, v2
	v_add_f32_e32 v2, v247, v249
	v_add_f32_e32 v2, v8, v2
	ds_bpermute_b32 v3, v145, v0
	ds_bpermute_b32 v4, v145, v2
	s_and_saveexec_b64 s[6:7], s[0:1]
	s_cbranch_execz .LBB0_248
	s_waitcnt lgkmcnt(1)
	v_add_f32_e32 v0, v0, v3
	s_waitcnt lgkmcnt(0)
	v_add_f32_e32 v4, v2, v4
	v_mul_f32_e32 v2, 0x3a000000, v0
	v_mul_f32_e32 v0, v2, v2
	v_fma_f32 v0, v4, s61, -v0
	v_add_f32_e32 v0, 0x3727c5ac, v0
	v_rsq_f32_e32 v3, v0
	v_lshl_add_u32 v0, v144, 3, 0
	v_add_u32_e32 v0, 0x20000, v0
	ds_write_b64 v0, v[2:3]

; #define LAS __attribute__((address_space(3)))
; __device__ __forceinline__ float bf_lo(unsigned w) { return __uint_as_float(w << 16); }
;     __device__ __forceinline__ void operator()(const f32x4 (&acc)[2][2][4][2], const pg8::Unit& u, int wr, int wc, int fr, int fq, LAS unsigned char* lds, int par) const {
;         const bool fold = F.stats != nullptr;
;         const LAS float* rsb = (const LAS float*)(lds + RS_OFF) + par * 512; const LAS float* cvb = (const LAS float*)(lds + CV_OFF) + (par * 2 + wr) * 512;
;         const int row0 = u.pm * 256 + wr * 64 + fr, c0 = u.pn * 256 + wc * 64 + 16 * fq;
; #pragma unroll
;         for (int ai = 0; ai < 2; ++ai)
; #pragma unroll
;             for (int m = 0; m < 4; ++m) {
;                 const int row = row0 + ai * 128 + m * 16, lrow = ai * 128 + wr * 64 + m * 16 + fr;
;                 float mu = 0.f, rstd = 1.f; if (fold) { mu = rsb[2 * lrow]; rstd = rsb[2 * lrow + 1]; }
; #pragma unroll
;                 for (int bj = 0; bj < 2; ++bj) {
;                     const size_t off = (size_t)row * ld + c0 + bj * 8;
;                     f32x4 v0 = acc[ai][bj][m][0], v1 = acc[ai][bj][m][1];
;                     if (fold) fold_apply(v0, v1, mu, rstd, cvb, wc * 64 + 16 * fq + bj * 8);
;                     if (MODE == 0) { v0 *= scale; v1 *= scale; }
;                     if (MODE == 1) {
; #pragma unroll
;                         for (int j = 0; j < 4; ++j) { const float a = fmaxf(v0[j], 0.f), b = fmaxf(v1[j], 0.f); v0[j] = a * a; v1[j] = b * b; }
;                     }
;                     if (MODE == 2 || MODE == 3) {
;                         const u32x4 gw = *(const u32x4*)(gate + off);
;                         v0[0] *= bf_lo(gw.x); v0[1] *= bf_hi(gw.x); v0[2] *= bf_lo(gw.y); v0[3] *= bf_hi(gw.y);
;                         v1[0] *= bf_lo(gw.z); v1[1] *= bf_hi(gw.z); v1[2] *= bf_lo(gw.w); v1[3] *= bf_hi(gw.w);
;                     }
;                     if (MODE == 3) {
;                         const u32x4 pw = *(const u32x4*)(o + off);
;                         v0[0] += bf_lo(pw.x); v0[1] += bf_hi(pw.x); v0[2] += bf_lo(pw.y); v0[3] += bf_hi(pw.y);
;                         v1[0] += bf_lo(pw.z); v1[1] += bf_hi(pw.z); v1[2] += bf_lo(pw.w); v1[3] += bf_hi(pw.w);
;                     }
;                     *(u32x4*)(o + off) = pack8(v0, v1);
;                 }
.LBB0_264:
	s_and_b32 s17, s43, 1
	v_lshl_add_u32 v156, s17, 11, v152
	v_lshl_add_u32 v155, s17, 12, v153
	ds_read_b64 v[174:175], v156
	ds_read_b128 v[158:161], v155
	ds_read_b128 v[162:165], v155 offset:16
	ds_read_b128 v[166:169], v155 offset:32
	ds_read_b128 v[178:181], v155 offset:48
	v_lshl_add_u32 v142, s26, 8, v148
	v_lshl_or_b32 v172, s42, 8, v150
	s_waitcnt lgkmcnt(0)
	v_pk_mul_f32 v[176:177], v[174:175], v[174:175] op_sel:[0,1] op_sel_hi:[1,0]
	v_mov_b32_e32 v182, v158
	v_mov_b32_e32 v183, v160
	v_pk_mul_f32 v[182:183], v[176:177], v[182:183] op_sel_hi:[0,1]
	v_pk_fma_f32 v[126:127], v[126:127], v[174:175], v[182:183] op_sel:[0,1,0] neg_lo:[0,0,1] neg_hi:[0,0,1]
	v_mov_b32_e32 v160, v159
	v_mul_f32_e32 v128, v128, v175
	v_pk_add_f32 v[126:127], v[160:161], v[126:127]
	v_pk_mov_b32 v[160:161], v[128:129], v[164:165] op_sel:[1,0]
	v_pk_mov_b32 v[182:183], v[174:175], v[176:177] op_sel:[1,0]
	v_mul_f32_e32 v158, v176, v162
	v_pk_mul_f32 v[160:161], v[160:161], v[182:183]
	v_mul_f32_e32 v124, v124, v175
	v_mov_b32_e32 v129, v160
	v_mov_b32_e32 v159, v161
	v_pk_add_f32 v[128:129], v[128:129], v[158:159] neg_lo:[0,1] neg_hi:[0,1]
	v_mov_b32_e32 v158, v166
	v_mov_b32_e32 v159, v168
	v_pk_mov_b32 v[160:161], v[124:125], v[180:181] op_sel:[1,0]
	v_pk_mul_f32 v[158:159], v[176:177], v[158:159] op_sel_hi:[0,1]
	v_pk_mul_f32 v[160:161], v[160:161], v[182:183]
	v_mov_b32_e32 v164, v163
	v_pk_fma_f32 v[122:123], v[122:123], v[174:175], v[158:159] op_sel:[0,1,0] neg_lo:[0,0,1] neg_hi:[0,0,1]
	v_mov_b32_e32 v168, v167
	v_mul_f32_e32 v158, v176, v178
	v_mov_b32_e32 v125, v160
	v_mov_b32_e32 v159, v161
	v_pk_add_f32 v[128:129], v[164:165], v[128:129]
	v_pk_add_f32 v[122:123], v[168:169], v[122:123]
	v_pk_add_f32 v[124:125], v[124:125], v[158:159] neg_lo:[0,1] neg_hi:[0,1]
	v_mov_b32_e32 v180, v179
	v_ashrrev_i32_e32 v143, 31, v142
	v_pk_add_f32 v[124:125], v[180:181], v[124:125]
	v_pk_mul_f32 v[128:129], v[128:129], s[74:75] op_sel_hi:[1,0]
	v_pk_mul_f32 v[126:127], v[126:127], s[74:75] op_sel_hi:[1,0]
	v_pk_mul_f32 v[122:123], v[122:123], s[74:75] op_sel_hi:[1,0]
	v_readlane_b32 s28, v251, 45
	v_ashrrev_i32_e32 v173, 31, v172
	v_pk_mul_f32 v[124:125], v[124:125], s[74:75] op_sel_hi:[1,0]
	v_cvt_pk_bf16_f32 v126, v126, v127
	v_cvt_pk_bf16_f32 v127, v128, v129
	v_cvt_pk_bf16_f32 v128, v122, v123
	v_lshlrev_b64 v[122:123], 10, v[142:143]
	v_readlane_b32 s29, v251, 46
	v_cvt_pk_bf16_f32 v129, v124, v125
	v_lshlrev_b64 v[124:125], 1, v[172:173]
	v_mul_f32_e32 v120, v120, v175
	v_lshl_add_u64 v[122:123], s[28:29], 0, v[122:123]
	v_lshl_add_u64 v[122:123], v[122:123], 0, v[124:125]
	flat_store_dwordx4 v[122:123], v[126:129]
	ds_read_b128 v[126:129], v155 offset:64
	ds_read_b128 v[158:161], v155 offset:80
	ds_read_b128 v[162:165], v155 offset:96
	ds_read_b128 v[166:169], v155 offset:112
	v_mul_f32_e32 v116, v116, v175
	s_waitcnt lgkmcnt(0)
	v_mov_b32_e32 v172, v126
	v_mov_b32_e32 v173, v128
	v_pk_mul_f32 v[172:173], v[176:177], v[172:173] op_sel_hi:[0,1]
	v_pk_fma_f32 v[118:119], v[118:119], v[174:175], v[172:173] op_sel:[0,1,0] neg_lo:[0,0,1] neg_hi:[0,0,1]
	v_mov_b32_e32 v128, v127
	v_pk_add_f32 v[118:119], v[128:129], v[118:119]
	v_pk_mov_b32 v[128:129], v[120:121], v[160:161] op_sel:[1,0]
	v_mul_f32_e32 v126, v176, v158
	v_pk_mul_f32 v[128:129], v[128:129], v[182:183]
	v_mov_b32_e32 v160, v159
	v_mov_b32_e32 v121, v128
	v_mov_b32_e32 v127, v129
	v_pk_add_f32 v[120:121], v[120:121], v[126:127] neg_lo:[0,1] neg_hi:[0,1]
	v_mov_b32_e32 v126, v162
	v_mov_b32_e32 v127, v164
	v_pk_mov_b32 v[128:129], v[116:117], v[168:169] op_sel:[1,0]
	v_pk_mul_f32 v[126:127], v[176:177], v[126:127] op_sel_hi:[0,1]
	v_pk_mul_f32 v[128:129], v[128:129], v[182:183]
	v_pk_fma_f32 v[114:115], v[114:115], v[174:175], v[126:127] op_sel:[0,1,0] neg_lo:[0,0,1] neg_hi:[0,0,1]
	v_mul_f32_e32 v126, v176, v166
	v_mov_b32_e32 v117, v128
	v_mov_b32_e32 v127, v129
	v_mov_b32_e32 v164, v163
	v_pk_add_f32 v[116:117], v[116:117], v[126:127] neg_lo:[0,1] neg_hi:[0,1]
	v_mov_b32_e32 v168, v167
	v_pk_add_f32 v[114:115], v[164:165], v[114:115]
	v_pk_add_f32 v[116:117], v[168:169], v[116:117]
	v_pk_add_f32 v[120:121], v[160:161], v[120:121]
	v_pk_mul_f32 v[126:127], v[116:117], s[74:75] op_sel_hi:[1,0]
	v_pk_mul_f32 v[116:117], v[114:115], s[74:75] op_sel_hi:[1,0]
	v_pk_mul_f32 v[120:121], v[120:121], s[74:75] op_sel_hi:[1,0]
	v_pk_mul_f32 v[118:119], v[118:119], s[74:75] op_sel_hi:[1,0]
	v_or_b32_e32 v164, 16, v142
	v_cvt_pk_bf16_f32 v114, v118, v119
	v_cvt_pk_bf16_f32 v115, v120, v121
	v_cvt_pk_bf16_f32 v116, v116, v117
	v_cvt_pk_bf16_f32 v117, v126, v127
	flat_store_dwordx4 v[122:123], v[114:117] offset:16
	ds_read_b64 v[162:163], v156 offset:128
	ds_read_b128 v[114:117], v155
	ds_read_b128 v[118:121], v155 offset:16
	ds_read_b128 v[126:129], v155 offset:32
	ds_read_b128 v[158:161], v155 offset:48
	v_ashrrev_i32_e32 v165, 31, v164
	s_waitcnt lgkmcnt(0)
; #define LAS __attribute__((address_space(3)))
; __device__ __forceinline__ float bf_lo(unsigned w) { return __uint_as_float(w << 16); }
;     __device__ __forceinline__ void operator()(const f32x4 (&acc)[2][2][4][2], const pg8::Unit& u, int wr, int wc, int fr, int fq, LAS unsigned char* lds, int par) const {
;         const bool fold = F.stats != nullptr;
;         const LAS float* rsb = (const LAS float*)(lds + RS_OFF) + par * 512; const LAS float* cvb = (const LAS float*)(lds + CV_OFF) + (par * 2 + wr) * 512;
;         const int row0 = u.pm * 256 + wr * 64 + fr, c0 = u.pn * 256 + wc * 64 + 16 * fq;
; #pragma unroll
;         for (int ai = 0; ai < 2; ++ai)
; #pragma unroll
;             for (int m = 0; m < 4; ++m) {
;                 const int row = row0 + ai * 128 + m * 16, lrow = ai * 128 + wr * 64 + m * 16 + fr;
;                 float mu = 0.f, rstd = 1.f; if (fold) { mu = rsb[2 * lrow]; rstd = rsb[2 * lrow + 1]; }
; #pragma unroll
;                 for (int bj = 0; bj < 2; ++bj) {
;                     const size_t off = (size_t)row * ld + c0 + bj * 8;
;                     f32x4 v0 = acc[ai][bj][m][0], v1 = acc[ai][bj][m][1];
;                     if (fold) fold_apply(v0, v1, mu, rstd, cvb, wc * 64 + 16 * fq + bj * 8);
;                     if (MODE == 0) { v0 *= scale; v1 *= scale; }
;                     if (MODE == 1) {
; #pragma unroll
;                         for (int j = 0; j < 4; ++j) { const float a = fmaxf(v0[j], 0.f), b = fmaxf(v1[j], 0.f); v0[j] = a * a; v1[j] = b * b; }
;                     }
;                     if (MODE == 2 || MODE == 3) {
;                         const u32x4 gw = *(const u32x4*)(gate + off);
;                         v0[0] *= bf_lo(gw.x); v0[1] *= bf_hi(gw.x); v0[2] *= bf_lo(gw.y); v0[3] *= bf_hi(gw.y);
;                         v1[0] *= bf_lo(gw.z); v1[1] *= bf_hi(gw.z); v1[2] *= bf_lo(gw.w); v1[3] *= bf_hi(gw.w);
;                     }
;                     if (MODE == 3) {
;                         const u32x4 pw = *(const u32x4*)(o + off);
;                         v0[0] += bf_lo(pw.x); v0[1] += bf_hi(pw.x); v0[2] += bf_lo(pw.y); v0[3] += bf_hi(pw.y);
;                         v1[0] += bf_lo(pw.z); v1[1] += bf_hi(pw.z); v1[2] += bf_lo(pw.w); v1[3] += bf_hi(pw.w);
;                     }
;                     *(u32x4*)(o + off) = pack8(v0, v1);
;                 }
	v_pk_mul_f32 v[166:167], v[162:163], v[162:163] op_sel:[0,1] op_sel_hi:[1,0]
	v_mov_b32_e32 v168, v114
	v_mov_b32_e32 v169, v116
	v_pk_mul_f32 v[168:169], v[166:167], v[168:169] op_sel_hi:[0,1]
	v_pk_fma_f32 v[110:111], v[110:111], v[162:163], v[168:169] op_sel:[0,1,0] neg_lo:[0,0,1] neg_hi:[0,0,1]
	v_mov_b32_e32 v116, v115
	v_mul_f32_e32 v112, v112, v163
	v_pk_add_f32 v[110:111], v[116:117], v[110:111]
	v_pk_mov_b32 v[116:117], v[112:113], v[120:121] op_sel:[1,0]
	v_pk_mov_b32 v[168:169], v[162:163], v[166:167] op_sel:[1,0]
	v_mul_f32_e32 v114, v166, v118
	v_pk_mul_f32 v[116:117], v[116:117], v[168:169]
	v_mul_f32_e32 v108, v108, v163
	v_mov_b32_e32 v113, v116
	v_mov_b32_e32 v115, v117
	v_pk_add_f32 v[112:113], v[112:113], v[114:115] neg_lo:[0,1] neg_hi:[0,1]
	v_mov_b32_e32 v114, v126
	v_mov_b32_e32 v115, v128
	v_pk_mov_b32 v[116:117], v[108:109], v[160:161] op_sel:[1,0]
	v_pk_mul_f32 v[114:115], v[166:167], v[114:115] op_sel_hi:[0,1]
	v_pk_mul_f32 v[116:117], v[116:117], v[168:169]
	v_pk_fma_f32 v[106:107], v[106:107], v[162:163], v[114:115] op_sel:[0,1,0] neg_lo:[0,0,1] neg_hi:[0,0,1]
	v_mul_f32_e32 v114, v166, v158
	v_mov_b32_e32 v109, v116
	v_mov_b32_e32 v115, v117
	v_mov_b32_e32 v128, v127
	v_pk_add_f32 v[108:109], v[108:109], v[114:115] neg_lo:[0,1] neg_hi:[0,1]
	v_mov_b32_e32 v160, v159
	v_pk_add_f32 v[106:107], v[128:129], v[106:107]
	v_pk_add_f32 v[108:109], v[160:161], v[108:109]
	v_pk_mul_f32 v[110:111], v[110:111], s[74:75] op_sel_hi:[1,0]
	v_pk_mul_f32 v[114:115], v[108:109], s[74:75] op_sel_hi:[1,0]
	v_pk_mul_f32 v[108:109], v[106:107], s[74:75] op_sel_hi:[1,0]
	v_cvt_pk_bf16_f32 v106, v110, v111
	v_lshlrev_b64 v[110:111], 10, v[164:165]
	v_mov_b32_e32 v120, v119
	v_lshl_add_u64 v[110:111], s[28:29], 0, v[110:111]
	v_pk_add_f32 v[112:113], v[120:121], v[112:113]
	v_lshl_add_u64 v[126:127], v[110:111], 0, v[124:125]
	v_pk_mul_f32 v[112:113], v[112:113], s[74:75] op_sel_hi:[1,0]
	v_mul_f32_e32 v104, v104, v163
	v_cvt_pk_bf16_f32 v107, v112, v113
	v_cvt_pk_bf16_f32 v108, v108, v109
	v_cvt_pk_bf16_f32 v109, v114, v115
	flat_store_dwordx4 v[126:127], v[106:109]
	ds_read_b128 v[106:109], v155 offset:64
	ds_read_b128 v[110:113], v155 offset:80
	ds_read_b128 v[114:117], v155 offset:96
	ds_read_b128 v[118:121], v155 offset:112
	v_mul_f32_e32 v100, v100, v163
	s_waitcnt lgkmcnt(0)
	v_mov_b32_e32 v128, v106
	v_mov_b32_e32 v129, v108
	v_pk_mul_f32 v[128:129], v[166:167], v[128:129] op_sel_hi:[0,1]
	v_pk_fma_f32 v[102:103], v[102:103], v[162:163], v[128:129] op_sel:[0,1,0] neg_lo:[0,0,1] neg_hi:[0,0,1]
	v_mov_b32_e32 v108, v107
	v_pk_add_f32 v[102:103], v[108:109], v[102:103]
	v_pk_mov_b32 v[108:109], v[104:105], v[112:113] op_sel:[1,0]
	v_mul_f32_e32 v106, v166, v110
	v_pk_mul_f32 v[108:109], v[108:109], v[168:169]
	v_mov_b32_e32 v112, v111
	v_mov_b32_e32 v105, v108
	v_mov_b32_e32 v107, v109
	v_pk_add_f32 v[104:105], v[104:105], v[106:107] neg_lo:[0,1] neg_hi:[0,1]
	v_mov_b32_e32 v106, v114
	v_mov_b32_e32 v107, v116
	v_pk_mov_b32 v[108:109], v[100:101], v[120:121] op_sel:[1,0]
	v_pk_mul_f32 v[106:107], v[166:167], v[106:107] op_sel_hi:[0,1]
	v_pk_mul_f32 v[108:109], v[108:109], v[168:169]
	v_pk_fma_f32 v[98:99], v[98:99], v[162:163], v[106:107] op_sel:[0,1,0] neg_lo:[0,0,1] neg_hi:[0,0,1]
	v_mul_f32_e32 v106, v166, v118
	v_mov_b32_e32 v101, v108
	v_mov_b32_e32 v107, v109
	v_mov_b32_e32 v116, v115
	v_pk_add_f32 v[100:101], v[100:101], v[106:107] neg_lo:[0,1] neg_hi:[0,1]
	v_mov_b32_e32 v120, v119
	v_pk_add_f32 v[98:99], v[116:117], v[98:99]
	v_pk_add_f32 v[100:101], v[120:121], v[100:101]
	v_pk_add_f32 v[104:105], v[112:113], v[104:105]
	v_pk_mul_f32 v[106:107], v[100:101], s[74:75] op_sel_hi:[1,0]
	v_pk_mul_f32 v[100:101], v[98:99], s[74:75] op_sel_hi:[1,0]
	v_pk_mul_f32 v[104:105], v[104:105], s[74:75] op_sel_hi:[1,0]
	v_pk_mul_f32 v[102:103], v[102:103], s[74:75] op_sel_hi:[1,0]
	v_or_b32_e32 v116, 32, v142
	v_cvt_pk_bf16_f32 v98, v102, v103
	v_cvt_pk_bf16_f32 v99, v104, v105
	v_cvt_pk_bf16_f32 v100, v100, v101
	v_cvt_pk_bf16_f32 v101, v106, v107
	flat_store_dwordx4 v[126:127], v[98:101] offset:16
	ds_read_b64 v[114:115], v156 offset:256
	ds_read_b128 v[98:101], v155
	ds_read_b128 v[102:105], v155 offset:16
	ds_read_b128 v[106:109], v155 offset:32
	ds_read_b128 v[110:113], v155 offset:48
	v_ashrrev_i32_e32 v117, 31, v116
	s_waitcnt lgkmcnt(0)
	v_pk_mul_f32 v[118:119], v[114:115], v[114:115] op_sel:[0,1] op_sel_hi:[1,0]
	v_mov_b32_e32 v120, v98
	v_mov_b32_e32 v121, v100
	v_pk_mul_f32 v[120:121], v[118:119], v[120:121] op_sel_hi:[0,1]
	v_pk_fma_f32 v[94:95], v[94:95], v[114:115], v[120:121] op_sel:[0,1,0] neg_lo:[0,0,1] neg_hi:[0,0,1]
	v_mov_b32_e32 v100, v99
	v_mul_f32_e32 v96, v96, v115
	v_pk_add_f32 v[94:95], v[100:101], v[94:95]
	v_pk_mov_b32 v[100:101], v[96:97], v[104:105] op_sel:[1,0]
	v_pk_mov_b32 v[120:121], v[114:115], v[118:119] op_sel:[1,0]
	v_mul_f32_e32 v98, v118, v102
	v_pk_mul_f32 v[100:101], v[100:101], v[120:121]
	v_mul_f32_e32 v92, v92, v115
	v_mov_b32_e32 v97, v100
	v_mov_b32_e32 v99, v101
	v_pk_add_f32 v[96:97], v[96:97], v[98:99] neg_lo:[0,1] neg_hi:[0,1]
	v_mov_b32_e32 v98, v106
	v_mov_b32_e32 v99, v108
	v_pk_mov_b32 v[100:101], v[92:93], v[112:113] op_sel:[1,0]
	v_pk_mul_f32 v[98:99], v[118:119], v[98:99] op_sel_hi:[0,1]
	v_pk_mul_f32 v[100:101], v[100:101], v[120:121]
	v_pk_fma_f32 v[90:91], v[90:91], v[114:115], v[98:99] op_sel:[0,1,0] neg_lo:[0,0,1] neg_hi:[0,0,1]
	v_mul_f32_e32 v98, v118, v110
	v_mov_b32_e32 v93, v100
	v_mov_b32_e32 v99, v101
	v_mov_b32_e32 v108, v107
	v_pk_add_f32 v[92:93], v[92:93], v[98:99] neg_lo:[0,1] neg_hi:[0,1]
	v_mov_b32_e32 v112, v111
	v_pk_add_f32 v[90:91], v[108:109], v[90:91]
	v_pk_add_f32 v[92:93], v[112:113], v[92:93]
	v_pk_mul_f32 v[94:95], v[94:95], s[74:75] op_sel_hi:[1,0]
	v_pk_mul_f32 v[98:99], v[92:93], s[74:75] op_sel_hi:[1,0]
	v_pk_mul_f32 v[92:93], v[90:91], s[74:75] op_sel_hi:[1,0]
	v_cvt_pk_bf16_f32 v90, v94, v95
	v_lshlrev_b64 v[94:95], 10, v[116:117]
	v_mov_b32_e32 v104, v103
	v_lshl_add_u64 v[94:95], s[28:29], 0, v[94:95]
	v_pk_add_f32 v[96:97], v[104:105], v[96:97]
	v_lshl_add_u64 v[106:107], v[94:95], 0, v[124:125]
	v_pk_mul_f32 v[96:97], v[96:97], s[74:75] op_sel_hi:[1,0]
	v_mul_f32_e32 v88, v88, v115
	v_cvt_pk_bf16_f32 v91, v96, v97
	v_cvt_pk_bf16_f32 v92, v92, v93
	v_cvt_pk_bf16_f32 v93, v98, v99
	flat_store_dwordx4 v[106:107], v[90:93]
	ds_read_b128 v[90:93], v155 offset:64
	ds_read_b128 v[94:97], v155 offset:80
	ds_read_b128 v[98:101], v155 offset:96
	ds_read_b128 v[102:105], v155 offset:112
	v_mul_f32_e32 v84, v84, v115
	s_waitcnt lgkmcnt(0)
; #define LAS __attribute__((address_space(3)))
; __device__ __forceinline__ float bf_lo(unsigned w) { return __uint_as_float(w << 16); }
;     __device__ __forceinline__ void operator()(const f32x4 (&acc)[2][2][4][2], const pg8::Unit& u, int wr, int wc, int fr, int fq, LAS unsigned char* lds, int par) const {
;         const bool fold = F.stats != nullptr;
;         const LAS float* rsb = (const LAS float*)(lds + RS_OFF) + par * 512; const LAS float* cvb = (const LAS float*)(lds + CV_OFF) + (par * 2 + wr) * 512;
;         const int row0 = u.pm * 256 + wr * 64 + fr, c0 = u.pn * 256 + wc * 64 + 16 * fq;
; #pragma unroll
;         for (int ai = 0; ai < 2; ++ai)
; #pragma unroll
;             for (int m = 0; m < 4; ++m) {
;                 const int row = row0 + ai * 128 + m * 16, lrow = ai * 128 + wr * 64 + m * 16 + fr;
;                 float mu = 0.f, rstd = 1.f; if (fold) { mu = rsb[2 * lrow]; rstd = rsb[2 * lrow + 1]; }
; #pragma unroll
;                 for (int bj = 0; bj < 2; ++bj) {
;                     const size_t off = (size_t)row * ld + c0 + bj * 8;
;                     f32x4 v0 = acc[ai][bj][m][0], v1 = acc[ai][bj][m][1];
;                     if (fold) fold_apply(v0, v1, mu, rstd, cvb, wc * 64 + 16 * fq + bj * 8);
;                     if (MODE == 0) { v0 *= scale; v1 *= scale; }
;                     if (MODE == 1) {
; #pragma unroll
;                         for (int j = 0; j < 4; ++j) { const float a = fmaxf(v0[j], 0.f), b = fmaxf(v1[j], 0.f); v0[j] = a * a; v1[j] = b * b; }
;                     }
;                     if (MODE == 2 || MODE == 3) {
;                         const u32x4 gw = *(const u32x4*)(gate + off);
;                         v0[0] *= bf_lo(gw.x); v0[1] *= bf_hi(gw.x); v0[2] *= bf_lo(gw.y); v0[3] *= bf_hi(gw.y);
;                         v1[0] *= bf_lo(gw.z); v1[1] *= bf_hi(gw.z); v1[2] *= bf_lo(gw.w); v1[3] *= bf_hi(gw.w);
;                     }
;                     if (MODE == 3) {
;                         const u32x4 pw = *(const u32x4*)(o + off);
;                         v0[0] += bf_lo(pw.x); v0[1] += bf_hi(pw.x); v0[2] += bf_lo(pw.y); v0[3] += bf_hi(pw.y);
;                         v1[0] += bf_lo(pw.z); v1[1] += bf_hi(pw.z); v1[2] += bf_lo(pw.w); v1[3] += bf_hi(pw.w);
;                     }
;                     *(u32x4*)(o + off) = pack8(v0, v1);
;                 }
	v_mov_b32_e32 v108, v90
	v_mov_b32_e32 v109, v92
	v_pk_mul_f32 v[108:109], v[118:119], v[108:109] op_sel_hi:[0,1]
	v_pk_fma_f32 v[86:87], v[86:87], v[114:115], v[108:109] op_sel:[0,1,0] neg_lo:[0,0,1] neg_hi:[0,0,1]
	v_mov_b32_e32 v92, v91
	v_pk_add_f32 v[86:87], v[92:93], v[86:87]
	v_pk_mov_b32 v[92:93], v[88:89], v[96:97] op_sel:[1,0]
	v_mul_f32_e32 v90, v118, v94
	v_pk_mul_f32 v[92:93], v[92:93], v[120:121]
	v_mov_b32_e32 v96, v95
	v_mov_b32_e32 v89, v92
	v_mov_b32_e32 v91, v93
	v_pk_add_f32 v[88:89], v[88:89], v[90:91] neg_lo:[0,1] neg_hi:[0,1]
	v_mov_b32_e32 v90, v98
	v_mov_b32_e32 v91, v100
	v_pk_mov_b32 v[92:93], v[84:85], v[104:105] op_sel:[1,0]
	v_pk_mul_f32 v[90:91], v[118:119], v[90:91] op_sel_hi:[0,1]
	v_pk_mul_f32 v[92:93], v[92:93], v[120:121]
	v_pk_fma_f32 v[82:83], v[82:83], v[114:115], v[90:91] op_sel:[0,1,0] neg_lo:[0,0,1] neg_hi:[0,0,1]
	v_mul_f32_e32 v90, v118, v102
	v_mov_b32_e32 v85, v92
	v_mov_b32_e32 v91, v93
	v_mov_b32_e32 v100, v99
	v_pk_add_f32 v[84:85], v[84:85], v[90:91] neg_lo:[0,1] neg_hi:[0,1]
	v_mov_b32_e32 v104, v103
	v_pk_add_f32 v[82:83], v[100:101], v[82:83]
	v_pk_add_f32 v[84:85], v[104:105], v[84:85]
	v_pk_add_f32 v[88:89], v[96:97], v[88:89]
	v_pk_mul_f32 v[90:91], v[84:85], s[74:75] op_sel_hi:[1,0]
	v_pk_mul_f32 v[84:85], v[82:83], s[74:75] op_sel_hi:[1,0]
	v_pk_mul_f32 v[88:89], v[88:89], s[74:75] op_sel_hi:[1,0]
	v_pk_mul_f32 v[86:87], v[86:87], s[74:75] op_sel_hi:[1,0]
	v_or_b32_e32 v100, 48, v142
	v_cvt_pk_bf16_f32 v82, v86, v87
	v_cvt_pk_bf16_f32 v83, v88, v89
	v_cvt_pk_bf16_f32 v84, v84, v85
	v_cvt_pk_bf16_f32 v85, v90, v91
	flat_store_dwordx4 v[106:107], v[82:85] offset:16
	ds_read_b64 v[98:99], v156 offset:384
	ds_read_b128 v[82:85], v155
	ds_read_b128 v[86:89], v155 offset:16
	ds_read_b128 v[90:93], v155 offset:32
	ds_read_b128 v[94:97], v155 offset:48
	v_ashrrev_i32_e32 v101, 31, v100
	s_waitcnt lgkmcnt(0)
	v_pk_mul_f32 v[102:103], v[98:99], v[98:99] op_sel:[0,1] op_sel_hi:[1,0]
	v_mov_b32_e32 v104, v82
	v_mov_b32_e32 v105, v84
	v_pk_mul_f32 v[104:105], v[102:103], v[104:105] op_sel_hi:[0,1]
	v_pk_fma_f32 v[78:79], v[78:79], v[98:99], v[104:105] op_sel:[0,1,0] neg_lo:[0,0,1] neg_hi:[0,0,1]
	v_mov_b32_e32 v84, v83
	v_mul_f32_e32 v80, v80, v99
	v_pk_add_f32 v[78:79], v[84:85], v[78:79]
	v_pk_mov_b32 v[84:85], v[80:81], v[88:89] op_sel:[1,0]
	v_pk_mov_b32 v[104:105], v[98:99], v[102:103] op_sel:[1,0]
	v_mul_f32_e32 v82, v102, v86
	v_pk_mul_f32 v[84:85], v[84:85], v[104:105]
	v_mul_f32_e32 v76, v76, v99
	v_mov_b32_e32 v81, v84
	v_mov_b32_e32 v83, v85
	v_pk_add_f32 v[80:81], v[80:81], v[82:83] neg_lo:[0,1] neg_hi:[0,1]
	v_mov_b32_e32 v82, v90
	v_mov_b32_e32 v83, v92
	v_pk_mov_b32 v[84:85], v[76:77], v[96:97] op_sel:[1,0]
	v_pk_mul_f32 v[82:83], v[102:103], v[82:83] op_sel_hi:[0,1]
	v_pk_mul_f32 v[84:85], v[84:85], v[104:105]
	v_pk_fma_f32 v[74:75], v[74:75], v[98:99], v[82:83] op_sel:[0,1,0] neg_lo:[0,0,1] neg_hi:[0,0,1]
	v_mul_f32_e32 v82, v102, v94
	v_mov_b32_e32 v77, v84
	v_mov_b32_e32 v83, v85
	v_mov_b32_e32 v92, v91
	v_pk_add_f32 v[76:77], v[76:77], v[82:83] neg_lo:[0,1] neg_hi:[0,1]
	v_mov_b32_e32 v96, v95
	v_pk_add_f32 v[74:75], v[92:93], v[74:75]
	v_pk_add_f32 v[76:77], v[96:97], v[76:77]
	v_pk_mul_f32 v[78:79], v[78:79], s[74:75] op_sel_hi:[1,0]
	v_pk_mul_f32 v[82:83], v[76:77], s[74:75] op_sel_hi:[1,0]
	v_pk_mul_f32 v[76:77], v[74:75], s[74:75] op_sel_hi:[1,0]
	v_cvt_pk_bf16_f32 v74, v78, v79
	v_lshlrev_b64 v[78:79], 10, v[100:101]
	v_mov_b32_e32 v88, v87
	v_lshl_add_u64 v[78:79], s[28:29], 0, v[78:79]
	v_pk_add_f32 v[80:81], v[88:89], v[80:81]
	v_lshl_add_u64 v[90:91], v[78:79], 0, v[124:125]
	v_pk_mul_f32 v[80:81], v[80:81], s[74:75] op_sel_hi:[1,0]
	v_mul_f32_e32 v72, v72, v99
	v_cvt_pk_bf16_f32 v75, v80, v81
	v_cvt_pk_bf16_f32 v76, v76, v77
	v_cvt_pk_bf16_f32 v77, v82, v83
	flat_store_dwordx4 v[90:91], v[74:77]
	ds_read_b128 v[74:77], v155 offset:64
	ds_read_b128 v[78:81], v155 offset:80
	ds_read_b128 v[82:85], v155 offset:96
	ds_read_b128 v[86:89], v155 offset:112
	v_mul_f32_e32 v68, v68, v99
	s_waitcnt lgkmcnt(0)
	v_mov_b32_e32 v92, v74
	v_mov_b32_e32 v93, v76
	v_pk_mul_f32 v[92:93], v[102:103], v[92:93] op_sel_hi:[0,1]
	v_pk_fma_f32 v[70:71], v[70:71], v[98:99], v[92:93] op_sel:[0,1,0] neg_lo:[0,0,1] neg_hi:[0,0,1]
	v_mov_b32_e32 v76, v75
	v_pk_add_f32 v[70:71], v[76:77], v[70:71]
	v_pk_mov_b32 v[76:77], v[72:73], v[80:81] op_sel:[1,0]
	v_mul_f32_e32 v74, v102, v78
	v_pk_mul_f32 v[76:77], v[76:77], v[104:105]
	v_mov_b32_e32 v80, v79
	v_mov_b32_e32 v73, v76
	v_mov_b32_e32 v75, v77
	v_pk_add_f32 v[72:73], v[72:73], v[74:75] neg_lo:[0,1] neg_hi:[0,1]
	v_mov_b32_e32 v74, v82
	v_mov_b32_e32 v75, v84
	v_pk_mov_b32 v[76:77], v[68:69], v[88:89] op_sel:[1,0]
	v_pk_mul_f32 v[74:75], v[102:103], v[74:75] op_sel_hi:[0,1]
	v_pk_mul_f32 v[76:77], v[76:77], v[104:105]
	v_pk_fma_f32 v[66:67], v[66:67], v[98:99], v[74:75] op_sel:[0,1,0] neg_lo:[0,0,1] neg_hi:[0,0,1]
	v_mul_f32_e32 v74, v102, v86
	v_mov_b32_e32 v69, v76
	v_mov_b32_e32 v75, v77
	v_mov_b32_e32 v84, v83
	v_pk_add_f32 v[68:69], v[68:69], v[74:75] neg_lo:[0,1] neg_hi:[0,1]
	v_mov_b32_e32 v88, v87
	v_pk_add_f32 v[66:67], v[84:85], v[66:67]
	v_pk_add_f32 v[68:69], v[88:89], v[68:69]
	v_pk_add_f32 v[72:73], v[80:81], v[72:73]
	v_pk_mul_f32 v[74:75], v[68:69], s[74:75] op_sel_hi:[1,0]
	v_pk_mul_f32 v[68:69], v[66:67], s[74:75] op_sel_hi:[1,0]
	v_pk_mul_f32 v[72:73], v[72:73], s[74:75] op_sel_hi:[1,0]
	v_pk_mul_f32 v[70:71], v[70:71], s[74:75] op_sel_hi:[1,0]
	s_mov_b64 s[28:29], 0x20000
	v_cvt_pk_bf16_f32 v66, v70, v71
	v_cvt_pk_bf16_f32 v67, v72, v73
	v_cvt_pk_bf16_f32 v68, v68, v69
	v_cvt_pk_bf16_f32 v69, v74, v75
	flat_store_dwordx4 v[90:91], v[66:69] offset:16
	ds_read_b64 v[82:83], v156 offset:1024
	ds_read_b128 v[66:69], v155
	ds_read_b128 v[70:73], v155 offset:16
	ds_read_b128 v[74:77], v155 offset:32
	ds_read_b128 v[78:81], v155 offset:48
	s_waitcnt lgkmcnt(0)
; #define LAS __attribute__((address_space(3)))
; __device__ __forceinline__ float bf_lo(unsigned w) { return __uint_as_float(w << 16); }
;     __device__ __forceinline__ void operator()(const f32x4 (&acc)[2][2][4][2], const pg8::Unit& u, int wr, int wc, int fr, int fq, LAS unsigned char* lds, int par) const {
;         const bool fold = F.stats != nullptr;
;         const LAS float* rsb = (const LAS float*)(lds + RS_OFF) + par * 512; const LAS float* cvb = (const LAS float*)(lds + CV_OFF) + (par * 2 + wr) * 512;
;         const int row0 = u.pm * 256 + wr * 64 + fr, c0 = u.pn * 256 + wc * 64 + 16 * fq;
; #pragma unroll
;         for (int ai = 0; ai < 2; ++ai)
; #pragma unroll
;             for (int m = 0; m < 4; ++m) {
;                 const int row = row0 + ai * 128 + m * 16, lrow = ai * 128 + wr * 64 + m * 16 + fr;
;                 float mu = 0.f, rstd = 1.f; if (fold) { mu = rsb[2 * lrow]; rstd = rsb[2 * lrow + 1]; }
; #pragma unroll
;                 for (int bj = 0; bj < 2; ++bj) {
;                     const size_t off = (size_t)row * ld + c0 + bj * 8;
;                     f32x4 v0 = acc[ai][bj][m][0], v1 = acc[ai][bj][m][1];
;                     if (fold) fold_apply(v0, v1, mu, rstd, cvb, wc * 64 + 16 * fq + bj * 8);
;                     if (MODE == 0) { v0 *= scale; v1 *= scale; }
;                     if (MODE == 1) {
; #pragma unroll
;                         for (int j = 0; j < 4; ++j) { const float a = fmaxf(v0[j], 0.f), b = fmaxf(v1[j], 0.f); v0[j] = a * a; v1[j] = b * b; }
;                     }
;                     if (MODE == 2 || MODE == 3) {
;                         const u32x4 gw = *(const u32x4*)(gate + off);
;                         v0[0] *= bf_lo(gw.x); v0[1] *= bf_hi(gw.x); v0[2] *= bf_lo(gw.y); v0[3] *= bf_hi(gw.y);
;                         v1[0] *= bf_lo(gw.z); v1[1] *= bf_hi(gw.z); v1[2] *= bf_lo(gw.w); v1[3] *= bf_hi(gw.w);
;                     }
;                     if (MODE == 3) {
;                         const u32x4 pw = *(const u32x4*)(o + off);
;                         v0[0] += bf_lo(pw.x); v0[1] += bf_hi(pw.x); v0[2] += bf_lo(pw.y); v0[3] += bf_hi(pw.y);
;                         v1[0] += bf_lo(pw.z); v1[1] += bf_hi(pw.z); v1[2] += bf_lo(pw.w); v1[3] += bf_hi(pw.w);
;                     }
;                     *(u32x4*)(o + off) = pack8(v0, v1);
;                 }
	v_pk_mul_f32 v[84:85], v[82:83], v[82:83] op_sel:[0,1] op_sel_hi:[1,0]
	v_mov_b32_e32 v86, v66
	v_mov_b32_e32 v87, v68
	v_pk_mul_f32 v[86:87], v[84:85], v[86:87] op_sel_hi:[0,1]
	v_pk_fma_f32 v[62:63], v[62:63], v[82:83], v[86:87] op_sel:[0,1,0] neg_lo:[0,0,1] neg_hi:[0,0,1]
	v_mov_b32_e32 v68, v67
	v_mul_f32_e32 v64, v64, v83
	v_pk_add_f32 v[62:63], v[68:69], v[62:63]
	v_pk_mov_b32 v[68:69], v[64:65], v[72:73] op_sel:[1,0]
	v_pk_mov_b32 v[86:87], v[82:83], v[84:85] op_sel:[1,0]
	v_mul_f32_e32 v66, v84, v70
	v_pk_mul_f32 v[68:69], v[68:69], v[86:87]
	v_mul_f32_e32 v60, v60, v83
	v_mov_b32_e32 v65, v68
	v_mov_b32_e32 v67, v69
	v_pk_add_f32 v[64:65], v[64:65], v[66:67] neg_lo:[0,1] neg_hi:[0,1]
	v_mov_b32_e32 v66, v74
	v_mov_b32_e32 v67, v76
	v_pk_mov_b32 v[68:69], v[60:61], v[80:81] op_sel:[1,0]
	v_pk_mul_f32 v[66:67], v[84:85], v[66:67] op_sel_hi:[0,1]
	v_pk_mul_f32 v[68:69], v[68:69], v[86:87]
	v_pk_fma_f32 v[58:59], v[58:59], v[82:83], v[66:67] op_sel:[0,1,0] neg_lo:[0,0,1] neg_hi:[0,0,1]
	v_mul_f32_e32 v66, v84, v78
	v_mov_b32_e32 v61, v68
	v_mov_b32_e32 v67, v69
	v_mov_b32_e32 v76, v75
	v_pk_add_f32 v[60:61], v[60:61], v[66:67] neg_lo:[0,1] neg_hi:[0,1]
	v_mov_b32_e32 v80, v79
	v_pk_add_f32 v[58:59], v[76:77], v[58:59]
	v_pk_add_f32 v[60:61], v[80:81], v[60:61]
	v_pk_mul_f32 v[62:63], v[62:63], s[74:75] op_sel_hi:[1,0]
	v_mov_b32_e32 v72, v71
	v_pk_mul_f32 v[66:67], v[60:61], s[74:75] op_sel_hi:[1,0]
	v_pk_mul_f32 v[60:61], v[58:59], s[74:75] op_sel_hi:[1,0]
	v_cvt_pk_bf16_f32 v58, v62, v63
	v_add_co_u32_e32 v62, vcc, s62, v122
	v_pk_add_f32 v[64:65], v[72:73], v[64:65]
	s_nop 0
	v_addc_co_u32_e32 v63, vcc, 0, v123, vcc
	v_pk_mul_f32 v[64:65], v[64:65], s[74:75] op_sel_hi:[1,0]
	v_mul_f32_e32 v56, v56, v83
	v_cvt_pk_bf16_f32 v59, v64, v65
	v_cvt_pk_bf16_f32 v60, v60, v61
	v_cvt_pk_bf16_f32 v61, v66, v67
	flat_store_dwordx4 v[62:63], v[58:61]
	ds_read_b128 v[58:61], v155 offset:64
	ds_read_b128 v[62:65], v155 offset:80
	ds_read_b128 v[66:69], v155 offset:96
	ds_read_b128 v[70:73], v155 offset:112
	v_mul_f32_e32 v52, v52, v83
	v_lshl_add_u64 v[74:75], v[122:123], 0, s[28:29]
	s_mov_b64 s[28:29], 0x24000
	s_waitcnt lgkmcnt(0)
	v_mov_b32_e32 v76, v58
	v_mov_b32_e32 v77, v60
	v_pk_mul_f32 v[76:77], v[84:85], v[76:77] op_sel_hi:[0,1]
	v_pk_fma_f32 v[54:55], v[54:55], v[82:83], v[76:77] op_sel:[0,1,0] neg_lo:[0,0,1] neg_hi:[0,0,1]
	v_mov_b32_e32 v60, v59
	v_pk_add_f32 v[54:55], v[60:61], v[54:55]
	v_pk_mov_b32 v[60:61], v[56:57], v[64:65] op_sel:[1,0]
	v_mul_f32_e32 v58, v84, v62
	v_pk_mul_f32 v[60:61], v[60:61], v[86:87]
	v_mov_b32_e32 v64, v63
	v_mov_b32_e32 v57, v60
	v_mov_b32_e32 v59, v61
	v_pk_add_f32 v[56:57], v[56:57], v[58:59] neg_lo:[0,1] neg_hi:[0,1]
	v_mov_b32_e32 v58, v66
	v_mov_b32_e32 v59, v68
	v_pk_mov_b32 v[60:61], v[52:53], v[72:73] op_sel:[1,0]
	v_pk_mul_f32 v[58:59], v[84:85], v[58:59] op_sel_hi:[0,1]
	v_pk_mul_f32 v[60:61], v[60:61], v[86:87]
	v_pk_fma_f32 v[50:51], v[50:51], v[82:83], v[58:59] op_sel:[0,1,0] neg_lo:[0,0,1] neg_hi:[0,0,1]
	v_mul_f32_e32 v58, v84, v70
	v_mov_b32_e32 v53, v60
	v_mov_b32_e32 v59, v61
	v_mov_b32_e32 v68, v67
	v_pk_add_f32 v[52:53], v[52:53], v[58:59] neg_lo:[0,1] neg_hi:[0,1]
	v_mov_b32_e32 v72, v71
	v_pk_add_f32 v[50:51], v[68:69], v[50:51]
	v_pk_add_f32 v[52:53], v[72:73], v[52:53]
	v_pk_add_f32 v[56:57], v[64:65], v[56:57]
	v_pk_mul_f32 v[58:59], v[52:53], s[74:75] op_sel_hi:[1,0]
	v_pk_mul_f32 v[52:53], v[50:51], s[74:75] op_sel_hi:[1,0]
	v_pk_mul_f32 v[56:57], v[56:57], s[74:75] op_sel_hi:[1,0]
	v_pk_mul_f32 v[54:55], v[54:55], s[74:75] op_sel_hi:[1,0]
	s_nop 0
	v_cvt_pk_bf16_f32 v50, v54, v55
	v_cvt_pk_bf16_f32 v51, v56, v57
	v_cvt_pk_bf16_f32 v52, v52, v53
	v_cvt_pk_bf16_f32 v53, v58, v59
	flat_store_dwordx4 v[74:75], v[50:53] offset:16
	ds_read_b64 v[66:67], v156 offset:1152
	ds_read_b128 v[50:53], v155
	ds_read_b128 v[54:57], v155 offset:16
	ds_read_b128 v[58:61], v155 offset:32
	ds_read_b128 v[62:65], v155 offset:48
	s_waitcnt lgkmcnt(0)
	v_pk_mul_f32 v[68:69], v[66:67], v[66:67] op_sel:[0,1] op_sel_hi:[1,0]
	v_mov_b32_e32 v70, v50
	v_mov_b32_e32 v71, v52
	v_pk_mul_f32 v[70:71], v[68:69], v[70:71] op_sel_hi:[0,1]
	v_pk_fma_f32 v[46:47], v[46:47], v[66:67], v[70:71] op_sel:[0,1,0] neg_lo:[0,0,1] neg_hi:[0,0,1]
	v_mov_b32_e32 v52, v51
	v_mul_f32_e32 v48, v48, v67
	v_pk_add_f32 v[46:47], v[52:53], v[46:47]
	v_pk_mov_b32 v[52:53], v[48:49], v[56:57] op_sel:[1,0]
	v_pk_mov_b32 v[70:71], v[66:67], v[68:69] op_sel:[1,0]
	v_mul_f32_e32 v50, v68, v54
	v_pk_mul_f32 v[52:53], v[52:53], v[70:71]
	v_mul_f32_e32 v44, v44, v67
	v_mov_b32_e32 v49, v52
	v_mov_b32_e32 v51, v53
	v_pk_add_f32 v[48:49], v[48:49], v[50:51] neg_lo:[0,1] neg_hi:[0,1]
	v_mov_b32_e32 v50, v58
	v_mov_b32_e32 v51, v60
	v_pk_mov_b32 v[52:53], v[44:45], v[64:65] op_sel:[1,0]
	v_pk_mul_f32 v[50:51], v[68:69], v[50:51] op_sel_hi:[0,1]
	v_pk_mul_f32 v[52:53], v[52:53], v[70:71]
	v_pk_fma_f32 v[42:43], v[42:43], v[66:67], v[50:51] op_sel:[0,1,0] neg_lo:[0,0,1] neg_hi:[0,0,1]
	v_mul_f32_e32 v50, v68, v62
	v_mov_b32_e32 v45, v52
	v_mov_b32_e32 v51, v53
	v_mov_b32_e32 v60, v59
	v_pk_add_f32 v[44:45], v[44:45], v[50:51] neg_lo:[0,1] neg_hi:[0,1]
	v_mov_b32_e32 v64, v63
	v_pk_add_f32 v[42:43], v[60:61], v[42:43]
	v_pk_add_f32 v[44:45], v[64:65], v[44:45]
	v_pk_mul_f32 v[46:47], v[46:47], s[74:75] op_sel_hi:[1,0]
	v_mov_b32_e32 v56, v55
	v_pk_mul_f32 v[50:51], v[44:45], s[74:75] op_sel_hi:[1,0]
	v_pk_mul_f32 v[44:45], v[42:43], s[74:75] op_sel_hi:[1,0]
	v_cvt_pk_bf16_f32 v42, v46, v47
	v_add_co_u32_e32 v46, vcc, s66, v122
	v_pk_add_f32 v[48:49], v[56:57], v[48:49]
	s_nop 0
	v_addc_co_u32_e32 v47, vcc, 0, v123, vcc
	v_pk_mul_f32 v[48:49], v[48:49], s[74:75] op_sel_hi:[1,0]
	v_mul_f32_e32 v40, v40, v67
	v_cvt_pk_bf16_f32 v43, v48, v49
	v_cvt_pk_bf16_f32 v44, v44, v45
	v_cvt_pk_bf16_f32 v45, v50, v51
	flat_store_dwordx4 v[46:47], v[42:45]
	ds_read_b128 v[42:45], v155 offset:64
	ds_read_b128 v[46:49], v155 offset:80
	ds_read_b128 v[50:53], v155 offset:96
	ds_read_b128 v[54:57], v155 offset:112
	v_mul_f32_e32 v36, v36, v67
	v_lshl_add_u64 v[58:59], v[122:123], 0, s[28:29]
	s_mov_b64 s[28:29], 0x28000
	s_waitcnt lgkmcnt(0)
; #define LAS __attribute__((address_space(3)))
; __device__ __forceinline__ float bf_lo(unsigned w) { return __uint_as_float(w << 16); }
;     __device__ __forceinline__ void operator()(const f32x4 (&acc)[2][2][4][2], const pg8::Unit& u, int wr, int wc, int fr, int fq, LAS unsigned char* lds, int par) const {
;         const bool fold = F.stats != nullptr;
;         const LAS float* rsb = (const LAS float*)(lds + RS_OFF) + par * 512; const LAS float* cvb = (const LAS float*)(lds + CV_OFF) + (par * 2 + wr) * 512;
;         const int row0 = u.pm * 256 + wr * 64 + fr, c0 = u.pn * 256 + wc * 64 + 16 * fq;
; #pragma unroll
;         for (int ai = 0; ai < 2; ++ai)
; #pragma unroll
;             for (int m = 0; m < 4; ++m) {
;                 const int row = row0 + ai * 128 + m * 16, lrow = ai * 128 + wr * 64 + m * 16 + fr;
;                 float mu = 0.f, rstd = 1.f; if (fold) { mu = rsb[2 * lrow]; rstd = rsb[2 * lrow + 1]; }
; #pragma unroll
;                 for (int bj = 0; bj < 2; ++bj) {
;                     const size_t off = (size_t)row * ld + c0 + bj * 8;
;                     f32x4 v0 = acc[ai][bj][m][0], v1 = acc[ai][bj][m][1];
;                     if (fold) fold_apply(v0, v1, mu, rstd, cvb, wc * 64 + 16 * fq + bj * 8);
;                     if (MODE == 0) { v0 *= scale; v1 *= scale; }
;                     if (MODE == 1) {
; #pragma unroll
;                         for (int j = 0; j < 4; ++j) { const float a = fmaxf(v0[j], 0.f), b = fmaxf(v1[j], 0.f); v0[j] = a * a; v1[j] = b * b; }
;                     }
;                     if (MODE == 2 || MODE == 3) {
;                         const u32x4 gw = *(const u32x4*)(gate + off);
;                         v0[0] *= bf_lo(gw.x); v0[1] *= bf_hi(gw.x); v0[2] *= bf_lo(gw.y); v0[3] *= bf_hi(gw.y);
;                         v1[0] *= bf_lo(gw.z); v1[1] *= bf_hi(gw.z); v1[2] *= bf_lo(gw.w); v1[3] *= bf_hi(gw.w);
;                     }
;                     if (MODE == 3) {
;                         const u32x4 pw = *(const u32x4*)(o + off);
;                         v0[0] += bf_lo(pw.x); v0[1] += bf_hi(pw.x); v0[2] += bf_lo(pw.y); v0[3] += bf_hi(pw.y);
;                         v1[0] += bf_lo(pw.z); v1[1] += bf_hi(pw.z); v1[2] += bf_lo(pw.w); v1[3] += bf_hi(pw.w);
;                     }
;                     *(u32x4*)(o + off) = pack8(v0, v1);
;                 }
	v_mov_b32_e32 v60, v42
	v_mov_b32_e32 v61, v44
	v_pk_mul_f32 v[60:61], v[68:69], v[60:61] op_sel_hi:[0,1]
	v_pk_fma_f32 v[38:39], v[38:39], v[66:67], v[60:61] op_sel:[0,1,0] neg_lo:[0,0,1] neg_hi:[0,0,1]
	v_mov_b32_e32 v44, v43
	v_pk_add_f32 v[38:39], v[44:45], v[38:39]
	v_pk_mov_b32 v[44:45], v[40:41], v[48:49] op_sel:[1,0]
	v_mul_f32_e32 v42, v68, v46
	v_pk_mul_f32 v[44:45], v[44:45], v[70:71]
	v_mov_b32_e32 v48, v47
	v_mov_b32_e32 v41, v44
	v_mov_b32_e32 v43, v45
	v_pk_add_f32 v[40:41], v[40:41], v[42:43] neg_lo:[0,1] neg_hi:[0,1]
	v_mov_b32_e32 v42, v50
	v_mov_b32_e32 v43, v52
	v_pk_mov_b32 v[44:45], v[36:37], v[56:57] op_sel:[1,0]
	v_pk_mul_f32 v[42:43], v[68:69], v[42:43] op_sel_hi:[0,1]
	v_pk_mul_f32 v[44:45], v[44:45], v[70:71]
	v_pk_fma_f32 v[34:35], v[34:35], v[66:67], v[42:43] op_sel:[0,1,0] neg_lo:[0,0,1] neg_hi:[0,0,1]
	v_mul_f32_e32 v42, v68, v54
	v_mov_b32_e32 v37, v44
	v_mov_b32_e32 v43, v45
	v_mov_b32_e32 v52, v51
	v_pk_add_f32 v[36:37], v[36:37], v[42:43] neg_lo:[0,1] neg_hi:[0,1]
	v_mov_b32_e32 v56, v55
	v_pk_add_f32 v[34:35], v[52:53], v[34:35]
	v_pk_add_f32 v[36:37], v[56:57], v[36:37]
	v_pk_add_f32 v[40:41], v[48:49], v[40:41]
	v_pk_mul_f32 v[42:43], v[36:37], s[74:75] op_sel_hi:[1,0]
	v_pk_mul_f32 v[36:37], v[34:35], s[74:75] op_sel_hi:[1,0]
	v_pk_mul_f32 v[40:41], v[40:41], s[74:75] op_sel_hi:[1,0]
	v_pk_mul_f32 v[38:39], v[38:39], s[74:75] op_sel_hi:[1,0]
	s_nop 0
	v_cvt_pk_bf16_f32 v34, v38, v39
	v_cvt_pk_bf16_f32 v35, v40, v41
	v_cvt_pk_bf16_f32 v36, v36, v37
	v_cvt_pk_bf16_f32 v37, v42, v43
	flat_store_dwordx4 v[58:59], v[34:37] offset:16
	ds_read_b64 v[50:51], v156 offset:1280
	ds_read_b128 v[34:37], v155
	ds_read_b128 v[38:41], v155 offset:16
	ds_read_b128 v[42:45], v155 offset:32
	ds_read_b128 v[46:49], v155 offset:48
	s_waitcnt lgkmcnt(0)
	v_pk_mul_f32 v[52:53], v[50:51], v[50:51] op_sel:[0,1] op_sel_hi:[1,0]
	v_mov_b32_e32 v54, v34
	v_mov_b32_e32 v55, v36
	v_pk_mul_f32 v[54:55], v[52:53], v[54:55] op_sel_hi:[0,1]
	v_pk_fma_f32 v[30:31], v[30:31], v[50:51], v[54:55] op_sel:[0,1,0] neg_lo:[0,0,1] neg_hi:[0,0,1]
	v_mov_b32_e32 v36, v35
	v_mul_f32_e32 v32, v32, v51
	v_pk_add_f32 v[30:31], v[36:37], v[30:31]
	v_pk_mov_b32 v[36:37], v[32:33], v[40:41] op_sel:[1,0]
	v_pk_mov_b32 v[54:55], v[50:51], v[52:53] op_sel:[1,0]
	v_mul_f32_e32 v34, v52, v38
	v_pk_mul_f32 v[36:37], v[36:37], v[54:55]
	v_mul_f32_e32 v28, v28, v51
	v_mov_b32_e32 v33, v36
	v_mov_b32_e32 v35, v37
	v_pk_add_f32 v[32:33], v[32:33], v[34:35] neg_lo:[0,1] neg_hi:[0,1]
	v_mov_b32_e32 v34, v42
	v_mov_b32_e32 v35, v44
	v_pk_mov_b32 v[36:37], v[28:29], v[48:49] op_sel:[1,0]
	v_pk_mul_f32 v[34:35], v[52:53], v[34:35] op_sel_hi:[0,1]
	v_pk_mul_f32 v[36:37], v[36:37], v[54:55]
	v_pk_fma_f32 v[26:27], v[26:27], v[50:51], v[34:35] op_sel:[0,1,0] neg_lo:[0,0,1] neg_hi:[0,0,1]
	v_mul_f32_e32 v34, v52, v46
	v_mov_b32_e32 v29, v36
	v_mov_b32_e32 v35, v37
	v_mov_b32_e32 v44, v43
	v_pk_add_f32 v[28:29], v[28:29], v[34:35] neg_lo:[0,1] neg_hi:[0,1]
	v_mov_b32_e32 v48, v47
	v_pk_add_f32 v[26:27], v[44:45], v[26:27]
	v_pk_add_f32 v[28:29], v[48:49], v[28:29]
	v_pk_mul_f32 v[30:31], v[30:31], s[74:75] op_sel_hi:[1,0]
	v_mov_b32_e32 v40, v39
	v_pk_mul_f32 v[34:35], v[28:29], s[74:75] op_sel_hi:[1,0]
	v_pk_mul_f32 v[28:29], v[26:27], s[74:75] op_sel_hi:[1,0]
	v_cvt_pk_bf16_f32 v26, v30, v31
	v_add_co_u32_e32 v30, vcc, s63, v122
	v_pk_add_f32 v[32:33], v[40:41], v[32:33]
	s_nop 0
	v_addc_co_u32_e32 v31, vcc, 0, v123, vcc
	v_pk_mul_f32 v[32:33], v[32:33], s[74:75] op_sel_hi:[1,0]
	v_mul_f32_e32 v24, v24, v51
	v_cvt_pk_bf16_f32 v27, v32, v33
	v_cvt_pk_bf16_f32 v28, v28, v29
	v_cvt_pk_bf16_f32 v29, v34, v35
	flat_store_dwordx4 v[30:31], v[26:29]
	ds_read_b128 v[26:29], v155 offset:64
	ds_read_b128 v[30:33], v155 offset:80
	ds_read_b128 v[34:37], v155 offset:96
	ds_read_b128 v[38:41], v155 offset:112
	v_mul_f32_e32 v20, v20, v51
	v_lshl_add_u64 v[42:43], v[122:123], 0, s[28:29]
	s_mov_b64 s[28:29], 0x2c000
	s_waitcnt lgkmcnt(0)
	v_mov_b32_e32 v44, v26
	v_mov_b32_e32 v45, v28
	v_pk_mul_f32 v[44:45], v[52:53], v[44:45] op_sel_hi:[0,1]
	v_pk_fma_f32 v[22:23], v[22:23], v[50:51], v[44:45] op_sel:[0,1,0] neg_lo:[0,0,1] neg_hi:[0,0,1]
	v_mov_b32_e32 v28, v27
	v_pk_add_f32 v[22:23], v[28:29], v[22:23]
	v_pk_mov_b32 v[28:29], v[24:25], v[32:33] op_sel:[1,0]
	v_mul_f32_e32 v26, v52, v30
	v_pk_mul_f32 v[28:29], v[28:29], v[54:55]
	v_mov_b32_e32 v32, v31
	v_mov_b32_e32 v25, v28
	v_mov_b32_e32 v27, v29
	v_pk_add_f32 v[24:25], v[24:25], v[26:27] neg_lo:[0,1] neg_hi:[0,1]
	v_mov_b32_e32 v26, v34
	v_mov_b32_e32 v27, v36
	v_pk_mov_b32 v[28:29], v[20:21], v[40:41] op_sel:[1,0]
	v_pk_mul_f32 v[26:27], v[52:53], v[26:27] op_sel_hi:[0,1]
	v_pk_mul_f32 v[28:29], v[28:29], v[54:55]
	v_pk_fma_f32 v[18:19], v[18:19], v[50:51], v[26:27] op_sel:[0,1,0] neg_lo:[0,0,1] neg_hi:[0,0,1]
	v_mul_f32_e32 v26, v52, v38
	v_mov_b32_e32 v21, v28
	v_mov_b32_e32 v27, v29
	v_mov_b32_e32 v36, v35
	v_pk_add_f32 v[20:21], v[20:21], v[26:27] neg_lo:[0,1] neg_hi:[0,1]
	v_mov_b32_e32 v40, v39
	v_pk_add_f32 v[18:19], v[36:37], v[18:19]
	v_pk_add_f32 v[20:21], v[40:41], v[20:21]
	v_pk_add_f32 v[24:25], v[32:33], v[24:25]
	v_pk_mul_f32 v[26:27], v[20:21], s[74:75] op_sel_hi:[1,0]
	v_pk_mul_f32 v[20:21], v[18:19], s[74:75] op_sel_hi:[1,0]
	v_pk_mul_f32 v[24:25], v[24:25], s[74:75] op_sel_hi:[1,0]
	v_pk_mul_f32 v[22:23], v[22:23], s[74:75] op_sel_hi:[1,0]
	s_nop 0
	v_cvt_pk_bf16_f32 v18, v22, v23
	v_cvt_pk_bf16_f32 v19, v24, v25
	v_cvt_pk_bf16_f32 v20, v20, v21
	v_cvt_pk_bf16_f32 v21, v26, v27
	flat_store_dwordx4 v[42:43], v[18:21] offset:16
	ds_read_b64 v[34:35], v156 offset:1408
	ds_read_b128 v[18:21], v155
	ds_read_b128 v[22:25], v155 offset:16
	ds_read_b128 v[26:29], v155 offset:32
	ds_read_b128 v[30:33], v155 offset:48
	s_waitcnt lgkmcnt(0)
;     __device__ __forceinline__ void prepare(const pg8::Unit& u, LAS unsigned char* lds, int par, int tid) const {
;         if (stats == nullptr) return;
;     __device__ __forceinline__ void operator()(const f32x4 (&acc)[2][2][4][2], const pg8::Unit& u, int wr, int wc, int fr, int fq, LAS unsigned char* lds, int par) const {
;         const bool fold = F.stats != nullptr;
;         const LAS float* rsb = (const LAS float*)(lds + RS_OFF) + par * 512; const LAS float* cvb = (const LAS float*)(lds + CV_OFF) + (par * 2 + wr) * 512;
;         const int row0 = u.pm * 256 + wr * 64 + fr, c0 = u.pn * 256 + wc * 64 + 16 * fq;
; #pragma unroll
;         for (int ai = 0; ai < 2; ++ai)
; #pragma unroll
;             for (int m = 0; m < 4; ++m) {
;                 const int row = row0 + ai * 128 + m * 16, lrow = ai * 128 + wr * 64 + m * 16 + fr;
;                 float mu = 0.f, rstd = 1.f; if (fold) { mu = rsb[2 * lrow]; rstd = rsb[2 * lrow + 1]; }
; #pragma unroll
;                 for (int bj = 0; bj < 2; ++bj) {
;                     const size_t off = (size_t)row * ld + c0 + bj * 8;
;                     f32x4 v0 = acc[ai][bj][m][0], v1 = acc[ai][bj][m][1];
;                     if (fold) fold_apply(v0, v1, mu, rstd, cvb, wc * 64 + 16 * fq + bj * 8);
;                     if (MODE == 0) { v0 *= scale; v1 *= scale; }
;                     if (MODE == 1) {
; #pragma unroll
;                         for (int j = 0; j < 4; ++j) { const float a = fmaxf(v0[j], 0.f), b = fmaxf(v1[j], 0.f); v0[j] = a * a; v1[j] = b * b; }
;                     }
;                     if (MODE == 2 || MODE == 3) {
;                         const u32x4 gw = *(const u32x4*)(gate + off);
;                         v0[0] *= bf_lo(gw.x); v0[1] *= bf_hi(gw.x); v0[2] *= bf_lo(gw.y); v0[3] *= bf_hi(gw.y);
;                         v1[0] *= bf_lo(gw.z); v1[1] *= bf_hi(gw.z); v1[2] *= bf_lo(gw.w); v1[3] *= bf_hi(gw.w);
;                     }
;                     if (MODE == 3) {
;                         const u32x4 pw = *(const u32x4*)(o + off);
;                         v0[0] += bf_lo(pw.x); v0[1] += bf_hi(pw.x); v0[2] += bf_lo(pw.y); v0[3] += bf_hi(pw.y);
;                         v1[0] += bf_lo(pw.z); v1[1] += bf_hi(pw.z); v1[2] += bf_lo(pw.w); v1[3] += bf_hi(pw.w);
;                     }
;                     *(u32x4*)(o + off) = pack8(v0, v1);
;                 }
	v_pk_mul_f32 v[36:37], v[34:35], v[34:35] op_sel:[0,1] op_sel_hi:[1,0]
	v_mov_b32_e32 v38, v18
	v_mov_b32_e32 v39, v20
	v_pk_mul_f32 v[38:39], v[36:37], v[38:39] op_sel_hi:[0,1]
	v_pk_fma_f32 v[14:15], v[14:15], v[34:35], v[38:39] op_sel:[0,1,0] neg_lo:[0,0,1] neg_hi:[0,0,1]
	v_mov_b32_e32 v20, v19
	v_mul_f32_e32 v16, v16, v35
	v_pk_add_f32 v[14:15], v[20:21], v[14:15]
	v_pk_mov_b32 v[20:21], v[16:17], v[24:25] op_sel:[1,0]
	v_pk_mov_b32 v[38:39], v[34:35], v[36:37] op_sel:[1,0]
	v_mul_f32_e32 v18, v36, v22
	v_pk_mul_f32 v[20:21], v[20:21], v[38:39]
	v_mul_f32_e32 v12, v12, v35
	v_mov_b32_e32 v17, v20
	v_mov_b32_e32 v19, v21
	v_pk_add_f32 v[16:17], v[16:17], v[18:19] neg_lo:[0,1] neg_hi:[0,1]
	v_mov_b32_e32 v18, v26
	v_mov_b32_e32 v19, v28
	v_pk_mov_b32 v[20:21], v[12:13], v[32:33] op_sel:[1,0]
	v_pk_mul_f32 v[18:19], v[36:37], v[18:19] op_sel_hi:[0,1]
	v_pk_mul_f32 v[20:21], v[20:21], v[38:39]
	v_pk_fma_f32 v[10:11], v[10:11], v[34:35], v[18:19] op_sel:[0,1,0] neg_lo:[0,0,1] neg_hi:[0,0,1]
	v_mul_f32_e32 v18, v36, v30
	v_mov_b32_e32 v13, v20
	v_mov_b32_e32 v19, v21
	v_mov_b32_e32 v28, v27
	v_pk_add_f32 v[12:13], v[12:13], v[18:19] neg_lo:[0,1] neg_hi:[0,1]
	v_mov_b32_e32 v32, v31
	v_pk_add_f32 v[10:11], v[28:29], v[10:11]
	v_pk_add_f32 v[12:13], v[32:33], v[12:13]
	v_pk_mul_f32 v[14:15], v[14:15], s[74:75] op_sel_hi:[1,0]
	v_mov_b32_e32 v24, v23
	v_pk_mul_f32 v[18:19], v[12:13], s[74:75] op_sel_hi:[1,0]
	v_pk_mul_f32 v[12:13], v[10:11], s[74:75] op_sel_hi:[1,0]
	v_cvt_pk_bf16_f32 v10, v14, v15
	v_add_co_u32_e32 v14, vcc, s82, v122
	v_pk_add_f32 v[16:17], v[24:25], v[16:17]
	s_nop 0
	v_addc_co_u32_e32 v15, vcc, 0, v123, vcc
	v_pk_mul_f32 v[16:17], v[16:17], s[74:75] op_sel_hi:[1,0]
	v_mul_f32_e32 v8, v8, v35
	v_cvt_pk_bf16_f32 v11, v16, v17
	v_cvt_pk_bf16_f32 v12, v12, v13
	v_cvt_pk_bf16_f32 v13, v18, v19
	flat_store_dwordx4 v[14:15], v[10:13]
	ds_read_b128 v[10:13], v155 offset:64
	ds_read_b128 v[14:17], v155 offset:80
	ds_read_b128 v[18:21], v155 offset:96
	ds_read_b128 v[22:25], v155 offset:112
	v_mul_f32_e32 v4, v4, v35
	v_lshl_add_u64 v[26:27], v[122:123], 0, s[28:29]
	s_andn2_b64 vcc, exec, s[24:25]
	s_waitcnt lgkmcnt(0)
	v_mov_b32_e32 v28, v10
	v_mov_b32_e32 v29, v12
	v_pk_mul_f32 v[28:29], v[36:37], v[28:29] op_sel_hi:[0,1]
	v_pk_fma_f32 v[6:7], v[6:7], v[34:35], v[28:29] op_sel:[0,1,0] neg_lo:[0,0,1] neg_hi:[0,0,1]
	v_mov_b32_e32 v12, v11
	v_pk_add_f32 v[6:7], v[12:13], v[6:7]
	v_pk_mov_b32 v[12:13], v[8:9], v[16:17] op_sel:[1,0]
	v_mul_f32_e32 v10, v36, v14
	v_pk_mul_f32 v[12:13], v[12:13], v[38:39]
	v_mov_b32_e32 v16, v15
	v_mov_b32_e32 v9, v12
	v_mov_b32_e32 v11, v13
	v_pk_add_f32 v[8:9], v[8:9], v[10:11] neg_lo:[0,1] neg_hi:[0,1]
	v_mov_b32_e32 v10, v18
	v_mov_b32_e32 v11, v20
	v_pk_mov_b32 v[12:13], v[4:5], v[24:25] op_sel:[1,0]
	v_pk_mul_f32 v[10:11], v[36:37], v[10:11] op_sel_hi:[0,1]
	v_pk_mul_f32 v[12:13], v[12:13], v[38:39]
	v_pk_fma_f32 v[2:3], v[2:3], v[34:35], v[10:11] op_sel:[0,1,0] neg_lo:[0,0,1] neg_hi:[0,0,1]
	v_mul_f32_e32 v10, v36, v22
	v_mov_b32_e32 v5, v12
	v_mov_b32_e32 v11, v13
	v_mov_b32_e32 v20, v19
	v_pk_add_f32 v[4:5], v[4:5], v[10:11] neg_lo:[0,1] neg_hi:[0,1]
	v_mov_b32_e32 v24, v23
	v_pk_add_f32 v[2:3], v[20:21], v[2:3]
	v_pk_add_f32 v[4:5], v[24:25], v[4:5]
	v_pk_add_f32 v[8:9], v[16:17], v[8:9]
	v_pk_mul_f32 v[10:11], v[4:5], s[74:75] op_sel_hi:[1,0]
	v_pk_mul_f32 v[4:5], v[2:3], s[74:75] op_sel_hi:[1,0]
	s_mov_b64 s[24:25], -1
	v_pk_mul_f32 v[8:9], v[8:9], s[74:75] op_sel_hi:[1,0]
	v_pk_mul_f32 v[6:7], v[6:7], s[74:75] op_sel_hi:[1,0]
	s_nop 0
	v_cvt_pk_bf16_f32 v2, v6, v7
	v_cvt_pk_bf16_f32 v3, v8, v9
	v_cvt_pk_bf16_f32 v4, v4, v5
	v_cvt_pk_bf16_f32 v5, v10, v11
	flat_store_dwordx4 v[26:27], v[2:5] offset:16
	s_cbranch_vccnz .LBB0_252
	s_nop 0
	v_lshl_add_u32 v2, s18, 8, v144
	v_ashrrev_i32_e32 v3, 31, v2
	v_lshlrev_b64 v[2:3], 8, v[2:3]
	v_lshl_add_u64 v[6:7], v[136:137], 0, v[2:3]
	global_load_dwordx4 v[2:5], v[6:7], off
	global_load_dwordx4 v[222:225], v[6:7], off offset:16
	global_load_dwordx4 v[226:229], v[6:7], off offset:32
	global_load_dwordx4 v[230:233], v[6:7], off offset:48
	global_load_dwordx4 v[234:237], v[6:7], off offset:64
	global_load_dwordx4 v[238:241], v[6:7], off offset:80
	global_load_dwordx4 v[242:245], v[6:7], off offset:96
	global_load_dwordx4 v[246:249], v[6:7], off offset:112
	s_and_b32 s17, s41, 1
	s_waitcnt vmcnt(0) lgkmcnt(0)
	v_add_f32_e32 v2, v2, v4
	v_add_f32_e32 v8, 0, v2
	v_add_f32_e32 v2, v3, v5
	v_add_f32_e32 v9, 0, v2
	v_add_f32_e32 v2, v222, v224
	v_add_f32_e32 v8, v8, v2
	v_add_f32_e32 v2, v223, v225
	v_add_f32_e32 v9, v9, v2
	v_add_f32_e32 v2, v226, v228
	v_add_f32_e32 v8, v8, v2
	v_add_f32_e32 v2, v227, v229
	v_add_f32_e32 v9, v9, v2
	v_add_f32_e32 v2, v230, v232
	v_add_f32_e32 v8, v8, v2
	v_add_f32_e32 v2, v231, v233
	v_add_f32_e32 v9, v9, v2
	v_add_f32_e32 v2, v234, v236
	v_add_f32_e32 v8, v8, v2
	v_add_f32_e32 v2, v235, v237
	v_add_f32_e32 v9, v9, v2
	v_add_f32_e32 v2, v238, v240
	v_add_f32_e32 v8, v8, v2
	v_add_f32_e32 v2, v239, v241
	v_add_f32_e32 v9, v9, v2
	v_add_f32_e32 v2, v242, v244
	v_add_f32_e32 v8, v8, v2
	v_add_f32_e32 v2, v243, v245
	v_add_f32_e32 v9, v9, v2
	v_add_f32_e32 v2, v246, v248
	v_add_f32_e32 v3, v247, v249
	v_add_f32_e32 v2, v8, v2
	v_add_f32_e32 v3, v9, v3
	ds_bpermute_b32 v4, v145, v2
	ds_bpermute_b32 v5, v145, v3
	s_and_saveexec_b64 s[24:25], s[0:1]
	s_cbranch_execz .LBB0_267
	s_waitcnt lgkmcnt(1)
	v_add_f32_e32 v2, v2, v4
	v_mul_f32_e32 v2, 0x3a000000, v2
	s_waitcnt lgkmcnt(0)
	v_add_f32_e32 v3, v3, v5
	v_mul_f32_e32 v4, v2, v2
	v_fma_f32 v3, v3, s61, -v4
	v_add_f32_e32 v3, 0x3727c5ac, v3
	v_rsq_f32_e32 v3, v3
	v_lshl_add_u32 v4, s17, 11, v151
	ds_write_b64 v4, v[2:3]

; #define LAS __attribute__((address_space(3)))
; __device__ __forceinline__ float shflx(float v, int k, int lane) { return __int_as_float(__builtin_amdgcn_ds_bpermute((lane ^ k) << 2, __float_as_int(v))); }
;     __device__ __forceinline__ void prepare(const pg8::Unit& u, LAS unsigned char* lds, int par, int tid) const { F.prepare(u, lds, par, tid); }
;     __device__ __forceinline__ void prepare(const pg8::Unit& u, LAS unsigned char* lds, int par, int tid) const { F.prepare(u, lds, par, tid); }
;     __device__ __forceinline__ void prepare(const pg8::Unit& u, LAS unsigned char* lds, int par, int tid) const { F.prepare(u, lds, par, tid); }
;     __device__ __forceinline__ void prepare(const pg8::Unit& u, LAS unsigned char* lds, int par, int tid) const {
;         if (stats == nullptr) return;
;         const int h = tid >> 8, tt = tid & 255, rl = tt >> 1, part = tt & 1, lrow = (rl >> 6) * 128 + h * 64 + (rl & 63);
;         const float* sp = stats + ((size_t)(u.pm * 256 + lrow) * 32 + part * 16) * 2;
;         float s1 = 0.f, s2 = 0.f;
; #pragma unroll
;         for (int i = 0; i < 8; ++i) { const f32x4 v = *(const f32x4*)(sp + 4 * i); s1 += v[0] + v[2]; s2 += v[1] + v[3]; }
;         s1 += shflx(s1, 1, tid & 63); s2 += shflx(s2, 1, tid & 63);
;         const float mu = s1 * (1.f / D), var = s2 * (1.f / D) - mu * mu, rstd = __builtin_amdgcn_rsqf(var + LN_EPS);
;         if (part == 0) { LAS float* rs = (LAS float*)(lds + RS_OFF) + (par * 256 + lrow) * 2; rs[0] = mu; rs[1] = rstd; }
.LBB0_297:
	s_load_dwordx2 s[12:13], s[0:1], 0x0
	s_load_dwordx4 s[4:7], s[0:1], 0xa8
	v_readlane_b32 s0, v251, 55
	s_add_i32 s0, s0, 9
	s_cmp_gt_u32 s0, 18
	s_cselect_b64 s[14:15], -1, 0
	s_cmp_lt_u32 s0, 19
	s_cbranch_scc1 .LBB0_301
	s_waitcnt vmcnt(0)
	v_ashrrev_i32_e32 v3, 2, v210
	v_and_b32_e32 v2, 0x80, v210
	v_and_b32_e32 v3, 0xffffffc0, v3
	v_lshrrev_b32_e32 v0, 1, v210
	v_add_u32_e32 v2, v3, v2
	v_and_or_b32 v2, v0, 63, v2
	v_lshl_add_u32 v4, s38, 8, v2
	v_ashrrev_i32_e32 v5, 31, v4
	v_readlane_b32 s0, v251, 35
	v_and_b32_e32 v10, 1, v210
	v_lshlrev_b64 v[4:5], 8, v[4:5]
	v_readlane_b32 s1, v251, 36
	v_lshlrev_b32_e32 v0, 7, v10
	v_cmp_eq_u32_e32 vcc, 0, v10
	v_lshl_add_u64 v[4:5], s[0:1], 0, v[4:5]
	v_lshl_add_u64 v[8:9], v[4:5], 0, v[0:1]
	global_load_dwordx4 v[4:7], v[8:9], off
	global_load_dwordx4 v[222:225], v[8:9], off offset:16
	global_load_dwordx4 v[226:229], v[8:9], off offset:32
	global_load_dwordx4 v[230:233], v[8:9], off offset:48
	global_load_dwordx4 v[234:237], v[8:9], off offset:64
	global_load_dwordx4 v[238:241], v[8:9], off offset:80
	global_load_dwordx4 v[242:245], v[8:9], off offset:96
	global_load_dwordx4 v[246:249], v[8:9], off offset:112
	s_waitcnt vmcnt(0) lgkmcnt(0)
	v_add_f32_e32 v0, v4, v6
	v_add_f32_e32 v3, v5, v7
	v_add_f32_e32 v0, 0, v0
	v_add_f32_e32 v3, 0, v3
	v_add_f32_e32 v4, v222, v224
	v_add_f32_e32 v0, v0, v4
	v_add_f32_e32 v4, v223, v225
	v_add_f32_e32 v3, v3, v4
	v_add_f32_e32 v4, v226, v228
	v_add_f32_e32 v0, v0, v4
	v_add_f32_e32 v4, v227, v229
	v_add_f32_e32 v3, v3, v4
	v_add_f32_e32 v4, v230, v232
	v_add_f32_e32 v0, v0, v4
	v_add_f32_e32 v4, v231, v233
	v_add_f32_e32 v3, v3, v4
	v_add_f32_e32 v4, v234, v236
	v_add_f32_e32 v0, v0, v4
	v_add_f32_e32 v4, v235, v237
	v_add_f32_e32 v3, v3, v4
	v_add_f32_e32 v4, v238, v240
	v_add_f32_e32 v0, v0, v4
	v_add_f32_e32 v4, v239, v241
	v_add_f32_e32 v3, v3, v4
	v_add_f32_e32 v4, v242, v244
	v_add_f32_e32 v0, v0, v4
	v_add_f32_e32 v4, v243, v245
	v_add_f32_e32 v3, v3, v4
	v_add_f32_e32 v4, v246, v248
	v_add_f32_e32 v0, v0, v4
	v_add_f32_e32 v4, v247, v249
	v_add_f32_e32 v3, v3, v4
	v_lshlrev_b32_e32 v4, 2, v210
	v_bitop3_b32 v5, v4, 4, v205 bitop3:0x6c
	ds_bpermute_b32 v4, v5, v0
	ds_bpermute_b32 v5, v5, v3
	s_and_saveexec_b64 s[0:1], vcc
	s_cbranch_execz .LBB0_300
	s_waitcnt lgkmcnt(1)
	v_add_f32_e32 v0, v0, v4
	v_mul_f32_e32 v4, 0x3a000000, v0
	s_waitcnt lgkmcnt(0)
	v_add_f32_e32 v3, v3, v5
	v_mul_f32_e32 v0, v4, v4
	v_fma_f32 v0, v3, s61, -v0
	v_add_f32_e32 v0, 0x3727c5ac, v0
	v_rsq_f32_e32 v5, v0
	v_lshl_add_u32 v0, v2, 3, 0
	v_add_u32_e32 v0, 0x20000, v0
	ds_write_b64 v0, v[4:5]

; #define LAS __attribute__((address_space(3)))
; __device__ __forceinline__ float shflx(float v, int k, int lane) { return __int_as_float(__builtin_amdgcn_ds_bpermute((lane ^ k) << 2, __float_as_int(v))); }
;     __device__ __forceinline__ void prepare(const pg8::Unit& u, LAS unsigned char* lds, int par, int tid) const { F.prepare(u, lds, par, tid); }
;     __device__ __forceinline__ void prepare(const pg8::Unit& u, LAS unsigned char* lds, int par, int tid) const { F.prepare(u, lds, par, tid); }
;     __device__ __forceinline__ void prepare(const pg8::Unit& u, LAS unsigned char* lds, int par, int tid) const { F.prepare(u, lds, par, tid); }
;     __device__ __forceinline__ void prepare(const pg8::Unit& u, LAS unsigned char* lds, int par, int tid) const {
;         if (stats == nullptr) return;
;         const int h = tid >> 8, tt = tid & 255, rl = tt >> 1, part = tt & 1, lrow = (rl >> 6) * 128 + h * 64 + (rl & 63);
;         const float* sp = stats + ((size_t)(u.pm * 256 + lrow) * 32 + part * 16) * 2;
;         float s1 = 0.f, s2 = 0.f;
; #pragma unroll
;         for (int i = 0; i < 8; ++i) { const f32x4 v = *(const f32x4*)(sp + 4 * i); s1 += v[0] + v[2]; s2 += v[1] + v[3]; }
;         s1 += shflx(s1, 1, tid & 63); s2 += shflx(s2, 1, tid & 63);
;         const float mu = s1 * (1.f / D), var = s2 * (1.f / D) - mu * mu, rstd = __builtin_amdgcn_rsqf(var + LN_EPS);
;         if (part == 0) { LAS float* rs = (LAS float*)(lds + RS_OFF) + (par * 256 + lrow) * 2; rs[0] = mu; rs[1] = rstd; }
.LBB0_422:
	s_or_b64 exec, exec, s[38:39]
	s_andn2_b64 vcc, exec, s[34:35]
	s_mov_b64 s[34:35], -1
	s_cbranch_vccnz .LBB0_305
	s_and_b64 vcc, exec, s[6:7]
	s_cbranch_vccnz .LBB0_427
	v_lshl_add_u32 v2, s26, 8, v216
	v_ashrrev_i32_e32 v3, 31, v2
	v_lshlrev_b64 v[2:3], 8, v[2:3]
	v_lshl_add_u64 v[6:7], v[184:185], 0, v[2:3]
	s_waitcnt lgkmcnt(0)
	global_load_dwordx4 v[2:5], v[6:7], off
	global_load_dwordx4 v[222:225], v[6:7], off offset:16
	global_load_dwordx4 v[226:229], v[6:7], off offset:32
	global_load_dwordx4 v[230:233], v[6:7], off offset:48
	global_load_dwordx4 v[234:237], v[6:7], off offset:64
	global_load_dwordx4 v[238:241], v[6:7], off offset:80
	global_load_dwordx4 v[242:245], v[6:7], off offset:96
	global_load_dwordx4 v[246:249], v[6:7], off offset:112
	s_waitcnt vmcnt(0) lgkmcnt(0)
	v_add_f32_e32 v2, v2, v4
	v_add_f32_e32 v8, 0, v2
	v_add_f32_e32 v2, v3, v5
	v_add_f32_e32 v9, 0, v2
	v_add_f32_e32 v2, v222, v224
	v_add_f32_e32 v8, v8, v2
	v_add_f32_e32 v2, v223, v225
	v_add_f32_e32 v9, v9, v2
	v_add_f32_e32 v2, v226, v228
	v_add_f32_e32 v8, v8, v2
	v_add_f32_e32 v2, v227, v229
	v_add_f32_e32 v9, v9, v2
	v_add_f32_e32 v2, v230, v232
	v_add_f32_e32 v8, v8, v2
	v_add_f32_e32 v2, v231, v233
	v_add_f32_e32 v9, v9, v2
	v_add_f32_e32 v2, v234, v236
	v_add_f32_e32 v8, v8, v2
	v_add_f32_e32 v2, v235, v237
	v_add_f32_e32 v9, v9, v2
	v_add_f32_e32 v2, v238, v240
	v_add_f32_e32 v8, v8, v2
	v_add_f32_e32 v2, v239, v241
	v_add_f32_e32 v9, v9, v2
	v_add_f32_e32 v2, v242, v244
	v_add_f32_e32 v8, v8, v2
	v_add_f32_e32 v2, v243, v245
	v_add_f32_e32 v9, v9, v2
	v_add_f32_e32 v2, v246, v248
	v_add_f32_e32 v3, v247, v249
	v_add_f32_e32 v2, v8, v2
	v_add_f32_e32 v3, v9, v3
	ds_bpermute_b32 v4, v217, v2
	ds_bpermute_b32 v5, v217, v3
	s_and_saveexec_b64 s[6:7], s[4:5]
	s_cbranch_execz .LBB0_426
	s_waitcnt lgkmcnt(1)
	v_add_f32_e32 v2, v2, v4
	v_mul_f32_e32 v2, 0x3a000000, v2
	s_waitcnt lgkmcnt(0)
	v_add_f32_e32 v3, v3, v5
	v_mul_f32_e32 v4, v2, v2
	v_fma_f32 v3, v3, s61, -v4
	v_add_f32_e32 v3, 0x3727c5ac, v3
	v_rsq_f32_e32 v3, v3
	s_lshl_b32 s25, s51, 11
	s_and_b32 s25, s25, 0x800
	v_add_u32_e32 v4, s25, v218
	ds_write_b64 v4, v[2:3]

; #define LAS __attribute__((address_space(3)))
; __device__ __forceinline__ float shflx(float v, int k, int lane) { return __int_as_float(__builtin_amdgcn_ds_bpermute((lane ^ k) << 2, __float_as_int(v))); }
;     __device__ __forceinline__ void prepare(const pg8::Unit& u, LAS unsigned char* lds, int par, int tid) const { F.prepare(u, lds, par, tid); }
;     __device__ __forceinline__ void prepare(const pg8::Unit& u, LAS unsigned char* lds, int par, int tid) const { F.prepare(u, lds, par, tid); }
;     __device__ __forceinline__ void prepare(const pg8::Unit& u, LAS unsigned char* lds, int par, int tid) const { F.prepare(u, lds, par, tid); }
;     __device__ __forceinline__ void prepare(const pg8::Unit& u, LAS unsigned char* lds, int par, int tid) const {
;         if (stats == nullptr) return;
;         const int h = tid >> 8, tt = tid & 255, rl = tt >> 1, part = tt & 1, lrow = (rl >> 6) * 128 + h * 64 + (rl & 63);
;         const float* sp = stats + ((size_t)(u.pm * 256 + lrow) * 32 + part * 16) * 2;
;         float s1 = 0.f, s2 = 0.f;
; #pragma unroll
;         for (int i = 0; i < 8; ++i) { const f32x4 v = *(const f32x4*)(sp + 4 * i); s1 += v[0] + v[2]; s2 += v[1] + v[3]; }
;         s1 += shflx(s1, 1, tid & 63); s2 += shflx(s2, 1, tid & 63);
;         const float mu = s1 * (1.f / D), var = s2 * (1.f / D) - mu * mu, rstd = __builtin_amdgcn_rsqf(var + LN_EPS);
;         if (part == 0) { LAS float* rs = (LAS float*)(lds + RS_OFF) + (par * 256 + lrow) * 2; rs[0] = mu; rs[1] = rstd; }
.LBB0_532:
	s_and_b64 vcc, exec, s[0:1]
	v_readlane_b32 s0, v251, 33
	v_readlane_b32 s1, v251, 34
	s_ashr_i32 s1, s0, 31
	v_writelane_b32 v251, s0, 33
	s_nop 1
	v_writelane_b32 v251, s1, 34
	s_cbranch_vccnz .LBB0_834
	s_load_dwordx2 s[12:13], s[6:7], 0x18
	v_readlane_b32 s0, v251, 55
	s_add_i32 s10, s0, 9
	s_cmp_gt_u32 s10, 18
	v_ashrrev_i32_e32 v0, 2, v210
	s_cselect_b64 s[0:1], -1, 0
	s_cmp_lt_u32 s10, 19
	s_waitcnt vmcnt(0)
	v_lshrrev_b32_e32 v10, 1, v210
	v_and_b32_e32 v11, 0x80, v210
	v_and_b32_e32 v12, 0xffffffc0, v0
	s_cbranch_scc1 .LBB0_537
	v_add_u32_e32 v0, v12, v11
	v_and_or_b32 v2, v10, 63, v0
	s_waitcnt lgkmcnt(0)
	v_lshl_add_u32 v4, s30, 8, v2
	v_ashrrev_i32_e32 v5, 31, v4
	v_readlane_b32 s10, v251, 35
	v_and_b32_e32 v13, 1, v210
	v_lshlrev_b64 v[4:5], 8, v[4:5]
	v_readlane_b32 s11, v251, 36
	v_lshlrev_b32_e32 v0, 7, v13
	v_cmp_eq_u32_e32 vcc, 0, v13
	v_lshl_add_u64 v[4:5], s[10:11], 0, v[4:5]
	v_lshl_add_u64 v[8:9], v[4:5], 0, v[0:1]
	global_load_dwordx4 v[4:7], v[8:9], off
	global_load_dwordx4 v[222:225], v[8:9], off offset:16
	global_load_dwordx4 v[226:229], v[8:9], off offset:32
	global_load_dwordx4 v[230:233], v[8:9], off offset:48
	global_load_dwordx4 v[234:237], v[8:9], off offset:64
	global_load_dwordx4 v[238:241], v[8:9], off offset:80
	global_load_dwordx4 v[242:245], v[8:9], off offset:96
	global_load_dwordx4 v[246:249], v[8:9], off offset:112
	s_waitcnt vmcnt(0) lgkmcnt(0)
	v_add_f32_e32 v0, v4, v6
	v_add_f32_e32 v3, v5, v7
	v_add_f32_e32 v0, 0, v0
	v_add_f32_e32 v3, 0, v3
	v_add_f32_e32 v4, v222, v224
	v_add_f32_e32 v0, v0, v4
	v_add_f32_e32 v4, v223, v225
	v_add_f32_e32 v3, v3, v4
	v_add_f32_e32 v4, v226, v228
	v_add_f32_e32 v0, v0, v4
	v_add_f32_e32 v4, v227, v229
	v_add_f32_e32 v3, v3, v4
	v_add_f32_e32 v4, v230, v232
	v_add_f32_e32 v0, v0, v4
	v_add_f32_e32 v4, v231, v233
	v_add_f32_e32 v3, v3, v4
	v_add_f32_e32 v4, v234, v236
	v_add_f32_e32 v0, v0, v4
	v_add_f32_e32 v4, v235, v237
	v_add_f32_e32 v3, v3, v4
	v_add_f32_e32 v4, v238, v240
	v_add_f32_e32 v0, v0, v4
	v_add_f32_e32 v4, v239, v241
	v_add_f32_e32 v3, v3, v4
	v_add_f32_e32 v4, v242, v244
	v_add_f32_e32 v0, v0, v4
	v_add_f32_e32 v4, v243, v245
	v_add_f32_e32 v3, v3, v4
	v_add_f32_e32 v4, v246, v248
	v_add_f32_e32 v0, v0, v4
	v_add_f32_e32 v4, v247, v249
	v_add_f32_e32 v3, v3, v4
	v_lshlrev_b32_e32 v4, 2, v210
	v_bitop3_b32 v5, v4, 4, v205 bitop3:0x6c
	ds_bpermute_b32 v4, v5, v0
	ds_bpermute_b32 v5, v5, v3
	s_and_saveexec_b64 s[10:11], vcc
	s_cbranch_execz .LBB0_536
	s_waitcnt lgkmcnt(1)
	v_add_f32_e32 v0, v0, v4
	v_mul_f32_e32 v4, 0x3a000000, v0
	s_waitcnt lgkmcnt(0)
	v_add_f32_e32 v3, v3, v5
	v_mul_f32_e32 v0, v4, v4
	v_fma_f32 v0, v3, s61, -v0
	v_add_f32_e32 v0, 0x3727c5ac, v0
	v_rsq_f32_e32 v5, v0
	v_lshl_add_u32 v0, v2, 3, 0
	v_add_u32_e32 v0, 0x20000, v0
	ds_write_b64 v0, v[4:5]

; #define LAS __attribute__((address_space(3)))
; __device__ __forceinline__ float shflx(float v, int k, int lane) { return __int_as_float(__builtin_amdgcn_ds_bpermute((lane ^ k) << 2, __float_as_int(v))); }
;     __device__ __forceinline__ void prepare(const pg8::Unit& u, LAS unsigned char* lds, int par, int tid) const { F.prepare(u, lds, par, tid); }
;     __device__ __forceinline__ void prepare(const pg8::Unit& u, LAS unsigned char* lds, int par, int tid) const { F.prepare(u, lds, par, tid); }
;     __device__ __forceinline__ void prepare(const pg8::Unit& u, LAS unsigned char* lds, int par, int tid) const { F.prepare(u, lds, par, tid); }
;     __device__ __forceinline__ void prepare(const pg8::Unit& u, LAS unsigned char* lds, int par, int tid) const {
;         if (stats == nullptr) return;
;         const int h = tid >> 8, tt = tid & 255, rl = tt >> 1, part = tt & 1, lrow = (rl >> 6) * 128 + h * 64 + (rl & 63);
;         const float* sp = stats + ((size_t)(u.pm * 256 + lrow) * 32 + part * 16) * 2;
;         float s1 = 0.f, s2 = 0.f;
; #pragma unroll
;         for (int i = 0; i < 8; ++i) { const f32x4 v = *(const f32x4*)(sp + 4 * i); s1 += v[0] + v[2]; s2 += v[1] + v[3]; }
;         s1 += shflx(s1, 1, tid & 63); s2 += shflx(s2, 1, tid & 63);
;         const float mu = s1 * (1.f / D), var = s2 * (1.f / D) - mu * mu, rstd = __builtin_amdgcn_rsqf(var + LN_EPS);
;         if (part == 0) { LAS float* rs = (LAS float*)(lds + RS_OFF) + (par * 256 + lrow) * 2; rs[0] = mu; rs[1] = rstd; }
.LBB0_825:
	s_andn2_b64 vcc, exec, s[24:25]
	s_mov_b64 s[24:25], -1
	s_cbranch_vccnz .LBB0_541
	s_and_b64 vcc, exec, s[44:45]
	s_cbranch_vccnz .LBB0_830
	v_lshl_add_u32 v2, s18, 8, v179
	v_ashrrev_i32_e32 v3, 31, v2
	v_lshlrev_b64 v[2:3], 8, v[2:3]
	v_lshl_add_u64 v[6:7], v[142:143], 0, v[2:3]
	s_waitcnt lgkmcnt(0)
	global_load_dwordx4 v[2:5], v[6:7], off
	global_load_dwordx4 v[222:225], v[6:7], off offset:16
	global_load_dwordx4 v[226:229], v[6:7], off offset:32
	global_load_dwordx4 v[230:233], v[6:7], off offset:48
	global_load_dwordx4 v[234:237], v[6:7], off offset:64
	global_load_dwordx4 v[238:241], v[6:7], off offset:80
	global_load_dwordx4 v[242:245], v[6:7], off offset:96
	global_load_dwordx4 v[246:249], v[6:7], off offset:112
	s_and_b32 s2, s66, 1
	s_waitcnt vmcnt(0) lgkmcnt(0)
	v_add_f32_e32 v0, v2, v4
	v_add_f32_e32 v2, v3, v5
	v_add_f32_e32 v8, 0, v2
	v_add_f32_e32 v0, 0, v0
	v_add_f32_e32 v2, v222, v224
	v_add_f32_e32 v0, v0, v2
	v_add_f32_e32 v2, v223, v225
	v_add_f32_e32 v8, v8, v2
	v_add_f32_e32 v2, v226, v228
	v_add_f32_e32 v0, v0, v2
	v_add_f32_e32 v2, v227, v229
	v_add_f32_e32 v8, v8, v2
	v_add_f32_e32 v2, v230, v232
	v_add_f32_e32 v0, v0, v2
	v_add_f32_e32 v2, v231, v233
	v_add_f32_e32 v8, v8, v2
	v_add_f32_e32 v2, v234, v236
	v_add_f32_e32 v0, v0, v2
	v_add_f32_e32 v2, v235, v237
	v_add_f32_e32 v8, v8, v2
	v_add_f32_e32 v2, v238, v240
	v_add_f32_e32 v0, v0, v2
	v_add_f32_e32 v2, v239, v241
	v_add_f32_e32 v8, v8, v2
	v_add_f32_e32 v2, v242, v244
	v_add_f32_e32 v0, v0, v2
	v_add_f32_e32 v2, v243, v245
	v_add_f32_e32 v8, v8, v2
	v_add_f32_e32 v2, v246, v248
	v_add_f32_e32 v0, v0, v2
	v_add_f32_e32 v2, v247, v249
	v_add_f32_e32 v2, v8, v2
	ds_bpermute_b32 v3, v181, v0
	ds_bpermute_b32 v4, v181, v2
	s_and_saveexec_b64 s[24:25], s[42:43]
	s_cbranch_execz .LBB0_829
	s_waitcnt lgkmcnt(1)
	v_add_f32_e32 v0, v0, v3
	s_waitcnt lgkmcnt(0)
	v_add_f32_e32 v4, v2, v4
	v_mul_f32_e32 v2, 0x3a000000, v0
	v_mul_f32_e32 v0, v2, v2
	s_mov_b32 s17, 0x3a000000
	v_fma_f32 v0, v4, s17, -v0
	v_add_f32_e32 v0, 0x3727c5ac, v0
	v_rsq_f32_e32 v3, v0
	v_lshl_add_u32 v0, s2, 11, v182
	ds_write_b64 v0, v[2:3]
